# all per-segment s_setprio toggles removed from the GEMM K loops (both waves of a SIMD stay at priority 0)
# speedup vs baseline: 1.0126x; 1.0126x over previous
.LBB0_125:
	s_ashr_i32 s9, s8, 31
	s_lshl_b64 s[22:23], s[8:9], 19
	s_add_u32 s40, s42, s22
	s_addc_u32 s41, s43, s23
	s_and_b64 s[22:23], s[38:39], exec
	s_cselect_b32 s9, s41, s11
	s_cselect_b32 s22, s40, s10
	s_ashr_i32 s7, s6, 31
	s_lshl_b64 s[24:25], s[6:7], 19
	s_add_u32 s82, s19, s24
	s_addc_u32 s83, s50, s25
	s_and_b64 s[24:25], s[38:39], exec
	s_cselect_b32 s7, s83, s37
	s_cselect_b32 s23, s82, s36
	s_add_u32 s10, s10, 0x40080
	s_addc_u32 s11, s11, 0
	s_add_u32 s24, s36, 0x100
	s_addc_u32 s25, s37, 0
	s_mov_b32 s26, -2
	s_add_u32 s13, s10, 0xfffc0080
	s_addc_u32 s27, s11, -1
	s_add_i32 s28, 0, 0x10000
	s_cmp_eq_u32 s26, 12
	s_cselect_b32 s49, s9, s27
	s_cselect_b32 s48, s22, s13
	v_add_u32_e32 v0, s28, v150
	s_cselect_b32 s37, s7, s25
	s_cselect_b32 s36, s23, s24
	s_add_i32 s13, 0, 0x14000
	ds_read_b128 v[166:169], v0
	ds_read_b128 v[170:173], v0 offset:1024
	ds_read_b128 v[174:177], v0 offset:2048
	ds_read_b128 v[178:181], v0 offset:3072
	v_add_u32_e32 v0, s13, v150
	ds_read_b128 v[182:185], v0
	ds_read_b128 v[186:189], v0 offset:1024
	ds_read_b128 v[190:193], v0 offset:2048
	ds_read_b128 v[194:197], v0 offset:3072
	v_lshl_add_u64 v[130:131], s[10:11], 0, v[146:147]
	s_add_i32 m0, s52, 0xc000
	ds_read_b128 v[198:201], v152
	ds_read_b128 v[202:205], v152 offset:1024
	ds_read_b128 v[206:209], v152 offset:2048
	ds_read_b128 v[210:213], v152 offset:3072
	ds_read_b128 v[214:217], v152 offset:4096
	ds_read_b128 v[218:221], v152 offset:5120
	ds_read_b128 v[222:225], v152 offset:6144
	ds_read_b128 v[226:229], v152 offset:7168
	global_load_lds_dwordx4 v[130:131], off
	v_lshl_add_u64 v[130:131], s[10:11], 0, v[148:149]
	s_add_i32 m0, s52, 0xe000
	s_nop 0
	global_load_lds_dwordx4 v[130:131], off
	s_waitcnt vmcnt(8)
	s_waitcnt lgkmcnt(0)
	s_barrier
	s_waitcnt lgkmcnt(0)
	v_mfma_f32_16x16x32_bf16 v[126:129], v[166:169], v[198:201], 0
	v_mfma_f32_16x16x32_bf16 v[114:117], v[174:177], v[198:201], 0
	v_mfma_f32_16x16x32_bf16 v[110:113], v[166:169], v[206:209], 0
	v_mfma_f32_16x16x32_bf16 v[98:101], v[174:177], v[206:209], 0
	v_mfma_f32_16x16x32_bf16 v[94:97], v[166:169], v[214:217], 0
	v_mfma_f32_16x16x32_bf16 v[82:85], v[174:177], v[214:217], 0
	v_mfma_f32_16x16x32_bf16 v[78:81], v[166:169], v[222:225], 0
	v_mfma_f32_16x16x32_bf16 v[66:69], v[174:177], v[222:225], 0
	v_mfma_f32_16x16x32_bf16 v[126:129], v[170:173], v[202:205], v[126:129]
	v_mfma_f32_16x16x32_bf16 v[114:117], v[178:181], v[202:205], v[114:117]
	v_mfma_f32_16x16x32_bf16 v[110:113], v[170:173], v[210:213], v[110:113]
	v_mfma_f32_16x16x32_bf16 v[98:101], v[178:181], v[210:213], v[98:101]
	v_mfma_f32_16x16x32_bf16 v[94:97], v[170:173], v[218:221], v[94:97]
	v_mfma_f32_16x16x32_bf16 v[82:85], v[178:181], v[218:221], v[82:85]
	v_mfma_f32_16x16x32_bf16 v[78:81], v[170:173], v[226:229], v[78:81]
	v_mfma_f32_16x16x32_bf16 v[66:69], v[178:181], v[226:229], v[66:69]
	v_mfma_f32_16x16x32_bf16 v[122:125], v[182:185], v[198:201], 0
	v_mfma_f32_16x16x32_bf16 v[118:121], v[190:193], v[198:201], 0
	v_mfma_f32_16x16x32_bf16 v[106:109], v[182:185], v[206:209], 0
	v_mfma_f32_16x16x32_bf16 v[102:105], v[190:193], v[206:209], 0
	v_mfma_f32_16x16x32_bf16 v[90:93], v[182:185], v[214:217], 0
	v_mfma_f32_16x16x32_bf16 v[86:89], v[190:193], v[214:217], 0
	v_mfma_f32_16x16x32_bf16 v[74:77], v[182:185], v[222:225], 0
	v_mfma_f32_16x16x32_bf16 v[70:73], v[190:193], v[222:225], 0
	v_mfma_f32_16x16x32_bf16 v[122:125], v[186:189], v[202:205], v[122:125]
	v_mfma_f32_16x16x32_bf16 v[118:121], v[194:197], v[202:205], v[118:121]
	v_mfma_f32_16x16x32_bf16 v[106:109], v[186:189], v[210:213], v[106:109]
	v_mfma_f32_16x16x32_bf16 v[102:105], v[194:197], v[210:213], v[102:105]
	v_mfma_f32_16x16x32_bf16 v[90:93], v[186:189], v[218:221], v[90:93]
	v_mfma_f32_16x16x32_bf16 v[86:89], v[194:197], v[218:221], v[86:89]
	v_mfma_f32_16x16x32_bf16 v[74:77], v[186:189], v[226:229], v[74:77]
	v_mfma_f32_16x16x32_bf16 v[70:73], v[194:197], v[226:229], v[70:73]
	s_barrier
	s_add_i32 s27, s28, s51
	v_lshl_add_u64 v[130:131], s[36:37], 0, v[142:143]
	s_mov_b32 m0, s27
	ds_read_b128 v[198:201], v152 offset:16384
	ds_read_b128 v[202:205], v152 offset:17408
	ds_read_b128 v[206:209], v152 offset:18432
	ds_read_b128 v[210:213], v152 offset:19456
	ds_read_b128 v[214:217], v152 offset:20480
	ds_read_b128 v[218:221], v152 offset:21504
	ds_read_b128 v[222:225], v152 offset:22528
	ds_read_b128 v[226:229], v152 offset:23552
	global_load_lds_dwordx4 v[130:131], off
	s_add_i32 m0, s27, 0x2000
	s_add_u32 s28, s36, 0x40000
	v_lshl_add_u64 v[136:137], s[36:37], 0, v[138:139]
	s_addc_u32 s29, s37, 0
	s_add_i32 s13, s13, s51
	global_load_lds_dwordx4 v[136:137], off
	v_lshl_add_u64 v[230:231], s[28:29], 0, v[142:143]
	s_mov_b32 m0, s13
	v_lshl_add_u64 v[232:233], s[48:49], 0, v[140:141]
	global_load_lds_dwordx4 v[230:231], off
	v_lshl_add_u64 v[230:231], s[28:29], 0, v[138:139]
	s_add_i32 m0, s13, 0x2000
	s_nop 0
	global_load_lds_dwordx4 v[230:231], off
	v_lshl_add_u64 v[230:231], s[48:49], 0, v[144:145]
	s_mov_b32 m0, s52
	s_nop 0
	global_load_lds_dwordx4 v[230:231], off
	s_mov_b32 m0, s53
	s_nop 0
	global_load_lds_dwordx4 v[232:233], off
	s_waitcnt vmcnt(8)
	s_waitcnt lgkmcnt(0)
	s_barrier
	s_waitcnt lgkmcnt(0)
	v_mfma_f32_16x16x32_bf16 v[62:65], v[166:169], v[198:201], 0
	v_mfma_f32_16x16x32_bf16 v[50:53], v[174:177], v[198:201], 0
	v_mfma_f32_16x16x32_bf16 v[46:49], v[166:169], v[206:209], 0
	v_mfma_f32_16x16x32_bf16 v[34:37], v[174:177], v[206:209], 0
	v_mfma_f32_16x16x32_bf16 v[30:33], v[166:169], v[214:217], 0
	v_mfma_f32_16x16x32_bf16 v[18:21], v[174:177], v[214:217], 0
	v_mfma_f32_16x16x32_bf16 v[14:17], v[166:169], v[222:225], 0
	v_mfma_f32_16x16x32_bf16 v[6:9], v[174:177], v[222:225], 0
	v_mfma_f32_16x16x32_bf16 v[62:65], v[170:173], v[202:205], v[62:65]
	v_mfma_f32_16x16x32_bf16 v[50:53], v[178:181], v[202:205], v[50:53]
	v_mfma_f32_16x16x32_bf16 v[46:49], v[170:173], v[210:213], v[46:49]
	v_mfma_f32_16x16x32_bf16 v[34:37], v[178:181], v[210:213], v[34:37]
	v_mfma_f32_16x16x32_bf16 v[30:33], v[170:173], v[218:221], v[30:33]
	v_mfma_f32_16x16x32_bf16 v[18:21], v[178:181], v[218:221], v[18:21]
	v_mfma_f32_16x16x32_bf16 v[14:17], v[170:173], v[226:229], v[14:17]
	v_mfma_f32_16x16x32_bf16 v[6:9], v[178:181], v[226:229], v[6:9]
	v_mfma_f32_16x16x32_bf16 v[58:61], v[182:185], v[198:201], 0
	v_mfma_f32_16x16x32_bf16 v[54:57], v[190:193], v[198:201], 0
	v_mfma_f32_16x16x32_bf16 v[42:45], v[182:185], v[206:209], 0
	v_mfma_f32_16x16x32_bf16 v[38:41], v[190:193], v[206:209], 0
	v_mfma_f32_16x16x32_bf16 v[26:29], v[182:185], v[214:217], 0
	v_mfma_f32_16x16x32_bf16 v[22:25], v[190:193], v[214:217], 0
	v_mfma_f32_16x16x32_bf16 v[10:13], v[182:185], v[222:225], 0
	v_mfma_f32_16x16x32_bf16 v[2:5], v[190:193], v[222:225], 0
	v_mfma_f32_16x16x32_bf16 v[58:61], v[186:189], v[202:205], v[58:61]
	v_mfma_f32_16x16x32_bf16 v[54:57], v[194:197], v[202:205], v[54:57]
	v_mfma_f32_16x16x32_bf16 v[42:45], v[186:189], v[210:213], v[42:45]
	v_mfma_f32_16x16x32_bf16 v[38:41], v[194:197], v[210:213], v[38:41]
	v_mfma_f32_16x16x32_bf16 v[26:29], v[186:189], v[218:221], v[26:29]
	v_mfma_f32_16x16x32_bf16 v[22:25], v[194:197], v[218:221], v[22:25]
	v_mfma_f32_16x16x32_bf16 v[10:13], v[186:189], v[226:229], v[10:13]
	v_mfma_f32_16x16x32_bf16 v[2:5], v[194:197], v[226:229], v[2:5]
	s_barrier
	s_add_i32 s13, 0, 0x18000
	v_add_u32_e32 v0, s13, v150
	s_add_i32 s27, 0, 0x1c000
	ds_read_b128 v[166:169], v0
	ds_read_b128 v[170:173], v0 offset:1024
	ds_read_b128 v[174:177], v0 offset:2048
	ds_read_b128 v[178:181], v0 offset:3072
	v_add_u32_e32 v0, s27, v150
	ds_read_b128 v[182:185], v0
	ds_read_b128 v[186:189], v0 offset:1024
	ds_read_b128 v[190:193], v0 offset:2048
	ds_read_b128 v[194:197], v0 offset:3072
	s_add_u32 s28, s48, 0x40000
	s_addc_u32 s29, s49, 0
	s_mov_b32 m0, s54
	v_lshl_add_u64 v[234:235], s[28:29], 0, v[144:145]
	ds_read_b128 v[198:201], v152 offset:32768
	ds_read_b128 v[202:205], v152 offset:33792
	ds_read_b128 v[206:209], v152 offset:34816
	ds_read_b128 v[210:213], v152 offset:35840
	ds_read_b128 v[214:217], v152 offset:36864
	ds_read_b128 v[218:221], v152 offset:37888
	ds_read_b128 v[222:225], v152 offset:38912
	ds_read_b128 v[226:229], v152 offset:39936
	global_load_lds_dwordx4 v[234:235], off
	v_lshl_add_u64 v[234:235], s[28:29], 0, v[140:141]
	s_mov_b32 m0, s55
	s_nop 0
	global_load_lds_dwordx4 v[234:235], off
	s_waitcnt vmcnt(8)
	s_waitcnt lgkmcnt(0)
	s_barrier
	s_waitcnt lgkmcnt(0)
	v_mfma_f32_16x16x32_bf16 v[126:129], v[166:169], v[198:201], v[126:129]
	v_mfma_f32_16x16x32_bf16 v[114:117], v[174:177], v[198:201], v[114:117]
	v_mfma_f32_16x16x32_bf16 v[110:113], v[166:169], v[206:209], v[110:113]
	v_mfma_f32_16x16x32_bf16 v[98:101], v[174:177], v[206:209], v[98:101]
	v_mfma_f32_16x16x32_bf16 v[94:97], v[166:169], v[214:217], v[94:97]
	v_mfma_f32_16x16x32_bf16 v[82:85], v[174:177], v[214:217], v[82:85]
	v_mfma_f32_16x16x32_bf16 v[78:81], v[166:169], v[222:225], v[78:81]
	v_mfma_f32_16x16x32_bf16 v[66:69], v[174:177], v[222:225], v[66:69]
	v_mfma_f32_16x16x32_bf16 v[126:129], v[170:173], v[202:205], v[126:129]
	v_mfma_f32_16x16x32_bf16 v[114:117], v[178:181], v[202:205], v[114:117]
	v_mfma_f32_16x16x32_bf16 v[110:113], v[170:173], v[210:213], v[110:113]
	v_mfma_f32_16x16x32_bf16 v[98:101], v[178:181], v[210:213], v[98:101]
	v_mfma_f32_16x16x32_bf16 v[94:97], v[170:173], v[218:221], v[94:97]
	v_mfma_f32_16x16x32_bf16 v[82:85], v[178:181], v[218:221], v[82:85]
	v_mfma_f32_16x16x32_bf16 v[78:81], v[170:173], v[226:229], v[78:81]
	v_mfma_f32_16x16x32_bf16 v[66:69], v[178:181], v[226:229], v[66:69]
	v_mfma_f32_16x16x32_bf16 v[122:125], v[182:185], v[198:201], v[122:125]
	v_mfma_f32_16x16x32_bf16 v[118:121], v[190:193], v[198:201], v[118:121]
	v_mfma_f32_16x16x32_bf16 v[106:109], v[182:185], v[206:209], v[106:109]
	v_mfma_f32_16x16x32_bf16 v[102:105], v[190:193], v[206:209], v[102:105]
	v_mfma_f32_16x16x32_bf16 v[90:93], v[182:185], v[214:217], v[90:93]
	v_mfma_f32_16x16x32_bf16 v[86:89], v[190:193], v[214:217], v[86:89]
	v_mfma_f32_16x16x32_bf16 v[74:77], v[182:185], v[222:225], v[74:77]
	v_mfma_f32_16x16x32_bf16 v[70:73], v[190:193], v[222:225], v[70:73]
	v_mfma_f32_16x16x32_bf16 v[122:125], v[186:189], v[202:205], v[122:125]
	v_mfma_f32_16x16x32_bf16 v[118:121], v[194:197], v[202:205], v[118:121]
	v_mfma_f32_16x16x32_bf16 v[106:109], v[186:189], v[210:213], v[106:109]
	v_mfma_f32_16x16x32_bf16 v[102:105], v[194:197], v[210:213], v[102:105]
	v_mfma_f32_16x16x32_bf16 v[90:93], v[186:189], v[218:221], v[90:93]
	v_mfma_f32_16x16x32_bf16 v[86:89], v[194:197], v[218:221], v[86:89]
	v_mfma_f32_16x16x32_bf16 v[74:77], v[186:189], v[226:229], v[74:77]
	v_mfma_f32_16x16x32_bf16 v[70:73], v[194:197], v[226:229], v[70:73]
	s_barrier
	s_add_i32 s13, s13, s51
	v_lshl_add_u64 v[130:131], v[130:131], 0, s[84:85]
	s_mov_b32 m0, s13
	ds_read_b128 v[198:201], v152 offset:49152
	ds_read_b128 v[202:205], v152 offset:50176
	ds_read_b128 v[206:209], v152 offset:51200
	ds_read_b128 v[210:213], v152 offset:52224
	ds_read_b128 v[214:217], v152 offset:53248
	ds_read_b128 v[218:221], v152 offset:54272
	ds_read_b128 v[222:225], v152 offset:55296
	ds_read_b128 v[226:229], v152 offset:56320
	global_load_lds_dwordx4 v[130:131], off
	s_add_i32 m0, s13, 0x2000
	s_add_u32 s28, s36, 0x40080
	v_lshl_add_u64 v[130:131], v[136:137], 0, s[84:85]
	s_addc_u32 s29, s37, 0
	s_add_i32 s13, s27, s51
	global_load_lds_dwordx4 v[130:131], off
	v_lshl_add_u64 v[130:131], s[28:29], 0, v[142:143]
	s_mov_b32 m0, s13
	s_nop 0
	global_load_lds_dwordx4 v[130:131], off
	v_lshl_add_u64 v[130:131], s[28:29], 0, v[138:139]
	s_add_i32 m0, s13, 0x2000
	s_nop 0
	global_load_lds_dwordx4 v[130:131], off
	v_lshl_add_u64 v[130:131], v[230:231], 0, s[84:85]
	s_mov_b32 m0, s60
	s_nop 0
	global_load_lds_dwordx4 v[130:131], off
	v_lshl_add_u64 v[130:131], v[232:233], 0, s[84:85]
	s_mov_b32 m0, s61
	s_nop 0
	global_load_lds_dwordx4 v[130:131], off
	s_waitcnt vmcnt(8)
	s_waitcnt lgkmcnt(0)
	s_barrier
	s_waitcnt lgkmcnt(0)
	v_mfma_f32_16x16x32_bf16 v[62:65], v[166:169], v[198:201], v[62:65]
	v_mfma_f32_16x16x32_bf16 v[50:53], v[174:177], v[198:201], v[50:53]
	v_mfma_f32_16x16x32_bf16 v[46:49], v[166:169], v[206:209], v[46:49]
	v_mfma_f32_16x16x32_bf16 v[34:37], v[174:177], v[206:209], v[34:37]
	v_mfma_f32_16x16x32_bf16 v[30:33], v[166:169], v[214:217], v[30:33]
	v_mfma_f32_16x16x32_bf16 v[18:21], v[174:177], v[214:217], v[18:21]
	v_mfma_f32_16x16x32_bf16 v[14:17], v[166:169], v[222:225], v[14:17]
	v_mfma_f32_16x16x32_bf16 v[6:9], v[174:177], v[222:225], v[6:9]
	v_mfma_f32_16x16x32_bf16 v[62:65], v[170:173], v[202:205], v[62:65]
	v_mfma_f32_16x16x32_bf16 v[50:53], v[178:181], v[202:205], v[50:53]
	v_mfma_f32_16x16x32_bf16 v[46:49], v[170:173], v[210:213], v[46:49]
	v_mfma_f32_16x16x32_bf16 v[34:37], v[178:181], v[210:213], v[34:37]
	v_mfma_f32_16x16x32_bf16 v[30:33], v[170:173], v[218:221], v[30:33]
	v_mfma_f32_16x16x32_bf16 v[18:21], v[178:181], v[218:221], v[18:21]
	v_mfma_f32_16x16x32_bf16 v[14:17], v[170:173], v[226:229], v[14:17]
	v_mfma_f32_16x16x32_bf16 v[6:9], v[178:181], v[226:229], v[6:9]
	v_mfma_f32_16x16x32_bf16 v[58:61], v[182:185], v[198:201], v[58:61]
	v_mfma_f32_16x16x32_bf16 v[54:57], v[190:193], v[198:201], v[54:57]
	v_mfma_f32_16x16x32_bf16 v[42:45], v[182:185], v[206:209], v[42:45]
	v_mfma_f32_16x16x32_bf16 v[38:41], v[190:193], v[206:209], v[38:41]
	v_mfma_f32_16x16x32_bf16 v[26:29], v[182:185], v[214:217], v[26:29]
	v_mfma_f32_16x16x32_bf16 v[22:25], v[190:193], v[214:217], v[22:25]
	v_mfma_f32_16x16x32_bf16 v[10:13], v[182:185], v[222:225], v[10:13]
	v_mfma_f32_16x16x32_bf16 v[2:5], v[190:193], v[222:225], v[2:5]
	v_mfma_f32_16x16x32_bf16 v[58:61], v[186:189], v[202:205], v[58:61]
	v_mfma_f32_16x16x32_bf16 v[54:57], v[194:197], v[202:205], v[54:57]
	v_mfma_f32_16x16x32_bf16 v[42:45], v[186:189], v[210:213], v[42:45]
	v_mfma_f32_16x16x32_bf16 v[38:41], v[194:197], v[210:213], v[38:41]
	v_mfma_f32_16x16x32_bf16 v[26:29], v[186:189], v[218:221], v[26:29]
	v_mfma_f32_16x16x32_bf16 v[22:25], v[194:197], v[218:221], v[22:25]
	v_mfma_f32_16x16x32_bf16 v[10:13], v[186:189], v[226:229], v[10:13]
	v_mfma_f32_16x16x32_bf16 v[2:5], v[194:197], v[226:229], v[2:5]
	s_barrier
	s_add_i32 s26, s26, 2
	s_add_u32 s10, s10, 0x100
	s_addc_u32 s11, s11, 0
	s_add_u32 s24, s24, 0x100
	s_addc_u32 s25, s25, 0
	s_cmp_gt_u32 s26, 13
	s_cbranch_scc1 .Lffnin_kdone
.LBB0_126:
	s_add_u32 s13, s10, 0xfffc0080
	s_addc_u32 s27, s11, -1
	s_add_i32 s28, 0, 0x10000
	s_cmp_eq_u32 s26, 12
	s_cselect_b32 s49, s9, s27
	s_cselect_b32 s48, s22, s13
	v_add_u32_e32 v0, s28, v150
	s_cselect_b32 s37, s7, s25
	s_cselect_b32 s36, s23, s24
	s_add_i32 s13, 0, 0x14000
	ds_read_b128 v[166:169], v0
	ds_read_b128 v[170:173], v0 offset:1024
	ds_read_b128 v[174:177], v0 offset:2048
	ds_read_b128 v[178:181], v0 offset:3072
	v_add_u32_e32 v0, s13, v150
	ds_read_b128 v[182:185], v0
	ds_read_b128 v[186:189], v0 offset:1024
	ds_read_b128 v[190:193], v0 offset:2048
	ds_read_b128 v[194:197], v0 offset:3072
	v_lshl_add_u64 v[130:131], s[10:11], 0, v[146:147]
	s_add_i32 m0, s52, 0xc000
	ds_read_b128 v[198:201], v152
	ds_read_b128 v[202:205], v152 offset:1024
	ds_read_b128 v[206:209], v152 offset:2048
	ds_read_b128 v[210:213], v152 offset:3072
	ds_read_b128 v[214:217], v152 offset:4096
	ds_read_b128 v[218:221], v152 offset:5120
	ds_read_b128 v[222:225], v152 offset:6144
	ds_read_b128 v[226:229], v152 offset:7168
	global_load_lds_dwordx4 v[130:131], off
	v_lshl_add_u64 v[130:131], s[10:11], 0, v[148:149]
	s_add_i32 m0, s52, 0xe000
	s_nop 0
	global_load_lds_dwordx4 v[130:131], off
	s_waitcnt vmcnt(8)
	s_waitcnt lgkmcnt(0)
	s_barrier
	s_waitcnt lgkmcnt(0)
	v_mfma_f32_16x16x32_bf16 v[126:129], v[166:169], v[198:201], v[126:129]
	v_mfma_f32_16x16x32_bf16 v[114:117], v[174:177], v[198:201], v[114:117]
	v_mfma_f32_16x16x32_bf16 v[110:113], v[166:169], v[206:209], v[110:113]
	v_mfma_f32_16x16x32_bf16 v[98:101], v[174:177], v[206:209], v[98:101]
	v_mfma_f32_16x16x32_bf16 v[94:97], v[166:169], v[214:217], v[94:97]
	v_mfma_f32_16x16x32_bf16 v[82:85], v[174:177], v[214:217], v[82:85]
	v_mfma_f32_16x16x32_bf16 v[78:81], v[166:169], v[222:225], v[78:81]
	v_mfma_f32_16x16x32_bf16 v[66:69], v[174:177], v[222:225], v[66:69]
	v_mfma_f32_16x16x32_bf16 v[126:129], v[170:173], v[202:205], v[126:129]
	v_mfma_f32_16x16x32_bf16 v[114:117], v[178:181], v[202:205], v[114:117]
	v_mfma_f32_16x16x32_bf16 v[110:113], v[170:173], v[210:213], v[110:113]
	v_mfma_f32_16x16x32_bf16 v[98:101], v[178:181], v[210:213], v[98:101]
	v_mfma_f32_16x16x32_bf16 v[94:97], v[170:173], v[218:221], v[94:97]
	v_mfma_f32_16x16x32_bf16 v[82:85], v[178:181], v[218:221], v[82:85]
	v_mfma_f32_16x16x32_bf16 v[78:81], v[170:173], v[226:229], v[78:81]
	v_mfma_f32_16x16x32_bf16 v[66:69], v[178:181], v[226:229], v[66:69]
	v_mfma_f32_16x16x32_bf16 v[122:125], v[182:185], v[198:201], v[122:125]
	v_mfma_f32_16x16x32_bf16 v[118:121], v[190:193], v[198:201], v[118:121]
	v_mfma_f32_16x16x32_bf16 v[106:109], v[182:185], v[206:209], v[106:109]
	v_mfma_f32_16x16x32_bf16 v[102:105], v[190:193], v[206:209], v[102:105]
	v_mfma_f32_16x16x32_bf16 v[90:93], v[182:185], v[214:217], v[90:93]
	v_mfma_f32_16x16x32_bf16 v[86:89], v[190:193], v[214:217], v[86:89]
	v_mfma_f32_16x16x32_bf16 v[74:77], v[182:185], v[222:225], v[74:77]
	v_mfma_f32_16x16x32_bf16 v[70:73], v[190:193], v[222:225], v[70:73]
	v_mfma_f32_16x16x32_bf16 v[122:125], v[186:189], v[202:205], v[122:125]
	v_mfma_f32_16x16x32_bf16 v[118:121], v[194:197], v[202:205], v[118:121]
	v_mfma_f32_16x16x32_bf16 v[106:109], v[186:189], v[210:213], v[106:109]
	v_mfma_f32_16x16x32_bf16 v[102:105], v[194:197], v[210:213], v[102:105]
	v_mfma_f32_16x16x32_bf16 v[90:93], v[186:189], v[218:221], v[90:93]
	v_mfma_f32_16x16x32_bf16 v[86:89], v[194:197], v[218:221], v[86:89]
	v_mfma_f32_16x16x32_bf16 v[74:77], v[186:189], v[226:229], v[74:77]
	v_mfma_f32_16x16x32_bf16 v[70:73], v[194:197], v[226:229], v[70:73]
	s_barrier
	s_add_i32 s27, s28, s51
	v_lshl_add_u64 v[130:131], s[36:37], 0, v[142:143]
	s_mov_b32 m0, s27
	ds_read_b128 v[198:201], v152 offset:16384
	ds_read_b128 v[202:205], v152 offset:17408
	ds_read_b128 v[206:209], v152 offset:18432
	ds_read_b128 v[210:213], v152 offset:19456
	ds_read_b128 v[214:217], v152 offset:20480
	ds_read_b128 v[218:221], v152 offset:21504
	ds_read_b128 v[222:225], v152 offset:22528
	ds_read_b128 v[226:229], v152 offset:23552
	global_load_lds_dwordx4 v[130:131], off
	s_add_i32 m0, s27, 0x2000
	s_add_u32 s28, s36, 0x40000
	v_lshl_add_u64 v[136:137], s[36:37], 0, v[138:139]
	s_addc_u32 s29, s37, 0
	s_add_i32 s13, s13, s51
	global_load_lds_dwordx4 v[136:137], off
	v_lshl_add_u64 v[230:231], s[28:29], 0, v[142:143]
	s_mov_b32 m0, s13
	v_lshl_add_u64 v[232:233], s[48:49], 0, v[140:141]
	global_load_lds_dwordx4 v[230:231], off
	v_lshl_add_u64 v[230:231], s[28:29], 0, v[138:139]
	s_add_i32 m0, s13, 0x2000
	s_nop 0
	global_load_lds_dwordx4 v[230:231], off
	v_lshl_add_u64 v[230:231], s[48:49], 0, v[144:145]
	s_mov_b32 m0, s52
	s_nop 0
	global_load_lds_dwordx4 v[230:231], off
	s_mov_b32 m0, s53
	s_nop 0
	global_load_lds_dwordx4 v[232:233], off
	s_waitcnt vmcnt(8)
	s_waitcnt lgkmcnt(0)
	s_barrier
	s_waitcnt lgkmcnt(0)
	v_mfma_f32_16x16x32_bf16 v[62:65], v[166:169], v[198:201], v[62:65]
	v_mfma_f32_16x16x32_bf16 v[50:53], v[174:177], v[198:201], v[50:53]
	v_mfma_f32_16x16x32_bf16 v[46:49], v[166:169], v[206:209], v[46:49]
	v_mfma_f32_16x16x32_bf16 v[34:37], v[174:177], v[206:209], v[34:37]
	v_mfma_f32_16x16x32_bf16 v[30:33], v[166:169], v[214:217], v[30:33]
	v_mfma_f32_16x16x32_bf16 v[18:21], v[174:177], v[214:217], v[18:21]
	v_mfma_f32_16x16x32_bf16 v[14:17], v[166:169], v[222:225], v[14:17]
	v_mfma_f32_16x16x32_bf16 v[6:9], v[174:177], v[222:225], v[6:9]
	v_mfma_f32_16x16x32_bf16 v[62:65], v[170:173], v[202:205], v[62:65]
	v_mfma_f32_16x16x32_bf16 v[50:53], v[178:181], v[202:205], v[50:53]
	v_mfma_f32_16x16x32_bf16 v[46:49], v[170:173], v[210:213], v[46:49]
	v_mfma_f32_16x16x32_bf16 v[34:37], v[178:181], v[210:213], v[34:37]
	v_mfma_f32_16x16x32_bf16 v[30:33], v[170:173], v[218:221], v[30:33]
	v_mfma_f32_16x16x32_bf16 v[18:21], v[178:181], v[218:221], v[18:21]
	v_mfma_f32_16x16x32_bf16 v[14:17], v[170:173], v[226:229], v[14:17]
	v_mfma_f32_16x16x32_bf16 v[6:9], v[178:181], v[226:229], v[6:9]
	v_mfma_f32_16x16x32_bf16 v[58:61], v[182:185], v[198:201], v[58:61]
	v_mfma_f32_16x16x32_bf16 v[54:57], v[190:193], v[198:201], v[54:57]
	v_mfma_f32_16x16x32_bf16 v[42:45], v[182:185], v[206:209], v[42:45]
	v_mfma_f32_16x16x32_bf16 v[38:41], v[190:193], v[206:209], v[38:41]
	v_mfma_f32_16x16x32_bf16 v[26:29], v[182:185], v[214:217], v[26:29]
	v_mfma_f32_16x16x32_bf16 v[22:25], v[190:193], v[214:217], v[22:25]
	v_mfma_f32_16x16x32_bf16 v[10:13], v[182:185], v[222:225], v[10:13]
	v_mfma_f32_16x16x32_bf16 v[2:5], v[190:193], v[222:225], v[2:5]
	v_mfma_f32_16x16x32_bf16 v[58:61], v[186:189], v[202:205], v[58:61]
	v_mfma_f32_16x16x32_bf16 v[54:57], v[194:197], v[202:205], v[54:57]
	v_mfma_f32_16x16x32_bf16 v[42:45], v[186:189], v[210:213], v[42:45]
	v_mfma_f32_16x16x32_bf16 v[38:41], v[194:197], v[210:213], v[38:41]
	v_mfma_f32_16x16x32_bf16 v[26:29], v[186:189], v[218:221], v[26:29]
	v_mfma_f32_16x16x32_bf16 v[22:25], v[194:197], v[218:221], v[22:25]
	v_mfma_f32_16x16x32_bf16 v[10:13], v[186:189], v[226:229], v[10:13]
	v_mfma_f32_16x16x32_bf16 v[2:5], v[194:197], v[226:229], v[2:5]
	s_barrier
	s_add_i32 s13, 0, 0x18000
	v_add_u32_e32 v0, s13, v150
	s_add_i32 s27, 0, 0x1c000
	ds_read_b128 v[166:169], v0
	ds_read_b128 v[170:173], v0 offset:1024
	ds_read_b128 v[174:177], v0 offset:2048
	ds_read_b128 v[178:181], v0 offset:3072
	v_add_u32_e32 v0, s27, v150
	ds_read_b128 v[182:185], v0
	ds_read_b128 v[186:189], v0 offset:1024
	ds_read_b128 v[190:193], v0 offset:2048
	ds_read_b128 v[194:197], v0 offset:3072
	s_add_u32 s28, s48, 0x40000
	s_addc_u32 s29, s49, 0
	s_mov_b32 m0, s54
	v_lshl_add_u64 v[234:235], s[28:29], 0, v[144:145]
	ds_read_b128 v[198:201], v152 offset:32768
	ds_read_b128 v[202:205], v152 offset:33792
	ds_read_b128 v[206:209], v152 offset:34816
	ds_read_b128 v[210:213], v152 offset:35840
	ds_read_b128 v[214:217], v152 offset:36864
	ds_read_b128 v[218:221], v152 offset:37888
	ds_read_b128 v[222:225], v152 offset:38912
	ds_read_b128 v[226:229], v152 offset:39936
	global_load_lds_dwordx4 v[234:235], off
	v_lshl_add_u64 v[234:235], s[28:29], 0, v[140:141]
	s_mov_b32 m0, s55
	s_nop 0
	global_load_lds_dwordx4 v[234:235], off
	s_waitcnt vmcnt(8)
	s_waitcnt lgkmcnt(0)
	s_barrier
	s_waitcnt lgkmcnt(0)
	v_mfma_f32_16x16x32_bf16 v[126:129], v[166:169], v[198:201], v[126:129]
	v_mfma_f32_16x16x32_bf16 v[114:117], v[174:177], v[198:201], v[114:117]
	v_mfma_f32_16x16x32_bf16 v[110:113], v[166:169], v[206:209], v[110:113]
	v_mfma_f32_16x16x32_bf16 v[98:101], v[174:177], v[206:209], v[98:101]
	v_mfma_f32_16x16x32_bf16 v[94:97], v[166:169], v[214:217], v[94:97]
	v_mfma_f32_16x16x32_bf16 v[82:85], v[174:177], v[214:217], v[82:85]
	v_mfma_f32_16x16x32_bf16 v[78:81], v[166:169], v[222:225], v[78:81]
	v_mfma_f32_16x16x32_bf16 v[66:69], v[174:177], v[222:225], v[66:69]
	v_mfma_f32_16x16x32_bf16 v[126:129], v[170:173], v[202:205], v[126:129]
	v_mfma_f32_16x16x32_bf16 v[114:117], v[178:181], v[202:205], v[114:117]
	v_mfma_f32_16x16x32_bf16 v[110:113], v[170:173], v[210:213], v[110:113]
	v_mfma_f32_16x16x32_bf16 v[98:101], v[178:181], v[210:213], v[98:101]
	v_mfma_f32_16x16x32_bf16 v[94:97], v[170:173], v[218:221], v[94:97]
	v_mfma_f32_16x16x32_bf16 v[82:85], v[178:181], v[218:221], v[82:85]
	v_mfma_f32_16x16x32_bf16 v[78:81], v[170:173], v[226:229], v[78:81]
	v_mfma_f32_16x16x32_bf16 v[66:69], v[178:181], v[226:229], v[66:69]
	v_mfma_f32_16x16x32_bf16 v[122:125], v[182:185], v[198:201], v[122:125]
	v_mfma_f32_16x16x32_bf16 v[118:121], v[190:193], v[198:201], v[118:121]
	v_mfma_f32_16x16x32_bf16 v[106:109], v[182:185], v[206:209], v[106:109]
	v_mfma_f32_16x16x32_bf16 v[102:105], v[190:193], v[206:209], v[102:105]
	v_mfma_f32_16x16x32_bf16 v[90:93], v[182:185], v[214:217], v[90:93]
	v_mfma_f32_16x16x32_bf16 v[86:89], v[190:193], v[214:217], v[86:89]
	v_mfma_f32_16x16x32_bf16 v[74:77], v[182:185], v[222:225], v[74:77]
	v_mfma_f32_16x16x32_bf16 v[70:73], v[190:193], v[222:225], v[70:73]
	v_mfma_f32_16x16x32_bf16 v[122:125], v[186:189], v[202:205], v[122:125]
	v_mfma_f32_16x16x32_bf16 v[118:121], v[194:197], v[202:205], v[118:121]
	v_mfma_f32_16x16x32_bf16 v[106:109], v[186:189], v[210:213], v[106:109]
	v_mfma_f32_16x16x32_bf16 v[102:105], v[194:197], v[210:213], v[102:105]
	v_mfma_f32_16x16x32_bf16 v[90:93], v[186:189], v[218:221], v[90:93]
	v_mfma_f32_16x16x32_bf16 v[86:89], v[194:197], v[218:221], v[86:89]
	v_mfma_f32_16x16x32_bf16 v[74:77], v[186:189], v[226:229], v[74:77]
	v_mfma_f32_16x16x32_bf16 v[70:73], v[194:197], v[226:229], v[70:73]
	s_barrier
	s_add_i32 s13, s13, s51
	v_lshl_add_u64 v[130:131], v[130:131], 0, s[84:85]
	s_mov_b32 m0, s13
	ds_read_b128 v[198:201], v152 offset:49152
	ds_read_b128 v[202:205], v152 offset:50176
	ds_read_b128 v[206:209], v152 offset:51200
	ds_read_b128 v[210:213], v152 offset:52224
	ds_read_b128 v[214:217], v152 offset:53248
	ds_read_b128 v[218:221], v152 offset:54272
	ds_read_b128 v[222:225], v152 offset:55296
	ds_read_b128 v[226:229], v152 offset:56320
	global_load_lds_dwordx4 v[130:131], off
	s_add_i32 m0, s13, 0x2000
	s_add_u32 s28, s36, 0x40080
	v_lshl_add_u64 v[130:131], v[136:137], 0, s[84:85]
	s_addc_u32 s29, s37, 0
	s_add_i32 s13, s27, s51
	global_load_lds_dwordx4 v[130:131], off
	v_lshl_add_u64 v[130:131], s[28:29], 0, v[142:143]
	s_mov_b32 m0, s13
	s_nop 0
	global_load_lds_dwordx4 v[130:131], off
	v_lshl_add_u64 v[130:131], s[28:29], 0, v[138:139]
	s_add_i32 m0, s13, 0x2000
	s_nop 0
	global_load_lds_dwordx4 v[130:131], off
	v_lshl_add_u64 v[130:131], v[230:231], 0, s[84:85]
	s_mov_b32 m0, s60
	s_nop 0
	global_load_lds_dwordx4 v[130:131], off
	v_lshl_add_u64 v[130:131], v[232:233], 0, s[84:85]
	s_mov_b32 m0, s61
	s_nop 0
	global_load_lds_dwordx4 v[130:131], off
	s_waitcnt vmcnt(8)
	s_waitcnt lgkmcnt(0)
	s_barrier
	s_waitcnt lgkmcnt(0)
	v_mfma_f32_16x16x32_bf16 v[62:65], v[166:169], v[198:201], v[62:65]
	v_mfma_f32_16x16x32_bf16 v[50:53], v[174:177], v[198:201], v[50:53]
	v_mfma_f32_16x16x32_bf16 v[46:49], v[166:169], v[206:209], v[46:49]
	v_mfma_f32_16x16x32_bf16 v[34:37], v[174:177], v[206:209], v[34:37]
	v_mfma_f32_16x16x32_bf16 v[30:33], v[166:169], v[214:217], v[30:33]
	v_mfma_f32_16x16x32_bf16 v[18:21], v[174:177], v[214:217], v[18:21]
	v_mfma_f32_16x16x32_bf16 v[14:17], v[166:169], v[222:225], v[14:17]
	v_mfma_f32_16x16x32_bf16 v[6:9], v[174:177], v[222:225], v[6:9]
	v_mfma_f32_16x16x32_bf16 v[62:65], v[170:173], v[202:205], v[62:65]
	v_mfma_f32_16x16x32_bf16 v[50:53], v[178:181], v[202:205], v[50:53]
	v_mfma_f32_16x16x32_bf16 v[46:49], v[170:173], v[210:213], v[46:49]
	v_mfma_f32_16x16x32_bf16 v[34:37], v[178:181], v[210:213], v[34:37]
	v_mfma_f32_16x16x32_bf16 v[30:33], v[170:173], v[218:221], v[30:33]
	v_mfma_f32_16x16x32_bf16 v[18:21], v[178:181], v[218:221], v[18:21]
	v_mfma_f32_16x16x32_bf16 v[14:17], v[170:173], v[226:229], v[14:17]
	v_mfma_f32_16x16x32_bf16 v[6:9], v[178:181], v[226:229], v[6:9]
	v_mfma_f32_16x16x32_bf16 v[58:61], v[182:185], v[198:201], v[58:61]
	v_mfma_f32_16x16x32_bf16 v[54:57], v[190:193], v[198:201], v[54:57]
	v_mfma_f32_16x16x32_bf16 v[42:45], v[182:185], v[206:209], v[42:45]
	v_mfma_f32_16x16x32_bf16 v[38:41], v[190:193], v[206:209], v[38:41]
	v_mfma_f32_16x16x32_bf16 v[26:29], v[182:185], v[214:217], v[26:29]
	v_mfma_f32_16x16x32_bf16 v[22:25], v[190:193], v[214:217], v[22:25]
	v_mfma_f32_16x16x32_bf16 v[10:13], v[182:185], v[222:225], v[10:13]
	v_mfma_f32_16x16x32_bf16 v[2:5], v[190:193], v[222:225], v[2:5]
	v_mfma_f32_16x16x32_bf16 v[58:61], v[186:189], v[202:205], v[58:61]
	v_mfma_f32_16x16x32_bf16 v[54:57], v[194:197], v[202:205], v[54:57]
	v_mfma_f32_16x16x32_bf16 v[42:45], v[186:189], v[210:213], v[42:45]
	v_mfma_f32_16x16x32_bf16 v[38:41], v[194:197], v[210:213], v[38:41]
	v_mfma_f32_16x16x32_bf16 v[26:29], v[186:189], v[218:221], v[26:29]
	v_mfma_f32_16x16x32_bf16 v[22:25], v[194:197], v[218:221], v[22:25]
	v_mfma_f32_16x16x32_bf16 v[10:13], v[186:189], v[226:229], v[10:13]
	v_mfma_f32_16x16x32_bf16 v[2:5], v[194:197], v[226:229], v[2:5]
	s_barrier
	s_add_i32 s26, s26, 2
	s_add_u32 s10, s10, 0x100
	s_addc_u32 s11, s11, 0
	s_add_u32 s24, s24, 0x100
	s_addc_u32 s25, s25, 0
	s_cmp_gt_u32 s26, 13
	s_cbranch_scc0 .LBB0_126

.LBB0_149:
	s_add_u32 s13, s40, 0xfffc0080
	s_addc_u32 s34, s41, -1
	s_add_i32 s35, 0, 0x10000
	s_cmp_eq_u32 s31, 12
	s_cselect_b32 s51, s9, s34
	s_cselect_b32 s50, s27, s13
	v_add_u32_e32 v0, s35, v159
	s_cselect_b32 s49, s7, s30
	s_cselect_b32 s48, s28, s29
	s_add_i32 s13, 0, 0x14000
	ds_read_b128 v[130:133], v0
	ds_read_b128 v[134:137], v0 offset:1024
	ds_read_b128 v[138:141], v0 offset:2048
	ds_read_b128 v[154:157], v0 offset:3072
	v_add_u32_e32 v0, s13, v159
	ds_read_b128 v[162:165], v0
	ds_read_b128 v[166:169], v0 offset:1024
	ds_read_b128 v[170:173], v0 offset:2048
	ds_read_b128 v[174:177], v0 offset:3072
	v_lshl_add_u64 v[210:211], s[40:41], 0, v[150:151]
	s_add_i32 m0, s21, 0xc000
	ds_read_b128 v[178:181], v161
	ds_read_b128 v[182:185], v161 offset:1024
	ds_read_b128 v[186:189], v161 offset:2048
	ds_read_b128 v[190:193], v161 offset:3072
	ds_read_b128 v[194:197], v161 offset:4096
	ds_read_b128 v[198:201], v161 offset:5120
	ds_read_b128 v[202:205], v161 offset:6144
	ds_read_b128 v[206:209], v161 offset:7168
	global_load_lds_dwordx4 v[210:211], off
	v_lshl_add_u64 v[210:211], s[40:41], 0, v[152:153]
	s_add_i32 m0, s21, 0xe000
	s_nop 0
	global_load_lds_dwordx4 v[210:211], off
	s_waitcnt vmcnt(8)
	s_waitcnt lgkmcnt(0)
	s_barrier
	s_waitcnt lgkmcnt(0)
	v_mfma_f32_16x16x32_bf16 v[126:129], v[130:133], v[178:181], v[126:129]
	v_mfma_f32_16x16x32_bf16 v[122:125], v[138:141], v[178:181], v[122:125]
	v_mfma_f32_16x16x32_bf16 v[114:117], v[130:133], v[186:189], v[114:117]
	v_mfma_f32_16x16x32_bf16 v[106:109], v[138:141], v[186:189], v[106:109]
	v_mfma_f32_16x16x32_bf16 v[102:105], v[130:133], v[194:197], v[102:105]
	v_mfma_f32_16x16x32_bf16 v[94:97], v[138:141], v[194:197], v[94:97]
	v_mfma_f32_16x16x32_bf16 v[86:89], v[130:133], v[202:205], v[86:89]
	v_mfma_f32_16x16x32_bf16 v[78:81], v[138:141], v[202:205], v[78:81]
	v_mfma_f32_16x16x32_bf16 v[126:129], v[134:137], v[182:185], v[126:129]
	v_mfma_f32_16x16x32_bf16 v[122:125], v[154:157], v[182:185], v[122:125]
	v_mfma_f32_16x16x32_bf16 v[114:117], v[134:137], v[190:193], v[114:117]
	v_mfma_f32_16x16x32_bf16 v[106:109], v[154:157], v[190:193], v[106:109]
	v_mfma_f32_16x16x32_bf16 v[102:105], v[134:137], v[198:201], v[102:105]
	v_mfma_f32_16x16x32_bf16 v[94:97], v[154:157], v[198:201], v[94:97]
	v_mfma_f32_16x16x32_bf16 v[86:89], v[134:137], v[206:209], v[86:89]
	v_mfma_f32_16x16x32_bf16 v[78:81], v[154:157], v[206:209], v[78:81]
	v_mfma_f32_16x16x32_bf16 v[118:121], v[162:165], v[178:181], v[118:121]
	v_mfma_f32_16x16x32_bf16 v[110:113], v[170:173], v[178:181], v[110:113]
	v_mfma_f32_16x16x32_bf16 v[98:101], v[162:165], v[186:189], v[98:101]
	v_mfma_f32_16x16x32_bf16 v[90:93], v[170:173], v[186:189], v[90:93]
	v_mfma_f32_16x16x32_bf16 v[82:85], v[162:165], v[194:197], v[82:85]
	v_mfma_f32_16x16x32_bf16 v[74:77], v[170:173], v[194:197], v[74:77]
	v_mfma_f32_16x16x32_bf16 v[70:73], v[162:165], v[202:205], v[70:73]
	v_mfma_f32_16x16x32_bf16 v[66:69], v[170:173], v[202:205], v[66:69]
	v_mfma_f32_16x16x32_bf16 v[118:121], v[166:169], v[182:185], v[118:121]
	v_mfma_f32_16x16x32_bf16 v[110:113], v[174:177], v[182:185], v[110:113]
	v_mfma_f32_16x16x32_bf16 v[98:101], v[166:169], v[190:193], v[98:101]
	v_mfma_f32_16x16x32_bf16 v[90:93], v[174:177], v[190:193], v[90:93]
	v_mfma_f32_16x16x32_bf16 v[82:85], v[166:169], v[198:201], v[82:85]
	v_mfma_f32_16x16x32_bf16 v[74:77], v[174:177], v[198:201], v[74:77]
	v_mfma_f32_16x16x32_bf16 v[70:73], v[166:169], v[206:209], v[70:73]
	v_mfma_f32_16x16x32_bf16 v[66:69], v[174:177], v[206:209], v[66:69]
	s_barrier
	s_add_i32 s34, s35, s20
	v_lshl_add_u64 v[210:211], s[48:49], 0, v[146:147]
	s_mov_b32 m0, s34
	ds_read_b128 v[178:181], v161 offset:16384
	ds_read_b128 v[182:185], v161 offset:17408
	ds_read_b128 v[186:189], v161 offset:18432
	ds_read_b128 v[190:193], v161 offset:19456
	ds_read_b128 v[194:197], v161 offset:20480
	ds_read_b128 v[198:201], v161 offset:21504
	ds_read_b128 v[202:205], v161 offset:22528
	ds_read_b128 v[206:209], v161 offset:23552
	global_load_lds_dwordx4 v[210:211], off
	s_add_i32 m0, s34, 0x2000
	s_add_u32 s34, s48, 0x40000
	v_lshl_add_u64 v[212:213], s[48:49], 0, v[142:143]
	s_addc_u32 s35, s49, 0
	s_add_i32 s13, s13, s20
	global_load_lds_dwordx4 v[212:213], off
	v_lshl_add_u64 v[214:215], s[34:35], 0, v[146:147]
	s_mov_b32 m0, s13
	v_lshl_add_u64 v[216:217], s[50:51], 0, v[144:145]
	global_load_lds_dwordx4 v[214:215], off
	v_lshl_add_u64 v[214:215], s[34:35], 0, v[142:143]
	s_add_i32 m0, s13, 0x2000
	s_nop 0
	global_load_lds_dwordx4 v[214:215], off
	v_lshl_add_u64 v[214:215], s[50:51], 0, v[148:149]
	s_mov_b32 m0, s21
	s_nop 0
	global_load_lds_dwordx4 v[214:215], off
	s_mov_b32 m0, s22
	s_nop 0
	global_load_lds_dwordx4 v[216:217], off
	s_waitcnt vmcnt(8)
	s_waitcnt lgkmcnt(0)
	s_barrier
	s_waitcnt lgkmcnt(0)
	v_mfma_f32_16x16x32_bf16 v[62:65], v[130:133], v[178:181], v[62:65]
	v_mfma_f32_16x16x32_bf16 v[58:61], v[138:141], v[178:181], v[58:61]
	v_mfma_f32_16x16x32_bf16 v[50:53], v[130:133], v[186:189], v[50:53]
	v_mfma_f32_16x16x32_bf16 v[42:45], v[138:141], v[186:189], v[42:45]
	v_mfma_f32_16x16x32_bf16 v[38:41], v[130:133], v[194:197], v[38:41]
	v_mfma_f32_16x16x32_bf16 v[30:33], v[138:141], v[194:197], v[30:33]
	v_mfma_f32_16x16x32_bf16 v[22:25], v[130:133], v[202:205], v[22:25]
	v_mfma_f32_16x16x32_bf16 v[14:17], v[138:141], v[202:205], v[14:17]
	v_mfma_f32_16x16x32_bf16 v[62:65], v[134:137], v[182:185], v[62:65]
	v_mfma_f32_16x16x32_bf16 v[58:61], v[154:157], v[182:185], v[58:61]
	v_mfma_f32_16x16x32_bf16 v[50:53], v[134:137], v[190:193], v[50:53]
	v_mfma_f32_16x16x32_bf16 v[42:45], v[154:157], v[190:193], v[42:45]
	v_mfma_f32_16x16x32_bf16 v[38:41], v[134:137], v[198:201], v[38:41]
	v_mfma_f32_16x16x32_bf16 v[30:33], v[154:157], v[198:201], v[30:33]
	v_mfma_f32_16x16x32_bf16 v[22:25], v[134:137], v[206:209], v[22:25]
	v_mfma_f32_16x16x32_bf16 v[14:17], v[154:157], v[206:209], v[14:17]
	v_mfma_f32_16x16x32_bf16 v[54:57], v[162:165], v[178:181], v[54:57]
	v_mfma_f32_16x16x32_bf16 v[46:49], v[170:173], v[178:181], v[46:49]
	v_mfma_f32_16x16x32_bf16 v[34:37], v[162:165], v[186:189], v[34:37]
	v_mfma_f32_16x16x32_bf16 v[26:29], v[170:173], v[186:189], v[26:29]
	v_mfma_f32_16x16x32_bf16 v[18:21], v[162:165], v[194:197], v[18:21]
	v_mfma_f32_16x16x32_bf16 v[10:13], v[170:173], v[194:197], v[10:13]
	v_mfma_f32_16x16x32_bf16 v[6:9], v[162:165], v[202:205], v[6:9]
	v_mfma_f32_16x16x32_bf16 v[2:5], v[170:173], v[202:205], v[2:5]
	v_mfma_f32_16x16x32_bf16 v[54:57], v[166:169], v[182:185], v[54:57]
	v_mfma_f32_16x16x32_bf16 v[46:49], v[174:177], v[182:185], v[46:49]
	v_mfma_f32_16x16x32_bf16 v[34:37], v[166:169], v[190:193], v[34:37]
	v_mfma_f32_16x16x32_bf16 v[26:29], v[174:177], v[190:193], v[26:29]
	v_mfma_f32_16x16x32_bf16 v[18:21], v[166:169], v[198:201], v[18:21]
	v_mfma_f32_16x16x32_bf16 v[10:13], v[174:177], v[198:201], v[10:13]
	v_mfma_f32_16x16x32_bf16 v[6:9], v[166:169], v[206:209], v[6:9]
	v_mfma_f32_16x16x32_bf16 v[2:5], v[174:177], v[206:209], v[2:5]
	s_barrier
	s_add_i32 s13, 0, 0x18000
	v_add_u32_e32 v0, s13, v159
	s_add_i32 s58, 0, 0x1c000
	ds_read_b128 v[130:133], v0
	ds_read_b128 v[134:137], v0 offset:1024
	ds_read_b128 v[138:141], v0 offset:2048
	ds_read_b128 v[154:157], v0 offset:3072
	v_add_u32_e32 v0, s58, v159
	ds_read_b128 v[162:165], v0
	ds_read_b128 v[166:169], v0 offset:1024
	ds_read_b128 v[170:173], v0 offset:2048
	ds_read_b128 v[174:177], v0 offset:3072
	s_add_u32 s34, s50, 0x40000
	s_addc_u32 s35, s51, 0
	s_mov_b32 m0, s23
	v_lshl_add_u64 v[218:219], s[34:35], 0, v[148:149]
	ds_read_b128 v[178:181], v161 offset:32768
	ds_read_b128 v[182:185], v161 offset:33792
	ds_read_b128 v[186:189], v161 offset:34816
	ds_read_b128 v[190:193], v161 offset:35840
	ds_read_b128 v[194:197], v161 offset:36864
	ds_read_b128 v[198:201], v161 offset:37888
	ds_read_b128 v[202:205], v161 offset:38912
	ds_read_b128 v[206:209], v161 offset:39936
	global_load_lds_dwordx4 v[218:219], off
	v_lshl_add_u64 v[218:219], s[34:35], 0, v[144:145]
	s_mov_b32 m0, s24
	s_nop 0
	global_load_lds_dwordx4 v[218:219], off
	s_waitcnt vmcnt(8)
	s_waitcnt lgkmcnt(0)
	s_barrier
	s_waitcnt lgkmcnt(0)
	v_mfma_f32_16x16x32_bf16 v[126:129], v[130:133], v[178:181], v[126:129]
	v_mfma_f32_16x16x32_bf16 v[122:125], v[138:141], v[178:181], v[122:125]
	v_mfma_f32_16x16x32_bf16 v[114:117], v[130:133], v[186:189], v[114:117]
	v_mfma_f32_16x16x32_bf16 v[106:109], v[138:141], v[186:189], v[106:109]
	v_mfma_f32_16x16x32_bf16 v[102:105], v[130:133], v[194:197], v[102:105]
	v_mfma_f32_16x16x32_bf16 v[94:97], v[138:141], v[194:197], v[94:97]
	v_mfma_f32_16x16x32_bf16 v[86:89], v[130:133], v[202:205], v[86:89]
	v_mfma_f32_16x16x32_bf16 v[78:81], v[138:141], v[202:205], v[78:81]
	v_mfma_f32_16x16x32_bf16 v[126:129], v[134:137], v[182:185], v[126:129]
	v_mfma_f32_16x16x32_bf16 v[122:125], v[154:157], v[182:185], v[122:125]
	v_mfma_f32_16x16x32_bf16 v[114:117], v[134:137], v[190:193], v[114:117]
	v_mfma_f32_16x16x32_bf16 v[106:109], v[154:157], v[190:193], v[106:109]
	v_mfma_f32_16x16x32_bf16 v[102:105], v[134:137], v[198:201], v[102:105]
	v_mfma_f32_16x16x32_bf16 v[94:97], v[154:157], v[198:201], v[94:97]
	v_mfma_f32_16x16x32_bf16 v[86:89], v[134:137], v[206:209], v[86:89]
	v_mfma_f32_16x16x32_bf16 v[78:81], v[154:157], v[206:209], v[78:81]
	v_mfma_f32_16x16x32_bf16 v[118:121], v[162:165], v[178:181], v[118:121]
	v_mfma_f32_16x16x32_bf16 v[110:113], v[170:173], v[178:181], v[110:113]
	v_mfma_f32_16x16x32_bf16 v[98:101], v[162:165], v[186:189], v[98:101]
	v_mfma_f32_16x16x32_bf16 v[90:93], v[170:173], v[186:189], v[90:93]
	v_mfma_f32_16x16x32_bf16 v[82:85], v[162:165], v[194:197], v[82:85]
	v_mfma_f32_16x16x32_bf16 v[74:77], v[170:173], v[194:197], v[74:77]
	v_mfma_f32_16x16x32_bf16 v[70:73], v[162:165], v[202:205], v[70:73]
	v_mfma_f32_16x16x32_bf16 v[66:69], v[170:173], v[202:205], v[66:69]
	v_mfma_f32_16x16x32_bf16 v[118:121], v[166:169], v[182:185], v[118:121]
	v_mfma_f32_16x16x32_bf16 v[110:113], v[174:177], v[182:185], v[110:113]
	v_mfma_f32_16x16x32_bf16 v[98:101], v[166:169], v[190:193], v[98:101]
	v_mfma_f32_16x16x32_bf16 v[90:93], v[174:177], v[190:193], v[90:93]
	v_mfma_f32_16x16x32_bf16 v[82:85], v[166:169], v[198:201], v[82:85]
	v_mfma_f32_16x16x32_bf16 v[74:77], v[174:177], v[198:201], v[74:77]
	v_mfma_f32_16x16x32_bf16 v[70:73], v[166:169], v[206:209], v[70:73]
	v_mfma_f32_16x16x32_bf16 v[66:69], v[174:177], v[206:209], v[66:69]
	s_barrier
	s_add_i32 s13, s13, s20
	v_lshl_add_u64 v[210:211], v[210:211], 0, s[84:85]
	s_mov_b32 m0, s13
	ds_read_b128 v[178:181], v161 offset:49152
	ds_read_b128 v[182:185], v161 offset:50176
	ds_read_b128 v[186:189], v161 offset:51200
	ds_read_b128 v[190:193], v161 offset:52224
	ds_read_b128 v[194:197], v161 offset:53248
	ds_read_b128 v[198:201], v161 offset:54272
	ds_read_b128 v[202:205], v161 offset:55296
	ds_read_b128 v[206:209], v161 offset:56320
	global_load_lds_dwordx4 v[210:211], off
	s_add_i32 m0, s13, 0x2000
	s_add_u32 s34, s48, 0x40080
	v_lshl_add_u64 v[210:211], v[212:213], 0, s[84:85]
	s_addc_u32 s35, s49, 0
	s_add_i32 s13, s58, s20
	global_load_lds_dwordx4 v[210:211], off
	v_lshl_add_u64 v[210:211], s[34:35], 0, v[146:147]
	s_mov_b32 m0, s13
	s_nop 0
	global_load_lds_dwordx4 v[210:211], off
	v_lshl_add_u64 v[210:211], s[34:35], 0, v[142:143]
	s_add_i32 m0, s13, 0x2000
	s_nop 0
	global_load_lds_dwordx4 v[210:211], off
	v_lshl_add_u64 v[210:211], v[214:215], 0, s[84:85]
	s_mov_b32 m0, s52
	s_nop 0
	global_load_lds_dwordx4 v[210:211], off
	v_lshl_add_u64 v[210:211], v[216:217], 0, s[84:85]
	s_mov_b32 m0, s53
	s_nop 0
	global_load_lds_dwordx4 v[210:211], off
	s_waitcnt vmcnt(8)
	s_waitcnt lgkmcnt(0)
	s_barrier
	s_waitcnt lgkmcnt(0)
	v_mfma_f32_16x16x32_bf16 v[62:65], v[130:133], v[178:181], v[62:65]
	v_mfma_f32_16x16x32_bf16 v[58:61], v[138:141], v[178:181], v[58:61]
	v_mfma_f32_16x16x32_bf16 v[50:53], v[130:133], v[186:189], v[50:53]
	v_mfma_f32_16x16x32_bf16 v[42:45], v[138:141], v[186:189], v[42:45]
	v_mfma_f32_16x16x32_bf16 v[38:41], v[130:133], v[194:197], v[38:41]
	v_mfma_f32_16x16x32_bf16 v[30:33], v[138:141], v[194:197], v[30:33]
	v_mfma_f32_16x16x32_bf16 v[22:25], v[130:133], v[202:205], v[22:25]
	v_mfma_f32_16x16x32_bf16 v[14:17], v[138:141], v[202:205], v[14:17]
	v_mfma_f32_16x16x32_bf16 v[62:65], v[134:137], v[182:185], v[62:65]
	v_mfma_f32_16x16x32_bf16 v[58:61], v[154:157], v[182:185], v[58:61]
	v_mfma_f32_16x16x32_bf16 v[50:53], v[134:137], v[190:193], v[50:53]
	v_mfma_f32_16x16x32_bf16 v[42:45], v[154:157], v[190:193], v[42:45]
	v_mfma_f32_16x16x32_bf16 v[38:41], v[134:137], v[198:201], v[38:41]
	v_mfma_f32_16x16x32_bf16 v[30:33], v[154:157], v[198:201], v[30:33]
	v_mfma_f32_16x16x32_bf16 v[22:25], v[134:137], v[206:209], v[22:25]
	v_mfma_f32_16x16x32_bf16 v[14:17], v[154:157], v[206:209], v[14:17]
	v_mfma_f32_16x16x32_bf16 v[54:57], v[162:165], v[178:181], v[54:57]
	v_mfma_f32_16x16x32_bf16 v[46:49], v[170:173], v[178:181], v[46:49]
	v_mfma_f32_16x16x32_bf16 v[34:37], v[162:165], v[186:189], v[34:37]
	v_mfma_f32_16x16x32_bf16 v[26:29], v[170:173], v[186:189], v[26:29]
	v_mfma_f32_16x16x32_bf16 v[18:21], v[162:165], v[194:197], v[18:21]
	v_mfma_f32_16x16x32_bf16 v[10:13], v[170:173], v[194:197], v[10:13]
	v_mfma_f32_16x16x32_bf16 v[6:9], v[162:165], v[202:205], v[6:9]
	v_mfma_f32_16x16x32_bf16 v[2:5], v[170:173], v[202:205], v[2:5]
	v_mfma_f32_16x16x32_bf16 v[54:57], v[166:169], v[182:185], v[54:57]
	v_mfma_f32_16x16x32_bf16 v[46:49], v[174:177], v[182:185], v[46:49]
	v_mfma_f32_16x16x32_bf16 v[34:37], v[166:169], v[190:193], v[34:37]
	v_mfma_f32_16x16x32_bf16 v[26:29], v[174:177], v[190:193], v[26:29]
	v_mfma_f32_16x16x32_bf16 v[18:21], v[166:169], v[198:201], v[18:21]
	v_mfma_f32_16x16x32_bf16 v[10:13], v[174:177], v[198:201], v[10:13]
	v_mfma_f32_16x16x32_bf16 v[6:9], v[166:169], v[206:209], v[6:9]
	v_mfma_f32_16x16x32_bf16 v[2:5], v[174:177], v[206:209], v[2:5]
	s_barrier
	s_add_i32 s31, s31, 2
	s_add_u32 s40, s40, 0x100
	s_addc_u32 s41, s41, 0
	s_add_u32 s29, s29, 0x100
	s_addc_u32 s30, s30, 0
	s_cmp_gt_u32 s31, 13
	s_cbranch_scc0 .LBB0_149
	s_and_b64 vcc, exec, s[4:5]
	s_cbranch_vccz .LBB0_152
	s_barrier

.LBB0_173:
	s_add_u32 s13, s10, 0xfffc0080
	s_addc_u32 s26, s11, -1
	s_add_i32 s27, 0, 0x10000
	s_cmp_eq_u32 s25, 12
	s_cselect_b32 s49, s5, s26
	s_cselect_b32 s48, s21, s13
	v_add_u32_e32 v0, s27, v160
	s_cselect_b32 s41, s1, s24
	s_cselect_b32 s40, s22, s23
	s_add_i32 s13, 0, 0x14000
	ds_read_b128 v[130:133], v0
	ds_read_b128 v[134:137], v0 offset:1024
	ds_read_b128 v[138:141], v0 offset:2048
	ds_read_b128 v[142:145], v0 offset:3072
	v_add_u32_e32 v0, s13, v160
	ds_read_b128 v[162:165], v0
	ds_read_b128 v[166:169], v0 offset:1024
	ds_read_b128 v[170:173], v0 offset:2048
	ds_read_b128 v[174:177], v0 offset:3072
	v_lshl_add_u64 v[158:159], s[10:11], 0, v[154:155]
	s_add_i32 m0, s52, 0xc000
	ds_read_b128 v[178:181], v161
	ds_read_b128 v[182:185], v161 offset:1024
	ds_read_b128 v[186:189], v161 offset:2048
	ds_read_b128 v[190:193], v161 offset:3072
	ds_read_b128 v[194:197], v161 offset:4096
	ds_read_b128 v[198:201], v161 offset:5120
	ds_read_b128 v[202:205], v161 offset:6144
	ds_read_b128 v[206:209], v161 offset:7168
	global_load_lds_dwordx4 v[158:159], off
	v_lshl_add_u64 v[158:159], s[10:11], 0, v[156:157]
	s_add_i32 m0, s52, 0xe000
	s_nop 0
	global_load_lds_dwordx4 v[158:159], off
	s_waitcnt vmcnt(8)
	s_waitcnt lgkmcnt(0)
	s_barrier
	s_waitcnt lgkmcnt(0)
	v_mfma_f32_16x16x32_bf16 v[126:129], v[130:133], v[178:181], v[126:129]
	v_mfma_f32_16x16x32_bf16 v[122:125], v[138:141], v[178:181], v[122:125]
	v_mfma_f32_16x16x32_bf16 v[118:121], v[130:133], v[186:189], v[118:121]
	v_mfma_f32_16x16x32_bf16 v[114:117], v[138:141], v[186:189], v[114:117]
	v_mfma_f32_16x16x32_bf16 v[110:113], v[130:133], v[194:197], v[110:113]
	v_mfma_f32_16x16x32_bf16 v[106:109], v[138:141], v[194:197], v[106:109]
	v_mfma_f32_16x16x32_bf16 v[102:105], v[130:133], v[202:205], v[102:105]
	v_mfma_f32_16x16x32_bf16 v[98:101], v[138:141], v[202:205], v[98:101]
	v_mfma_f32_16x16x32_bf16 v[126:129], v[134:137], v[182:185], v[126:129]
	v_mfma_f32_16x16x32_bf16 v[122:125], v[142:145], v[182:185], v[122:125]
	v_mfma_f32_16x16x32_bf16 v[118:121], v[134:137], v[190:193], v[118:121]
	v_mfma_f32_16x16x32_bf16 v[114:117], v[142:145], v[190:193], v[114:117]
	v_mfma_f32_16x16x32_bf16 v[110:113], v[134:137], v[198:201], v[110:113]
	v_mfma_f32_16x16x32_bf16 v[106:109], v[142:145], v[198:201], v[106:109]
	v_mfma_f32_16x16x32_bf16 v[102:105], v[134:137], v[206:209], v[102:105]
	v_mfma_f32_16x16x32_bf16 v[98:101], v[142:145], v[206:209], v[98:101]
	v_mfma_f32_16x16x32_bf16 v[62:65], v[162:165], v[178:181], v[62:65]
	v_mfma_f32_16x16x32_bf16 v[58:61], v[170:173], v[178:181], v[58:61]
	v_mfma_f32_16x16x32_bf16 v[54:57], v[162:165], v[186:189], v[54:57]
	v_mfma_f32_16x16x32_bf16 v[50:53], v[170:173], v[186:189], v[50:53]
	v_mfma_f32_16x16x32_bf16 v[46:49], v[162:165], v[194:197], v[46:49]
	v_mfma_f32_16x16x32_bf16 v[42:45], v[170:173], v[194:197], v[42:45]
	v_mfma_f32_16x16x32_bf16 v[38:41], v[162:165], v[202:205], v[38:41]
	v_mfma_f32_16x16x32_bf16 v[34:37], v[170:173], v[202:205], v[34:37]
	v_mfma_f32_16x16x32_bf16 v[62:65], v[166:169], v[182:185], v[62:65]
	v_mfma_f32_16x16x32_bf16 v[58:61], v[174:177], v[182:185], v[58:61]
	v_mfma_f32_16x16x32_bf16 v[54:57], v[166:169], v[190:193], v[54:57]
	v_mfma_f32_16x16x32_bf16 v[50:53], v[174:177], v[190:193], v[50:53]
	v_mfma_f32_16x16x32_bf16 v[46:49], v[166:169], v[198:201], v[46:49]
	v_mfma_f32_16x16x32_bf16 v[42:45], v[174:177], v[198:201], v[42:45]
	v_mfma_f32_16x16x32_bf16 v[38:41], v[166:169], v[206:209], v[38:41]
	v_mfma_f32_16x16x32_bf16 v[34:37], v[174:177], v[206:209], v[34:37]
	s_barrier
	s_add_i32 s26, s27, s51
	v_lshl_add_u64 v[158:159], s[40:41], 0, v[150:151]
	s_mov_b32 m0, s26
	ds_read_b128 v[178:181], v161 offset:16384
	ds_read_b128 v[182:185], v161 offset:17408
	ds_read_b128 v[186:189], v161 offset:18432
	ds_read_b128 v[190:193], v161 offset:19456
	ds_read_b128 v[194:197], v161 offset:20480
	ds_read_b128 v[198:201], v161 offset:21504
	ds_read_b128 v[202:205], v161 offset:22528
	ds_read_b128 v[206:209], v161 offset:23552
	global_load_lds_dwordx4 v[158:159], off
	s_add_i32 m0, s26, 0x2000
	s_add_u32 s26, s40, 0x40000
	v_lshl_add_u64 v[210:211], s[40:41], 0, v[146:147]
	s_addc_u32 s27, s41, 0
	s_add_i32 s13, s13, s51
	global_load_lds_dwordx4 v[210:211], off
	v_lshl_add_u64 v[212:213], s[26:27], 0, v[150:151]
	s_mov_b32 m0, s13
	v_lshl_add_u64 v[214:215], s[48:49], 0, v[148:149]
	global_load_lds_dwordx4 v[212:213], off
	v_lshl_add_u64 v[212:213], s[26:27], 0, v[146:147]
	s_add_i32 m0, s13, 0x2000
	s_nop 0
	global_load_lds_dwordx4 v[212:213], off
	v_lshl_add_u64 v[212:213], s[48:49], 0, v[152:153]
	s_mov_b32 m0, s52
	s_nop 0
	global_load_lds_dwordx4 v[212:213], off
	s_mov_b32 m0, s53
	s_nop 0
	global_load_lds_dwordx4 v[214:215], off
	s_waitcnt vmcnt(8)
	s_waitcnt lgkmcnt(0)
	s_barrier
	s_waitcnt lgkmcnt(0)
	v_mfma_f32_16x16x32_bf16 v[94:97], v[130:133], v[178:181], v[94:97]
	v_mfma_f32_16x16x32_bf16 v[90:93], v[138:141], v[178:181], v[90:93]
	v_mfma_f32_16x16x32_bf16 v[86:89], v[130:133], v[186:189], v[86:89]
	v_mfma_f32_16x16x32_bf16 v[82:85], v[138:141], v[186:189], v[82:85]
	v_mfma_f32_16x16x32_bf16 v[78:81], v[130:133], v[194:197], v[78:81]
	v_mfma_f32_16x16x32_bf16 v[74:77], v[138:141], v[194:197], v[74:77]
	v_mfma_f32_16x16x32_bf16 v[70:73], v[130:133], v[202:205], v[70:73]
	v_mfma_f32_16x16x32_bf16 v[66:69], v[138:141], v[202:205], v[66:69]
	v_mfma_f32_16x16x32_bf16 v[94:97], v[134:137], v[182:185], v[94:97]
	v_mfma_f32_16x16x32_bf16 v[90:93], v[142:145], v[182:185], v[90:93]
	v_mfma_f32_16x16x32_bf16 v[86:89], v[134:137], v[190:193], v[86:89]
	v_mfma_f32_16x16x32_bf16 v[82:85], v[142:145], v[190:193], v[82:85]
	v_mfma_f32_16x16x32_bf16 v[78:81], v[134:137], v[198:201], v[78:81]
	v_mfma_f32_16x16x32_bf16 v[74:77], v[142:145], v[198:201], v[74:77]
	v_mfma_f32_16x16x32_bf16 v[70:73], v[134:137], v[206:209], v[70:73]
	v_mfma_f32_16x16x32_bf16 v[66:69], v[142:145], v[206:209], v[66:69]
	v_mfma_f32_16x16x32_bf16 v[30:33], v[162:165], v[178:181], v[30:33]
	v_mfma_f32_16x16x32_bf16 v[26:29], v[170:173], v[178:181], v[26:29]
	v_mfma_f32_16x16x32_bf16 v[22:25], v[162:165], v[186:189], v[22:25]
	v_mfma_f32_16x16x32_bf16 v[18:21], v[170:173], v[186:189], v[18:21]
	v_mfma_f32_16x16x32_bf16 v[14:17], v[162:165], v[194:197], v[14:17]
	v_mfma_f32_16x16x32_bf16 v[10:13], v[170:173], v[194:197], v[10:13]
	v_mfma_f32_16x16x32_bf16 v[6:9], v[162:165], v[202:205], v[6:9]
	v_mfma_f32_16x16x32_bf16 v[2:5], v[170:173], v[202:205], v[2:5]
	v_mfma_f32_16x16x32_bf16 v[30:33], v[166:169], v[182:185], v[30:33]
	v_mfma_f32_16x16x32_bf16 v[26:29], v[174:177], v[182:185], v[26:29]
	v_mfma_f32_16x16x32_bf16 v[22:25], v[166:169], v[190:193], v[22:25]
	v_mfma_f32_16x16x32_bf16 v[18:21], v[174:177], v[190:193], v[18:21]
	v_mfma_f32_16x16x32_bf16 v[14:17], v[166:169], v[198:201], v[14:17]
	v_mfma_f32_16x16x32_bf16 v[10:13], v[174:177], v[198:201], v[10:13]
	v_mfma_f32_16x16x32_bf16 v[6:9], v[166:169], v[206:209], v[6:9]
	v_mfma_f32_16x16x32_bf16 v[2:5], v[174:177], v[206:209], v[2:5]
	s_barrier
	s_add_i32 s13, 0, 0x18000
	v_add_u32_e32 v0, s13, v160
	s_add_i32 s28, 0, 0x1c000
	ds_read_b128 v[130:133], v0
	ds_read_b128 v[134:137], v0 offset:1024
	ds_read_b128 v[138:141], v0 offset:2048
	ds_read_b128 v[142:145], v0 offset:3072
	v_add_u32_e32 v0, s28, v160
	ds_read_b128 v[162:165], v0
	ds_read_b128 v[166:169], v0 offset:1024
	ds_read_b128 v[170:173], v0 offset:2048
	ds_read_b128 v[174:177], v0 offset:3072
	s_add_u32 s26, s48, 0x40000
	s_addc_u32 s27, s49, 0
	s_mov_b32 m0, s54
	v_lshl_add_u64 v[216:217], s[26:27], 0, v[152:153]
	ds_read_b128 v[178:181], v161 offset:32768
	ds_read_b128 v[182:185], v161 offset:33792
	ds_read_b128 v[186:189], v161 offset:34816
	ds_read_b128 v[190:193], v161 offset:35840
	ds_read_b128 v[194:197], v161 offset:36864
	ds_read_b128 v[198:201], v161 offset:37888
	ds_read_b128 v[202:205], v161 offset:38912
	ds_read_b128 v[206:209], v161 offset:39936
	global_load_lds_dwordx4 v[216:217], off
	v_lshl_add_u64 v[216:217], s[26:27], 0, v[148:149]
	s_mov_b32 m0, s55
	s_nop 0
	global_load_lds_dwordx4 v[216:217], off
	s_waitcnt vmcnt(8)
	s_waitcnt lgkmcnt(0)
	s_barrier
	s_waitcnt lgkmcnt(0)
	v_mfma_f32_16x16x32_bf16 v[126:129], v[130:133], v[178:181], v[126:129]
	v_mfma_f32_16x16x32_bf16 v[122:125], v[138:141], v[178:181], v[122:125]
	v_mfma_f32_16x16x32_bf16 v[118:121], v[130:133], v[186:189], v[118:121]
	v_mfma_f32_16x16x32_bf16 v[114:117], v[138:141], v[186:189], v[114:117]
	v_mfma_f32_16x16x32_bf16 v[110:113], v[130:133], v[194:197], v[110:113]
	v_mfma_f32_16x16x32_bf16 v[106:109], v[138:141], v[194:197], v[106:109]
	v_mfma_f32_16x16x32_bf16 v[102:105], v[130:133], v[202:205], v[102:105]
	v_mfma_f32_16x16x32_bf16 v[98:101], v[138:141], v[202:205], v[98:101]
	v_mfma_f32_16x16x32_bf16 v[126:129], v[134:137], v[182:185], v[126:129]
	v_mfma_f32_16x16x32_bf16 v[122:125], v[142:145], v[182:185], v[122:125]
	v_mfma_f32_16x16x32_bf16 v[118:121], v[134:137], v[190:193], v[118:121]
	v_mfma_f32_16x16x32_bf16 v[114:117], v[142:145], v[190:193], v[114:117]
	v_mfma_f32_16x16x32_bf16 v[110:113], v[134:137], v[198:201], v[110:113]
	v_mfma_f32_16x16x32_bf16 v[106:109], v[142:145], v[198:201], v[106:109]
	v_mfma_f32_16x16x32_bf16 v[102:105], v[134:137], v[206:209], v[102:105]
	v_mfma_f32_16x16x32_bf16 v[98:101], v[142:145], v[206:209], v[98:101]
	v_mfma_f32_16x16x32_bf16 v[62:65], v[162:165], v[178:181], v[62:65]
	v_mfma_f32_16x16x32_bf16 v[58:61], v[170:173], v[178:181], v[58:61]
	v_mfma_f32_16x16x32_bf16 v[54:57], v[162:165], v[186:189], v[54:57]
	v_mfma_f32_16x16x32_bf16 v[50:53], v[170:173], v[186:189], v[50:53]
	v_mfma_f32_16x16x32_bf16 v[46:49], v[162:165], v[194:197], v[46:49]
	v_mfma_f32_16x16x32_bf16 v[42:45], v[170:173], v[194:197], v[42:45]
	v_mfma_f32_16x16x32_bf16 v[38:41], v[162:165], v[202:205], v[38:41]
	v_mfma_f32_16x16x32_bf16 v[34:37], v[170:173], v[202:205], v[34:37]
	v_mfma_f32_16x16x32_bf16 v[62:65], v[166:169], v[182:185], v[62:65]
	v_mfma_f32_16x16x32_bf16 v[58:61], v[174:177], v[182:185], v[58:61]
	v_mfma_f32_16x16x32_bf16 v[54:57], v[166:169], v[190:193], v[54:57]
	v_mfma_f32_16x16x32_bf16 v[50:53], v[174:177], v[190:193], v[50:53]
	v_mfma_f32_16x16x32_bf16 v[46:49], v[166:169], v[198:201], v[46:49]
	v_mfma_f32_16x16x32_bf16 v[42:45], v[174:177], v[198:201], v[42:45]
	v_mfma_f32_16x16x32_bf16 v[38:41], v[166:169], v[206:209], v[38:41]
	v_mfma_f32_16x16x32_bf16 v[34:37], v[174:177], v[206:209], v[34:37]
	s_barrier
	s_add_i32 s13, s13, s51
	v_lshl_add_u64 v[158:159], v[158:159], 0, s[84:85]
	s_mov_b32 m0, s13
	ds_read_b128 v[178:181], v161 offset:49152
	ds_read_b128 v[182:185], v161 offset:50176
	ds_read_b128 v[186:189], v161 offset:51200
	ds_read_b128 v[190:193], v161 offset:52224
	ds_read_b128 v[194:197], v161 offset:53248
	ds_read_b128 v[198:201], v161 offset:54272
	ds_read_b128 v[202:205], v161 offset:55296
	ds_read_b128 v[206:209], v161 offset:56320
	global_load_lds_dwordx4 v[158:159], off
	s_add_i32 m0, s13, 0x2000
	s_add_u32 s26, s40, 0x40080
	v_lshl_add_u64 v[158:159], v[210:211], 0, s[84:85]
	s_addc_u32 s27, s41, 0
	s_add_i32 s13, s28, s51
	global_load_lds_dwordx4 v[158:159], off
	v_lshl_add_u64 v[158:159], s[26:27], 0, v[150:151]
	s_mov_b32 m0, s13
	s_nop 0
	global_load_lds_dwordx4 v[158:159], off
	v_lshl_add_u64 v[158:159], s[26:27], 0, v[146:147]
	s_add_i32 m0, s13, 0x2000
	s_nop 0
	global_load_lds_dwordx4 v[158:159], off
	v_lshl_add_u64 v[158:159], v[212:213], 0, s[84:85]
	s_mov_b32 m0, s59
	s_nop 0
	global_load_lds_dwordx4 v[158:159], off
	v_lshl_add_u64 v[158:159], v[214:215], 0, s[84:85]
	s_mov_b32 m0, s60
	s_nop 0
	global_load_lds_dwordx4 v[158:159], off
	s_waitcnt vmcnt(8)
	s_waitcnt lgkmcnt(0)
	s_barrier
	s_waitcnt lgkmcnt(0)
	v_mfma_f32_16x16x32_bf16 v[94:97], v[130:133], v[178:181], v[94:97]
	v_mfma_f32_16x16x32_bf16 v[90:93], v[138:141], v[178:181], v[90:93]
	v_mfma_f32_16x16x32_bf16 v[86:89], v[130:133], v[186:189], v[86:89]
	v_mfma_f32_16x16x32_bf16 v[82:85], v[138:141], v[186:189], v[82:85]
	v_mfma_f32_16x16x32_bf16 v[78:81], v[130:133], v[194:197], v[78:81]
	v_mfma_f32_16x16x32_bf16 v[74:77], v[138:141], v[194:197], v[74:77]
	v_mfma_f32_16x16x32_bf16 v[70:73], v[130:133], v[202:205], v[70:73]
	v_mfma_f32_16x16x32_bf16 v[66:69], v[138:141], v[202:205], v[66:69]
	v_mfma_f32_16x16x32_bf16 v[94:97], v[134:137], v[182:185], v[94:97]
	v_mfma_f32_16x16x32_bf16 v[90:93], v[142:145], v[182:185], v[90:93]
	v_mfma_f32_16x16x32_bf16 v[86:89], v[134:137], v[190:193], v[86:89]
	v_mfma_f32_16x16x32_bf16 v[82:85], v[142:145], v[190:193], v[82:85]
	v_mfma_f32_16x16x32_bf16 v[78:81], v[134:137], v[198:201], v[78:81]
	v_mfma_f32_16x16x32_bf16 v[74:77], v[142:145], v[198:201], v[74:77]
	v_mfma_f32_16x16x32_bf16 v[70:73], v[134:137], v[206:209], v[70:73]
	v_mfma_f32_16x16x32_bf16 v[66:69], v[142:145], v[206:209], v[66:69]
	v_mfma_f32_16x16x32_bf16 v[30:33], v[162:165], v[178:181], v[30:33]
	v_mfma_f32_16x16x32_bf16 v[26:29], v[170:173], v[178:181], v[26:29]
	v_mfma_f32_16x16x32_bf16 v[22:25], v[162:165], v[186:189], v[22:25]
	v_mfma_f32_16x16x32_bf16 v[18:21], v[170:173], v[186:189], v[18:21]
	v_mfma_f32_16x16x32_bf16 v[14:17], v[162:165], v[194:197], v[14:17]
	v_mfma_f32_16x16x32_bf16 v[10:13], v[170:173], v[194:197], v[10:13]
	v_mfma_f32_16x16x32_bf16 v[6:9], v[162:165], v[202:205], v[6:9]
	v_mfma_f32_16x16x32_bf16 v[2:5], v[170:173], v[202:205], v[2:5]
	v_mfma_f32_16x16x32_bf16 v[30:33], v[166:169], v[182:185], v[30:33]
	v_mfma_f32_16x16x32_bf16 v[26:29], v[174:177], v[182:185], v[26:29]
	v_mfma_f32_16x16x32_bf16 v[22:25], v[166:169], v[190:193], v[22:25]
	v_mfma_f32_16x16x32_bf16 v[18:21], v[174:177], v[190:193], v[18:21]
	v_mfma_f32_16x16x32_bf16 v[14:17], v[166:169], v[198:201], v[14:17]
	v_mfma_f32_16x16x32_bf16 v[10:13], v[174:177], v[198:201], v[10:13]
	v_mfma_f32_16x16x32_bf16 v[6:9], v[166:169], v[206:209], v[6:9]
	v_mfma_f32_16x16x32_bf16 v[2:5], v[174:177], v[206:209], v[2:5]
	s_barrier
	s_add_i32 s25, s25, 2
	s_add_u32 s10, s10, 0x100
	s_addc_u32 s11, s11, 0
	s_add_u32 s23, s23, 0x100
	s_addc_u32 s24, s24, 0
	s_cmp_gt_u32 s25, 13
	s_cbranch_scc0 .LBB0_173
	s_and_b64 vcc, exec, s[82:83]
	s_cbranch_vccz .LBB0_176
	s_barrier

.LBB0_271:
	s_add_u32 s13, s82, 0xfff00800
	s_addc_u32 s34, s83, -1
	s_add_i32 s35, 0, 0x10000
	s_cmp_eq_u32 s31, 60
	s_cselect_b32 s51, s9, s34
	s_cselect_b32 s50, s27, s13
	s_cselect_b32 s49, s7, s30
	s_cselect_b32 s48, s28, s29
	s_add_i32 s13, 0, 0x14000
	v_add_u32_e32 v126, s35, v242
	v_add_u32_e32 v158, s13, v242
	ds_read_b128 v[94:97], v126
	ds_read_b128 v[106:109], v126 offset:1024
	ds_read_b128 v[114:117], v126 offset:2048
	ds_read_b128 v[126:129], v126 offset:3072
	ds_read_b128 v[138:141], v158
	ds_read_b128 v[142:145], v158 offset:1024
	ds_read_b128 v[150:153], v158 offset:2048
	ds_read_b128 v[158:161], v158 offset:3072
	v_lshl_add_u64 v[204:205], s[82:83], 0, v[200:201]
	s_add_i32 m0, s20, 0xc000
	ds_read_b128 v[162:165], v243
	ds_read_b128 v[166:169], v243 offset:1024
	ds_read_b128 v[170:173], v243 offset:2048
	ds_read_b128 v[174:177], v243 offset:3072
	ds_read_b128 v[178:181], v243 offset:4096
	ds_read_b128 v[182:185], v243 offset:5120
	ds_read_b128 v[186:189], v243 offset:6144
	ds_read_b128 v[190:193], v243 offset:7168
	global_load_lds_dwordx4 v[204:205], off
	v_lshl_add_u64 v[204:205], s[82:83], 0, v[202:203]
	s_add_i32 m0, s20, 0xe000
	s_nop 0
	global_load_lds_dwordx4 v[204:205], off
	s_waitcnt vmcnt(8)
	s_waitcnt lgkmcnt(0)
	s_barrier
	s_waitcnt lgkmcnt(0)
	v_mfma_f32_16x16x32_bf16 v[154:157], v[94:97], v[162:165], v[154:157]
	v_mfma_f32_16x16x32_bf16 v[146:149], v[114:117], v[162:165], v[146:149]
	v_mfma_f32_16x16x32_bf16 v[122:125], v[94:97], v[170:173], v[122:125]
	v_mfma_f32_16x16x32_bf16 v[118:121], v[114:117], v[170:173], v[118:121]
	v_mfma_f32_16x16x32_bf16 v[98:101], v[94:97], v[178:181], v[98:101]
	v_mfma_f32_16x16x32_bf16 v[90:93], v[114:117], v[178:181], v[90:93]
	v_mfma_f32_16x16x32_bf16 v[78:81], v[94:97], v[186:189], v[78:81]
	v_mfma_f32_16x16x32_bf16 v[74:77], v[114:117], v[186:189], v[74:77]
	v_mfma_f32_16x16x32_bf16 v[154:157], v[106:109], v[166:169], v[154:157]
	v_mfma_f32_16x16x32_bf16 v[146:149], v[126:129], v[166:169], v[146:149]
	v_mfma_f32_16x16x32_bf16 v[122:125], v[106:109], v[174:177], v[122:125]
	v_mfma_f32_16x16x32_bf16 v[118:121], v[126:129], v[174:177], v[118:121]
	v_mfma_f32_16x16x32_bf16 v[98:101], v[106:109], v[182:185], v[98:101]
	v_mfma_f32_16x16x32_bf16 v[90:93], v[126:129], v[182:185], v[90:93]
	v_mfma_f32_16x16x32_bf16 v[78:81], v[106:109], v[190:193], v[78:81]
	v_mfma_f32_16x16x32_bf16 v[74:77], v[126:129], v[190:193], v[74:77]
	v_mfma_f32_16x16x32_bf16 v[134:137], v[138:141], v[162:165], v[134:137]
	v_mfma_f32_16x16x32_bf16 v[130:133], v[150:153], v[162:165], v[130:133]
	v_mfma_f32_16x16x32_bf16 v[110:113], v[138:141], v[170:173], v[110:113]
	v_mfma_f32_16x16x32_bf16 v[102:105], v[150:153], v[170:173], v[102:105]
	v_mfma_f32_16x16x32_bf16 v[86:89], v[138:141], v[178:181], v[86:89]
	v_mfma_f32_16x16x32_bf16 v[82:85], v[150:153], v[178:181], v[82:85]
	v_mfma_f32_16x16x32_bf16 v[70:73], v[138:141], v[186:189], v[70:73]
	v_mfma_f32_16x16x32_bf16 v[66:69], v[150:153], v[186:189], v[66:69]
	v_mfma_f32_16x16x32_bf16 v[134:137], v[142:145], v[166:169], v[134:137]
	v_mfma_f32_16x16x32_bf16 v[130:133], v[158:161], v[166:169], v[130:133]
	v_mfma_f32_16x16x32_bf16 v[110:113], v[142:145], v[174:177], v[110:113]
	v_mfma_f32_16x16x32_bf16 v[102:105], v[158:161], v[174:177], v[102:105]
	v_mfma_f32_16x16x32_bf16 v[86:89], v[142:145], v[182:185], v[86:89]
	v_mfma_f32_16x16x32_bf16 v[82:85], v[158:161], v[182:185], v[82:85]
	v_mfma_f32_16x16x32_bf16 v[70:73], v[142:145], v[190:193], v[70:73]
	v_mfma_f32_16x16x32_bf16 v[66:69], v[158:161], v[190:193], v[66:69]
	s_barrier
	s_add_i32 s34, s35, s54
	v_lshl_add_u64 v[204:205], s[48:49], 0, v[0:1]
	s_mov_b32 m0, s34
	ds_read_b128 v[162:165], v243 offset:16384
	ds_read_b128 v[166:169], v243 offset:17408
	ds_read_b128 v[170:173], v243 offset:18432
	ds_read_b128 v[174:177], v243 offset:19456
	ds_read_b128 v[178:181], v243 offset:20480
	ds_read_b128 v[182:185], v243 offset:21504
	ds_read_b128 v[186:189], v243 offset:22528
	ds_read_b128 v[190:193], v243 offset:23552
	global_load_lds_dwordx4 v[204:205], off
	s_add_i32 m0, s34, 0x2000
	s_add_u32 s34, s48, 0x100000
	v_lshl_add_u64 v[206:207], s[48:49], 0, v[194:195]
	s_addc_u32 s35, s49, 0
	s_add_i32 s13, s13, s54
	global_load_lds_dwordx4 v[206:207], off
	v_lshl_add_u64 v[208:209], s[34:35], 0, v[0:1]
	s_mov_b32 m0, s13
	v_lshl_add_u64 v[210:211], s[50:51], 0, v[196:197]
	global_load_lds_dwordx4 v[208:209], off
	v_lshl_add_u64 v[208:209], s[34:35], 0, v[194:195]
	s_add_i32 m0, s13, 0x2000
	s_nop 0
	global_load_lds_dwordx4 v[208:209], off
	v_lshl_add_u64 v[208:209], s[50:51], 0, v[198:199]
	s_mov_b32 m0, s20
	s_nop 0
	global_load_lds_dwordx4 v[208:209], off
	s_mov_b32 m0, s21
	s_nop 0
	global_load_lds_dwordx4 v[210:211], off
	s_waitcnt vmcnt(8)
	s_waitcnt lgkmcnt(0)
	s_barrier
	s_waitcnt lgkmcnt(0)
	v_mfma_f32_16x16x32_bf16 v[62:65], v[94:97], v[162:165], v[62:65]
	v_mfma_f32_16x16x32_bf16 v[58:61], v[114:117], v[162:165], v[58:61]
	v_mfma_f32_16x16x32_bf16 v[46:49], v[94:97], v[170:173], v[46:49]
	v_mfma_f32_16x16x32_bf16 v[42:45], v[114:117], v[170:173], v[42:45]
	v_mfma_f32_16x16x32_bf16 v[30:33], v[94:97], v[178:181], v[30:33]
	v_mfma_f32_16x16x32_bf16 v[26:29], v[114:117], v[178:181], v[26:29]
	v_mfma_f32_16x16x32_bf16 v[14:17], v[94:97], v[186:189], v[14:17]
	v_mfma_f32_16x16x32_bf16 v[10:13], v[114:117], v[186:189], v[10:13]
	v_mfma_f32_16x16x32_bf16 v[62:65], v[106:109], v[166:169], v[62:65]
	v_mfma_f32_16x16x32_bf16 v[58:61], v[126:129], v[166:169], v[58:61]
	v_mfma_f32_16x16x32_bf16 v[46:49], v[106:109], v[174:177], v[46:49]
	v_mfma_f32_16x16x32_bf16 v[42:45], v[126:129], v[174:177], v[42:45]
	v_mfma_f32_16x16x32_bf16 v[30:33], v[106:109], v[182:185], v[30:33]
	v_mfma_f32_16x16x32_bf16 v[26:29], v[126:129], v[182:185], v[26:29]
	v_mfma_f32_16x16x32_bf16 v[14:17], v[106:109], v[190:193], v[14:17]
	v_mfma_f32_16x16x32_bf16 v[10:13], v[126:129], v[190:193], v[10:13]
	v_mfma_f32_16x16x32_bf16 v[54:57], v[138:141], v[162:165], v[54:57]
	v_mfma_f32_16x16x32_bf16 v[50:53], v[150:153], v[162:165], v[50:53]
	v_mfma_f32_16x16x32_bf16 v[38:41], v[138:141], v[170:173], v[38:41]
	v_mfma_f32_16x16x32_bf16 v[34:37], v[150:153], v[170:173], v[34:37]
	v_mfma_f32_16x16x32_bf16 v[22:25], v[138:141], v[178:181], v[22:25]
	v_mfma_f32_16x16x32_bf16 v[18:21], v[150:153], v[178:181], v[18:21]
	v_mfma_f32_16x16x32_bf16 v[6:9], v[138:141], v[186:189], v[6:9]
	v_mfma_f32_16x16x32_bf16 v[2:5], v[150:153], v[186:189], v[2:5]
	v_mfma_f32_16x16x32_bf16 v[54:57], v[142:145], v[166:169], v[54:57]
	v_mfma_f32_16x16x32_bf16 v[50:53], v[158:161], v[166:169], v[50:53]
	v_mfma_f32_16x16x32_bf16 v[38:41], v[142:145], v[174:177], v[38:41]
	v_mfma_f32_16x16x32_bf16 v[34:37], v[158:161], v[174:177], v[34:37]
	v_mfma_f32_16x16x32_bf16 v[22:25], v[142:145], v[182:185], v[22:25]
	v_mfma_f32_16x16x32_bf16 v[18:21], v[158:161], v[182:185], v[18:21]
	v_mfma_f32_16x16x32_bf16 v[6:9], v[142:145], v[190:193], v[6:9]
	v_mfma_f32_16x16x32_bf16 v[2:5], v[158:161], v[190:193], v[2:5]
	s_barrier
	s_add_i32 s13, 0, 0x18000
	s_add_i32 s74, 0, 0x1c000
	v_add_u32_e32 v126, s13, v242
	v_add_u32_e32 v158, s74, v242
	ds_read_b128 v[94:97], v126
	ds_read_b128 v[106:109], v126 offset:1024
	ds_read_b128 v[114:117], v126 offset:2048
	ds_read_b128 v[126:129], v126 offset:3072
	ds_read_b128 v[138:141], v158
	ds_read_b128 v[142:145], v158 offset:1024
	ds_read_b128 v[150:153], v158 offset:2048
	ds_read_b128 v[158:161], v158 offset:3072
	s_add_u32 s34, s50, 0x100000
	s_addc_u32 s35, s51, 0
	s_mov_b32 m0, s22
	v_lshl_add_u64 v[212:213], s[34:35], 0, v[198:199]
	ds_read_b128 v[162:165], v243 offset:32768
	ds_read_b128 v[166:169], v243 offset:33792
	ds_read_b128 v[170:173], v243 offset:34816
	ds_read_b128 v[174:177], v243 offset:35840
	ds_read_b128 v[178:181], v243 offset:36864
	ds_read_b128 v[182:185], v243 offset:37888
	ds_read_b128 v[186:189], v243 offset:38912
	ds_read_b128 v[190:193], v243 offset:39936
	global_load_lds_dwordx4 v[212:213], off
	v_lshl_add_u64 v[212:213], s[34:35], 0, v[196:197]
	s_mov_b32 m0, s23
	s_nop 0
	global_load_lds_dwordx4 v[212:213], off
	s_waitcnt vmcnt(8)
	s_waitcnt lgkmcnt(0)
	s_barrier
	s_waitcnt lgkmcnt(0)
	v_mfma_f32_16x16x32_bf16 v[154:157], v[94:97], v[162:165], v[154:157]
	v_mfma_f32_16x16x32_bf16 v[146:149], v[114:117], v[162:165], v[146:149]
	v_mfma_f32_16x16x32_bf16 v[122:125], v[94:97], v[170:173], v[122:125]
	v_mfma_f32_16x16x32_bf16 v[118:121], v[114:117], v[170:173], v[118:121]
	v_mfma_f32_16x16x32_bf16 v[98:101], v[94:97], v[178:181], v[98:101]
	v_mfma_f32_16x16x32_bf16 v[90:93], v[114:117], v[178:181], v[90:93]
	v_mfma_f32_16x16x32_bf16 v[78:81], v[94:97], v[186:189], v[78:81]
	v_mfma_f32_16x16x32_bf16 v[74:77], v[114:117], v[186:189], v[74:77]
	v_mfma_f32_16x16x32_bf16 v[154:157], v[106:109], v[166:169], v[154:157]
	v_mfma_f32_16x16x32_bf16 v[146:149], v[126:129], v[166:169], v[146:149]
	v_mfma_f32_16x16x32_bf16 v[122:125], v[106:109], v[174:177], v[122:125]
	v_mfma_f32_16x16x32_bf16 v[118:121], v[126:129], v[174:177], v[118:121]
	v_mfma_f32_16x16x32_bf16 v[98:101], v[106:109], v[182:185], v[98:101]
	v_mfma_f32_16x16x32_bf16 v[90:93], v[126:129], v[182:185], v[90:93]
	v_mfma_f32_16x16x32_bf16 v[78:81], v[106:109], v[190:193], v[78:81]
	v_mfma_f32_16x16x32_bf16 v[74:77], v[126:129], v[190:193], v[74:77]
	v_mfma_f32_16x16x32_bf16 v[134:137], v[138:141], v[162:165], v[134:137]
	v_mfma_f32_16x16x32_bf16 v[130:133], v[150:153], v[162:165], v[130:133]
	v_mfma_f32_16x16x32_bf16 v[110:113], v[138:141], v[170:173], v[110:113]
	v_mfma_f32_16x16x32_bf16 v[102:105], v[150:153], v[170:173], v[102:105]
	v_mfma_f32_16x16x32_bf16 v[86:89], v[138:141], v[178:181], v[86:89]
	v_mfma_f32_16x16x32_bf16 v[82:85], v[150:153], v[178:181], v[82:85]
	v_mfma_f32_16x16x32_bf16 v[70:73], v[138:141], v[186:189], v[70:73]
	v_mfma_f32_16x16x32_bf16 v[66:69], v[150:153], v[186:189], v[66:69]
	v_mfma_f32_16x16x32_bf16 v[134:137], v[142:145], v[166:169], v[134:137]
	v_mfma_f32_16x16x32_bf16 v[130:133], v[158:161], v[166:169], v[130:133]
	v_mfma_f32_16x16x32_bf16 v[110:113], v[142:145], v[174:177], v[110:113]
	v_mfma_f32_16x16x32_bf16 v[102:105], v[158:161], v[174:177], v[102:105]
	v_mfma_f32_16x16x32_bf16 v[86:89], v[142:145], v[182:185], v[86:89]
	v_mfma_f32_16x16x32_bf16 v[82:85], v[158:161], v[182:185], v[82:85]
	v_mfma_f32_16x16x32_bf16 v[70:73], v[142:145], v[190:193], v[70:73]
	v_mfma_f32_16x16x32_bf16 v[66:69], v[158:161], v[190:193], v[66:69]
	s_barrier
	s_add_i32 s13, s13, s54
	v_lshl_add_u64 v[204:205], v[204:205], 0, s[84:85]
	s_mov_b32 m0, s13
	ds_read_b128 v[162:165], v243 offset:49152
	ds_read_b128 v[166:169], v243 offset:50176
	ds_read_b128 v[170:173], v243 offset:51200
	ds_read_b128 v[174:177], v243 offset:52224
	ds_read_b128 v[178:181], v243 offset:53248
	ds_read_b128 v[182:185], v243 offset:54272
	ds_read_b128 v[186:189], v243 offset:55296
	ds_read_b128 v[190:193], v243 offset:56320
	global_load_lds_dwordx4 v[204:205], off
	s_add_i32 m0, s13, 0x2000
	s_add_u32 s34, s48, 0x100080
	v_lshl_add_u64 v[204:205], v[206:207], 0, s[84:85]
	s_addc_u32 s35, s49, 0
	s_add_i32 s13, s74, s54
	global_load_lds_dwordx4 v[204:205], off
	v_lshl_add_u64 v[204:205], s[34:35], 0, v[0:1]
	s_mov_b32 m0, s13
	s_nop 0
	global_load_lds_dwordx4 v[204:205], off
	v_lshl_add_u64 v[204:205], s[34:35], 0, v[194:195]
	s_add_i32 m0, s13, 0x2000
	s_nop 0
	global_load_lds_dwordx4 v[204:205], off
	v_lshl_add_u64 v[204:205], v[208:209], 0, s[16:17]
	s_mov_b32 m0, s60
	s_nop 0
	global_load_lds_dwordx4 v[204:205], off
	v_lshl_add_u64 v[204:205], v[210:211], 0, s[16:17]
	s_mov_b32 m0, s61
	s_nop 0
	global_load_lds_dwordx4 v[204:205], off
	s_waitcnt vmcnt(8)
	s_waitcnt lgkmcnt(0)
	s_barrier
	s_waitcnt lgkmcnt(0)
	v_mfma_f32_16x16x32_bf16 v[62:65], v[94:97], v[162:165], v[62:65]
	v_mfma_f32_16x16x32_bf16 v[58:61], v[114:117], v[162:165], v[58:61]
	v_mfma_f32_16x16x32_bf16 v[46:49], v[94:97], v[170:173], v[46:49]
	v_mfma_f32_16x16x32_bf16 v[42:45], v[114:117], v[170:173], v[42:45]
	v_mfma_f32_16x16x32_bf16 v[30:33], v[94:97], v[178:181], v[30:33]
	v_mfma_f32_16x16x32_bf16 v[26:29], v[114:117], v[178:181], v[26:29]
	v_mfma_f32_16x16x32_bf16 v[14:17], v[94:97], v[186:189], v[14:17]
	v_mfma_f32_16x16x32_bf16 v[10:13], v[114:117], v[186:189], v[10:13]
	v_mfma_f32_16x16x32_bf16 v[62:65], v[106:109], v[166:169], v[62:65]
	v_mfma_f32_16x16x32_bf16 v[58:61], v[126:129], v[166:169], v[58:61]
	v_mfma_f32_16x16x32_bf16 v[46:49], v[106:109], v[174:177], v[46:49]
	v_mfma_f32_16x16x32_bf16 v[42:45], v[126:129], v[174:177], v[42:45]
	v_mfma_f32_16x16x32_bf16 v[30:33], v[106:109], v[182:185], v[30:33]
	v_mfma_f32_16x16x32_bf16 v[26:29], v[126:129], v[182:185], v[26:29]
	v_mfma_f32_16x16x32_bf16 v[14:17], v[106:109], v[190:193], v[14:17]
	v_mfma_f32_16x16x32_bf16 v[10:13], v[126:129], v[190:193], v[10:13]
	v_mfma_f32_16x16x32_bf16 v[54:57], v[138:141], v[162:165], v[54:57]
	v_mfma_f32_16x16x32_bf16 v[50:53], v[150:153], v[162:165], v[50:53]
	v_mfma_f32_16x16x32_bf16 v[38:41], v[138:141], v[170:173], v[38:41]
	v_mfma_f32_16x16x32_bf16 v[34:37], v[150:153], v[170:173], v[34:37]
	v_mfma_f32_16x16x32_bf16 v[22:25], v[138:141], v[178:181], v[22:25]
	v_mfma_f32_16x16x32_bf16 v[18:21], v[150:153], v[178:181], v[18:21]
	v_mfma_f32_16x16x32_bf16 v[6:9], v[138:141], v[186:189], v[6:9]
	v_mfma_f32_16x16x32_bf16 v[2:5], v[150:153], v[186:189], v[2:5]
	v_mfma_f32_16x16x32_bf16 v[54:57], v[142:145], v[166:169], v[54:57]
	v_mfma_f32_16x16x32_bf16 v[50:53], v[158:161], v[166:169], v[50:53]
	v_mfma_f32_16x16x32_bf16 v[38:41], v[142:145], v[174:177], v[38:41]
	v_mfma_f32_16x16x32_bf16 v[34:37], v[158:161], v[174:177], v[34:37]
	v_mfma_f32_16x16x32_bf16 v[22:25], v[142:145], v[182:185], v[22:25]
	v_mfma_f32_16x16x32_bf16 v[18:21], v[158:161], v[182:185], v[18:21]
	v_mfma_f32_16x16x32_bf16 v[6:9], v[142:145], v[190:193], v[6:9]
	v_mfma_f32_16x16x32_bf16 v[2:5], v[158:161], v[190:193], v[2:5]
	s_barrier
	s_add_i32 s31, s31, 2
	s_add_u32 s29, s29, 0x100
	s_addc_u32 s30, s30, 0
	s_add_u32 s82, s82, 0x1000
	s_addc_u32 s83, s83, 0
	s_cmp_gt_u32 s31, 61
	s_cbranch_scc0 .LBB0_271
	s_and_b64 vcc, exec, s[4:5]
	s_cbranch_vccz .LBB0_274
	s_barrier

.LBB0_308:
	s_add_u32 s13, s44, s35
	s_addc_u32 s58, s45, 0
	s_add_u32 s52, s13, 0x100
	s_addc_u32 s53, s58, 0
	s_and_b64 s[50:51], s[48:49], exec
	s_cselect_b32 s53, s9, s53
	s_cselect_b32 s52, s31, s52
	s_add_u32 s35, s42, s35
	s_addc_u32 s50, s43, 0
	s_add_u32 s35, s35, 0x100
	s_addc_u32 s50, s50, 0
	s_add_i32 s74, 0, 0x10000
	s_and_b64 s[48:49], s[48:49], exec
	s_cselect_b32 s55, s7, s50
	s_cselect_b32 s54, s34, s35
	s_add_i32 s49, 0, 0x14000
	s_add_u32 s60, s13, 0x10080
	s_addc_u32 s61, s58, 0
	s_add_i32 s92, s74, s20
	s_add_i32 m0, s21, 0xc000
	s_add_i32 s75, s21, 0xe000
	s_add_i32 s80, s92, 0x2000
	s_add_u32 s58, s54, 0x10000
	v_add_u32_e32 v150, s74, v136
	v_add_u32_e32 v166, s49, v136
	s_addc_u32 s59, s55, 0
	s_add_i32 s93, s49, s20
	ds_read_b128 v[138:141], v150
	ds_read_b128 v[142:145], v150 offset:1024
	ds_read_b128 v[146:149], v150 offset:2048
	ds_read_b128 v[150:153], v150 offset:3072
	ds_read_b128 v[154:157], v166
	ds_read_b128 v[158:161], v166 offset:1024
	ds_read_b128 v[162:165], v166 offset:2048
	ds_read_b128 v[166:169], v166 offset:3072
	s_add_i32 s13, s93, 0x2000
	s_add_i32 vcc_lo, 0, 0x18000
	s_add_i32 vcc_hi, 0, 0x1c000
	s_add_u32 s50, s52, 0x10000
	s_addc_u32 s51, s53, 0
	s_add_i32 s35, vcc_lo, s20
	s_add_i32 s97, s35, 0x2000
	s_add_u32 s48, s54, 0x10080
	s_addc_u32 s49, s55, 0
	s_add_i32 s81, vcc_hi, s20
	s_add_i32 s74, s81, 0x2000
	v_lshl_add_u64 v[202:203], s[60:61], 0, v[134:135]
	ds_read_b128 v[170:173], v137
	ds_read_b128 v[174:177], v137 offset:1024
	ds_read_b128 v[178:181], v137 offset:2048
	ds_read_b128 v[182:185], v137 offset:3072
	ds_read_b128 v[186:189], v137 offset:4096
	ds_read_b128 v[190:193], v137 offset:5120
	ds_read_b128 v[194:197], v137 offset:6144
	ds_read_b128 v[198:201], v137 offset:7168
	global_load_lds_dwordx4 v[202:203], off
	v_lshl_add_u64 v[202:203], s[60:61], 0, v[132:133]
	s_mov_b32 m0, s75
	s_nop 0
	global_load_lds_dwordx4 v[202:203], off
	s_waitcnt vmcnt(8)
	s_waitcnt lgkmcnt(0)
	s_barrier
	s_waitcnt lgkmcnt(0)
	v_mfma_f32_16x16x32_bf16 v[126:129], v[138:141], v[170:173], v[126:129]
	v_mfma_f32_16x16x32_bf16 v[122:125], v[146:149], v[170:173], v[122:125]
	v_mfma_f32_16x16x32_bf16 v[118:121], v[138:141], v[178:181], v[118:121]
	v_mfma_f32_16x16x32_bf16 v[114:117], v[146:149], v[178:181], v[114:117]
	v_mfma_f32_16x16x32_bf16 v[102:105], v[138:141], v[186:189], v[102:105]
	v_mfma_f32_16x16x32_bf16 v[98:101], v[146:149], v[186:189], v[98:101]
	v_mfma_f32_16x16x32_bf16 v[86:89], v[138:141], v[194:197], v[86:89]
	v_mfma_f32_16x16x32_bf16 v[82:85], v[146:149], v[194:197], v[82:85]
	v_mfma_f32_16x16x32_bf16 v[126:129], v[142:145], v[174:177], v[126:129]
	v_mfma_f32_16x16x32_bf16 v[122:125], v[150:153], v[174:177], v[122:125]
	v_mfma_f32_16x16x32_bf16 v[118:121], v[142:145], v[182:185], v[118:121]
	v_mfma_f32_16x16x32_bf16 v[114:117], v[150:153], v[182:185], v[114:117]
	v_mfma_f32_16x16x32_bf16 v[102:105], v[142:145], v[190:193], v[102:105]
	v_mfma_f32_16x16x32_bf16 v[98:101], v[150:153], v[190:193], v[98:101]
	v_mfma_f32_16x16x32_bf16 v[86:89], v[142:145], v[198:201], v[86:89]
	v_mfma_f32_16x16x32_bf16 v[82:85], v[150:153], v[198:201], v[82:85]
	v_mfma_f32_16x16x32_bf16 v[110:113], v[154:157], v[170:173], v[110:113]
	v_mfma_f32_16x16x32_bf16 v[106:109], v[162:165], v[170:173], v[106:109]
	v_mfma_f32_16x16x32_bf16 v[94:97], v[154:157], v[178:181], v[94:97]
	v_mfma_f32_16x16x32_bf16 v[90:93], v[162:165], v[178:181], v[90:93]
	v_mfma_f32_16x16x32_bf16 v[78:81], v[154:157], v[186:189], v[78:81]
	v_mfma_f32_16x16x32_bf16 v[74:77], v[162:165], v[186:189], v[74:77]
	v_mfma_f32_16x16x32_bf16 v[70:73], v[154:157], v[194:197], v[70:73]
	v_mfma_f32_16x16x32_bf16 v[66:69], v[162:165], v[194:197], v[66:69]
	v_mfma_f32_16x16x32_bf16 v[110:113], v[158:161], v[174:177], v[110:113]
	v_mfma_f32_16x16x32_bf16 v[106:109], v[166:169], v[174:177], v[106:109]
	v_mfma_f32_16x16x32_bf16 v[94:97], v[158:161], v[182:185], v[94:97]
	v_mfma_f32_16x16x32_bf16 v[90:93], v[166:169], v[182:185], v[90:93]
	v_mfma_f32_16x16x32_bf16 v[78:81], v[158:161], v[190:193], v[78:81]
	v_mfma_f32_16x16x32_bf16 v[74:77], v[166:169], v[190:193], v[74:77]
	v_mfma_f32_16x16x32_bf16 v[70:73], v[158:161], v[198:201], v[70:73]
	v_mfma_f32_16x16x32_bf16 v[66:69], v[166:169], v[198:201], v[66:69]
	s_barrier
	s_mov_b32 m0, s92
	v_lshl_add_u64 v[202:203], s[54:55], 0, v[0:1]
	ds_read_b128 v[170:173], v137 offset:16384
	ds_read_b128 v[174:177], v137 offset:17408
	ds_read_b128 v[178:181], v137 offset:18432
	ds_read_b128 v[182:185], v137 offset:19456
	ds_read_b128 v[186:189], v137 offset:20480
	ds_read_b128 v[190:193], v137 offset:21504
	ds_read_b128 v[194:197], v137 offset:22528
	ds_read_b128 v[198:201], v137 offset:23552
	global_load_lds_dwordx4 v[202:203], off
	v_lshl_add_u64 v[204:205], s[54:55], 0, v[130:131]
	s_mov_b32 m0, s80
	v_lshl_add_u64 v[206:207], s[58:59], 0, v[0:1]
	global_load_lds_dwordx4 v[204:205], off
	s_mov_b32 m0, s93
	v_lshl_add_u64 v[208:209], s[52:53], 0, v[132:133]
	global_load_lds_dwordx4 v[206:207], off
	v_lshl_add_u64 v[206:207], s[58:59], 0, v[130:131]
	s_mov_b32 m0, s13
	s_nop 0
	global_load_lds_dwordx4 v[206:207], off
	v_lshl_add_u64 v[206:207], s[52:53], 0, v[134:135]
	s_mov_b32 m0, s21
	s_nop 0
	global_load_lds_dwordx4 v[206:207], off
	s_mov_b32 m0, s22
	s_nop 0
	global_load_lds_dwordx4 v[208:209], off
	s_waitcnt vmcnt(8)
	s_waitcnt lgkmcnt(0)
	s_barrier
	s_waitcnt lgkmcnt(0)
	v_mfma_f32_16x16x32_bf16 v[62:65], v[138:141], v[170:173], v[62:65]
	v_mfma_f32_16x16x32_bf16 v[58:61], v[146:149], v[170:173], v[58:61]
	v_mfma_f32_16x16x32_bf16 v[54:57], v[138:141], v[178:181], v[54:57]
	v_mfma_f32_16x16x32_bf16 v[50:53], v[146:149], v[178:181], v[50:53]
	v_mfma_f32_16x16x32_bf16 v[38:41], v[138:141], v[186:189], v[38:41]
	v_mfma_f32_16x16x32_bf16 v[34:37], v[146:149], v[186:189], v[34:37]
	v_mfma_f32_16x16x32_bf16 v[22:25], v[138:141], v[194:197], v[22:25]
	v_mfma_f32_16x16x32_bf16 v[18:21], v[146:149], v[194:197], v[18:21]
	v_mfma_f32_16x16x32_bf16 v[62:65], v[142:145], v[174:177], v[62:65]
	v_mfma_f32_16x16x32_bf16 v[58:61], v[150:153], v[174:177], v[58:61]
	v_mfma_f32_16x16x32_bf16 v[54:57], v[142:145], v[182:185], v[54:57]
	v_mfma_f32_16x16x32_bf16 v[50:53], v[150:153], v[182:185], v[50:53]
	v_mfma_f32_16x16x32_bf16 v[38:41], v[142:145], v[190:193], v[38:41]
	v_mfma_f32_16x16x32_bf16 v[34:37], v[150:153], v[190:193], v[34:37]
	v_mfma_f32_16x16x32_bf16 v[22:25], v[142:145], v[198:201], v[22:25]
	v_mfma_f32_16x16x32_bf16 v[18:21], v[150:153], v[198:201], v[18:21]
	v_mfma_f32_16x16x32_bf16 v[46:49], v[154:157], v[170:173], v[46:49]
	v_mfma_f32_16x16x32_bf16 v[42:45], v[162:165], v[170:173], v[42:45]
	v_mfma_f32_16x16x32_bf16 v[30:33], v[154:157], v[178:181], v[30:33]
	v_mfma_f32_16x16x32_bf16 v[26:29], v[162:165], v[178:181], v[26:29]
	v_mfma_f32_16x16x32_bf16 v[14:17], v[154:157], v[186:189], v[14:17]
	v_mfma_f32_16x16x32_bf16 v[10:13], v[162:165], v[186:189], v[10:13]
	v_mfma_f32_16x16x32_bf16 v[6:9], v[154:157], v[194:197], v[6:9]
	v_mfma_f32_16x16x32_bf16 v[2:5], v[162:165], v[194:197], v[2:5]
	v_mfma_f32_16x16x32_bf16 v[46:49], v[158:161], v[174:177], v[46:49]
	v_mfma_f32_16x16x32_bf16 v[42:45], v[166:169], v[174:177], v[42:45]
	v_mfma_f32_16x16x32_bf16 v[30:33], v[158:161], v[182:185], v[30:33]
	v_mfma_f32_16x16x32_bf16 v[26:29], v[166:169], v[182:185], v[26:29]
	v_mfma_f32_16x16x32_bf16 v[14:17], v[158:161], v[190:193], v[14:17]
	v_mfma_f32_16x16x32_bf16 v[10:13], v[166:169], v[190:193], v[10:13]
	v_mfma_f32_16x16x32_bf16 v[6:9], v[158:161], v[198:201], v[6:9]
	v_mfma_f32_16x16x32_bf16 v[2:5], v[166:169], v[198:201], v[2:5]
	s_barrier
	v_add_u32_e32 v150, vcc_lo, v136
	v_add_u32_e32 v166, vcc_hi, v136
	ds_read_b128 v[138:141], v150
	ds_read_b128 v[142:145], v150 offset:1024
	ds_read_b128 v[146:149], v150 offset:2048
	ds_read_b128 v[150:153], v150 offset:3072
	ds_read_b128 v[154:157], v166
	ds_read_b128 v[158:161], v166 offset:1024
	ds_read_b128 v[162:165], v166 offset:2048
	ds_read_b128 v[166:169], v166 offset:3072
	s_mov_b32 m0, s23
	v_lshl_add_u64 v[210:211], s[50:51], 0, v[134:135]
	ds_read_b128 v[170:173], v137 offset:32768
	ds_read_b128 v[174:177], v137 offset:33792
	ds_read_b128 v[178:181], v137 offset:34816
	ds_read_b128 v[182:185], v137 offset:35840
	ds_read_b128 v[186:189], v137 offset:36864
	ds_read_b128 v[190:193], v137 offset:37888
	ds_read_b128 v[194:197], v137 offset:38912
	ds_read_b128 v[198:201], v137 offset:39936
	global_load_lds_dwordx4 v[210:211], off
	v_lshl_add_u64 v[210:211], s[50:51], 0, v[132:133]
	s_mov_b32 m0, s24
	s_nop 0
	global_load_lds_dwordx4 v[210:211], off
	s_waitcnt vmcnt(8)
	s_waitcnt lgkmcnt(0)
	s_barrier
	s_waitcnt lgkmcnt(0)
	v_mfma_f32_16x16x32_bf16 v[126:129], v[138:141], v[170:173], v[126:129]
	v_mfma_f32_16x16x32_bf16 v[122:125], v[146:149], v[170:173], v[122:125]
	v_mfma_f32_16x16x32_bf16 v[118:121], v[138:141], v[178:181], v[118:121]
	v_mfma_f32_16x16x32_bf16 v[114:117], v[146:149], v[178:181], v[114:117]
	v_mfma_f32_16x16x32_bf16 v[102:105], v[138:141], v[186:189], v[102:105]
	v_mfma_f32_16x16x32_bf16 v[98:101], v[146:149], v[186:189], v[98:101]
	v_mfma_f32_16x16x32_bf16 v[86:89], v[138:141], v[194:197], v[86:89]
	v_mfma_f32_16x16x32_bf16 v[82:85], v[146:149], v[194:197], v[82:85]
	v_mfma_f32_16x16x32_bf16 v[126:129], v[142:145], v[174:177], v[126:129]
	v_mfma_f32_16x16x32_bf16 v[122:125], v[150:153], v[174:177], v[122:125]
	v_mfma_f32_16x16x32_bf16 v[118:121], v[142:145], v[182:185], v[118:121]
	v_mfma_f32_16x16x32_bf16 v[114:117], v[150:153], v[182:185], v[114:117]
	v_mfma_f32_16x16x32_bf16 v[102:105], v[142:145], v[190:193], v[102:105]
	v_mfma_f32_16x16x32_bf16 v[98:101], v[150:153], v[190:193], v[98:101]
	v_mfma_f32_16x16x32_bf16 v[86:89], v[142:145], v[198:201], v[86:89]
	v_mfma_f32_16x16x32_bf16 v[82:85], v[150:153], v[198:201], v[82:85]
	v_mfma_f32_16x16x32_bf16 v[110:113], v[154:157], v[170:173], v[110:113]
	v_mfma_f32_16x16x32_bf16 v[106:109], v[162:165], v[170:173], v[106:109]
	v_mfma_f32_16x16x32_bf16 v[94:97], v[154:157], v[178:181], v[94:97]
	v_mfma_f32_16x16x32_bf16 v[90:93], v[162:165], v[178:181], v[90:93]
	v_mfma_f32_16x16x32_bf16 v[78:81], v[154:157], v[186:189], v[78:81]
	v_mfma_f32_16x16x32_bf16 v[74:77], v[162:165], v[186:189], v[74:77]
	v_mfma_f32_16x16x32_bf16 v[70:73], v[154:157], v[194:197], v[70:73]
	v_mfma_f32_16x16x32_bf16 v[66:69], v[162:165], v[194:197], v[66:69]
	v_mfma_f32_16x16x32_bf16 v[110:113], v[158:161], v[174:177], v[110:113]
	v_mfma_f32_16x16x32_bf16 v[106:109], v[166:169], v[174:177], v[106:109]
	v_mfma_f32_16x16x32_bf16 v[94:97], v[158:161], v[182:185], v[94:97]
	v_mfma_f32_16x16x32_bf16 v[90:93], v[166:169], v[182:185], v[90:93]
	v_mfma_f32_16x16x32_bf16 v[78:81], v[158:161], v[190:193], v[78:81]
	v_mfma_f32_16x16x32_bf16 v[74:77], v[166:169], v[190:193], v[74:77]
	v_mfma_f32_16x16x32_bf16 v[70:73], v[158:161], v[198:201], v[70:73]
	v_mfma_f32_16x16x32_bf16 v[66:69], v[166:169], v[198:201], v[66:69]
	s_barrier
	s_mov_b32 m0, s35
	v_lshl_add_u64 v[202:203], v[202:203], 0, s[84:85]
	ds_read_b128 v[170:173], v137 offset:49152
	ds_read_b128 v[174:177], v137 offset:50176
	ds_read_b128 v[178:181], v137 offset:51200
	ds_read_b128 v[182:185], v137 offset:52224
	ds_read_b128 v[186:189], v137 offset:53248
	ds_read_b128 v[190:193], v137 offset:54272
	ds_read_b128 v[194:197], v137 offset:55296
	ds_read_b128 v[198:201], v137 offset:56320
	global_load_lds_dwordx4 v[202:203], off
	v_lshl_add_u64 v[202:203], v[204:205], 0, s[84:85]
	s_mov_b32 m0, s97
	s_nop 0
	global_load_lds_dwordx4 v[202:203], off
	v_lshl_add_u64 v[202:203], s[48:49], 0, v[0:1]
	s_mov_b32 m0, s81
	s_nop 0
	global_load_lds_dwordx4 v[202:203], off
	v_lshl_add_u64 v[202:203], s[48:49], 0, v[130:131]
	s_mov_b32 m0, s74
	s_nop 0
	global_load_lds_dwordx4 v[202:203], off
	v_lshl_add_u64 v[202:203], v[206:207], 0, s[84:85]
	s_mov_b32 m0, s26
	s_nop 0
	global_load_lds_dwordx4 v[202:203], off
	v_lshl_add_u64 v[202:203], v[208:209], 0, s[84:85]
	s_mov_b32 m0, s27
	s_nop 0
	global_load_lds_dwordx4 v[202:203], off
	s_waitcnt vmcnt(8)
	s_waitcnt lgkmcnt(0)
	s_barrier
	s_waitcnt lgkmcnt(0)
	v_mfma_f32_16x16x32_bf16 v[62:65], v[138:141], v[170:173], v[62:65]
	v_mfma_f32_16x16x32_bf16 v[58:61], v[146:149], v[170:173], v[58:61]
	v_mfma_f32_16x16x32_bf16 v[54:57], v[138:141], v[178:181], v[54:57]
	v_mfma_f32_16x16x32_bf16 v[50:53], v[146:149], v[178:181], v[50:53]
	v_mfma_f32_16x16x32_bf16 v[38:41], v[138:141], v[186:189], v[38:41]
	v_mfma_f32_16x16x32_bf16 v[34:37], v[146:149], v[186:189], v[34:37]
	v_mfma_f32_16x16x32_bf16 v[22:25], v[138:141], v[194:197], v[22:25]
	v_mfma_f32_16x16x32_bf16 v[18:21], v[146:149], v[194:197], v[18:21]
	v_mfma_f32_16x16x32_bf16 v[62:65], v[142:145], v[174:177], v[62:65]
	v_mfma_f32_16x16x32_bf16 v[58:61], v[150:153], v[174:177], v[58:61]
	v_mfma_f32_16x16x32_bf16 v[54:57], v[142:145], v[182:185], v[54:57]
	v_mfma_f32_16x16x32_bf16 v[50:53], v[150:153], v[182:185], v[50:53]
	v_mfma_f32_16x16x32_bf16 v[38:41], v[142:145], v[190:193], v[38:41]
	v_mfma_f32_16x16x32_bf16 v[34:37], v[150:153], v[190:193], v[34:37]
	v_mfma_f32_16x16x32_bf16 v[22:25], v[142:145], v[198:201], v[22:25]
	v_mfma_f32_16x16x32_bf16 v[18:21], v[150:153], v[198:201], v[18:21]
	v_mfma_f32_16x16x32_bf16 v[46:49], v[154:157], v[170:173], v[46:49]
	v_mfma_f32_16x16x32_bf16 v[42:45], v[162:165], v[170:173], v[42:45]
	v_mfma_f32_16x16x32_bf16 v[30:33], v[154:157], v[178:181], v[30:33]
	v_mfma_f32_16x16x32_bf16 v[26:29], v[162:165], v[178:181], v[26:29]
	v_mfma_f32_16x16x32_bf16 v[14:17], v[154:157], v[186:189], v[14:17]
	v_mfma_f32_16x16x32_bf16 v[10:13], v[162:165], v[186:189], v[10:13]
	v_mfma_f32_16x16x32_bf16 v[6:9], v[154:157], v[194:197], v[6:9]
	v_mfma_f32_16x16x32_bf16 v[2:5], v[162:165], v[194:197], v[2:5]
	v_mfma_f32_16x16x32_bf16 v[46:49], v[158:161], v[174:177], v[46:49]
	v_mfma_f32_16x16x32_bf16 v[42:45], v[166:169], v[174:177], v[42:45]
	v_mfma_f32_16x16x32_bf16 v[30:33], v[158:161], v[182:185], v[30:33]
	v_mfma_f32_16x16x32_bf16 v[26:29], v[166:169], v[182:185], v[26:29]
	v_mfma_f32_16x16x32_bf16 v[14:17], v[158:161], v[190:193], v[14:17]
	v_mfma_f32_16x16x32_bf16 v[10:13], v[166:169], v[190:193], v[10:13]
	v_mfma_f32_16x16x32_bf16 v[6:9], v[158:161], v[198:201], v[6:9]
	v_mfma_f32_16x16x32_bf16 v[2:5], v[166:169], v[198:201], v[2:5]
	s_barrier
	s_movk_i32 s35, 0x100
	s_andn2_b64 vcc, exec, s[82:83]
	s_mov_b64 s[48:49], -1
	s_mov_b64 s[82:83], 0
	s_cbranch_vccz .LBB0_308
	s_and_b64 vcc, exec, s[4:5]
	s_cbranch_vccz .LBB0_311
	s_barrier

.LBB0_408:
	s_add_u32 s13, s44, 0xfffc0080
	s_addc_u32 s34, s45, -1
	s_add_i32 s35, 0, 0x10000
	s_cmp_eq_u32 s31, 12
	s_cselect_b32 s51, s11, s34
	s_cselect_b32 s50, s27, s13
	v_add_u32_e32 v0, s35, v158
	s_cselect_b32 s49, s9, s30
	s_cselect_b32 s48, s28, s29
	s_add_i32 s13, 0, 0x14000
	ds_read_b128 v[130:133], v0
	ds_read_b128 v[134:137], v0 offset:1024
	ds_read_b128 v[138:141], v0 offset:2048
	ds_read_b128 v[154:157], v0 offset:3072
	v_add_u32_e32 v0, s13, v158
	ds_read_b128 v[160:163], v0
	ds_read_b128 v[164:167], v0 offset:1024
	ds_read_b128 v[168:171], v0 offset:2048
	ds_read_b128 v[172:175], v0 offset:3072
	v_lshl_add_u64 v[208:209], s[44:45], 0, v[150:151]
	s_add_i32 m0, s22, 0xc000
	ds_read_b128 v[176:179], v159
	ds_read_b128 v[180:183], v159 offset:1024
	ds_read_b128 v[184:187], v159 offset:2048
	ds_read_b128 v[188:191], v159 offset:3072
	ds_read_b128 v[192:195], v159 offset:4096
	ds_read_b128 v[196:199], v159 offset:5120
	ds_read_b128 v[200:203], v159 offset:6144
	ds_read_b128 v[204:207], v159 offset:7168
	global_load_lds_dwordx4 v[208:209], off
	v_lshl_add_u64 v[208:209], s[44:45], 0, v[152:153]
	s_add_i32 m0, s22, 0xe000
	s_nop 0
	global_load_lds_dwordx4 v[208:209], off
	s_waitcnt vmcnt(8)
	s_waitcnt lgkmcnt(0)
	s_barrier
	s_waitcnt lgkmcnt(0)
	v_mfma_f32_16x16x32_bf16 v[126:129], v[130:133], v[176:179], v[126:129]
	v_mfma_f32_16x16x32_bf16 v[122:125], v[138:141], v[176:179], v[122:125]
	v_mfma_f32_16x16x32_bf16 v[114:117], v[130:133], v[184:187], v[114:117]
	v_mfma_f32_16x16x32_bf16 v[106:109], v[138:141], v[184:187], v[106:109]
	v_mfma_f32_16x16x32_bf16 v[102:105], v[130:133], v[192:195], v[102:105]
	v_mfma_f32_16x16x32_bf16 v[94:97], v[138:141], v[192:195], v[94:97]
	v_mfma_f32_16x16x32_bf16 v[86:89], v[130:133], v[200:203], v[86:89]
	v_mfma_f32_16x16x32_bf16 v[78:81], v[138:141], v[200:203], v[78:81]
	v_mfma_f32_16x16x32_bf16 v[126:129], v[134:137], v[180:183], v[126:129]
	v_mfma_f32_16x16x32_bf16 v[122:125], v[154:157], v[180:183], v[122:125]
	v_mfma_f32_16x16x32_bf16 v[114:117], v[134:137], v[188:191], v[114:117]
	v_mfma_f32_16x16x32_bf16 v[106:109], v[154:157], v[188:191], v[106:109]
	v_mfma_f32_16x16x32_bf16 v[102:105], v[134:137], v[196:199], v[102:105]
	v_mfma_f32_16x16x32_bf16 v[94:97], v[154:157], v[196:199], v[94:97]
	v_mfma_f32_16x16x32_bf16 v[86:89], v[134:137], v[204:207], v[86:89]
	v_mfma_f32_16x16x32_bf16 v[78:81], v[154:157], v[204:207], v[78:81]
	v_mfma_f32_16x16x32_bf16 v[118:121], v[160:163], v[176:179], v[118:121]
	v_mfma_f32_16x16x32_bf16 v[110:113], v[168:171], v[176:179], v[110:113]
	v_mfma_f32_16x16x32_bf16 v[98:101], v[160:163], v[184:187], v[98:101]
	v_mfma_f32_16x16x32_bf16 v[90:93], v[168:171], v[184:187], v[90:93]
	v_mfma_f32_16x16x32_bf16 v[82:85], v[160:163], v[192:195], v[82:85]
	v_mfma_f32_16x16x32_bf16 v[74:77], v[168:171], v[192:195], v[74:77]
	v_mfma_f32_16x16x32_bf16 v[70:73], v[160:163], v[200:203], v[70:73]
	v_mfma_f32_16x16x32_bf16 v[66:69], v[168:171], v[200:203], v[66:69]
	v_mfma_f32_16x16x32_bf16 v[118:121], v[164:167], v[180:183], v[118:121]
	v_mfma_f32_16x16x32_bf16 v[110:113], v[172:175], v[180:183], v[110:113]
	v_mfma_f32_16x16x32_bf16 v[98:101], v[164:167], v[188:191], v[98:101]
	v_mfma_f32_16x16x32_bf16 v[90:93], v[172:175], v[188:191], v[90:93]
	v_mfma_f32_16x16x32_bf16 v[82:85], v[164:167], v[196:199], v[82:85]
	v_mfma_f32_16x16x32_bf16 v[74:77], v[172:175], v[196:199], v[74:77]
	v_mfma_f32_16x16x32_bf16 v[70:73], v[164:167], v[204:207], v[70:73]
	v_mfma_f32_16x16x32_bf16 v[66:69], v[172:175], v[204:207], v[66:69]
	s_barrier
	s_add_i32 s34, s35, s21
	v_lshl_add_u64 v[208:209], s[48:49], 0, v[146:147]
	s_mov_b32 m0, s34
	ds_read_b128 v[176:179], v159 offset:16384
	ds_read_b128 v[180:183], v159 offset:17408
	ds_read_b128 v[184:187], v159 offset:18432
	ds_read_b128 v[188:191], v159 offset:19456
	ds_read_b128 v[192:195], v159 offset:20480
	ds_read_b128 v[196:199], v159 offset:21504
	ds_read_b128 v[200:203], v159 offset:22528
	ds_read_b128 v[204:207], v159 offset:23552
	global_load_lds_dwordx4 v[208:209], off
	s_add_i32 m0, s34, 0x2000
	s_add_u32 s34, s48, 0x40000
	v_lshl_add_u64 v[210:211], s[48:49], 0, v[142:143]
	s_addc_u32 s35, s49, 0
	s_add_i32 s13, s13, s21
	global_load_lds_dwordx4 v[210:211], off
	v_lshl_add_u64 v[212:213], s[34:35], 0, v[146:147]
	s_mov_b32 m0, s13
	v_lshl_add_u64 v[214:215], s[50:51], 0, v[144:145]
	global_load_lds_dwordx4 v[212:213], off
	v_lshl_add_u64 v[212:213], s[34:35], 0, v[142:143]
	s_add_i32 m0, s13, 0x2000
	s_nop 0
	global_load_lds_dwordx4 v[212:213], off
	v_lshl_add_u64 v[212:213], s[50:51], 0, v[148:149]
	s_mov_b32 m0, s22
	s_nop 0
	global_load_lds_dwordx4 v[212:213], off
	s_mov_b32 m0, s23
	s_nop 0
	global_load_lds_dwordx4 v[214:215], off
	s_waitcnt vmcnt(8)
	s_waitcnt lgkmcnt(0)
	s_barrier
	s_waitcnt lgkmcnt(0)
	v_mfma_f32_16x16x32_bf16 v[62:65], v[130:133], v[176:179], v[62:65]
	v_mfma_f32_16x16x32_bf16 v[58:61], v[138:141], v[176:179], v[58:61]
	v_mfma_f32_16x16x32_bf16 v[50:53], v[130:133], v[184:187], v[50:53]
	v_mfma_f32_16x16x32_bf16 v[42:45], v[138:141], v[184:187], v[42:45]
	v_mfma_f32_16x16x32_bf16 v[38:41], v[130:133], v[192:195], v[38:41]
	v_mfma_f32_16x16x32_bf16 v[30:33], v[138:141], v[192:195], v[30:33]
	v_mfma_f32_16x16x32_bf16 v[22:25], v[130:133], v[200:203], v[22:25]
	v_mfma_f32_16x16x32_bf16 v[14:17], v[138:141], v[200:203], v[14:17]
	v_mfma_f32_16x16x32_bf16 v[62:65], v[134:137], v[180:183], v[62:65]
	v_mfma_f32_16x16x32_bf16 v[58:61], v[154:157], v[180:183], v[58:61]
	v_mfma_f32_16x16x32_bf16 v[50:53], v[134:137], v[188:191], v[50:53]
	v_mfma_f32_16x16x32_bf16 v[42:45], v[154:157], v[188:191], v[42:45]
	v_mfma_f32_16x16x32_bf16 v[38:41], v[134:137], v[196:199], v[38:41]
	v_mfma_f32_16x16x32_bf16 v[30:33], v[154:157], v[196:199], v[30:33]
	v_mfma_f32_16x16x32_bf16 v[22:25], v[134:137], v[204:207], v[22:25]
	v_mfma_f32_16x16x32_bf16 v[14:17], v[154:157], v[204:207], v[14:17]
	v_mfma_f32_16x16x32_bf16 v[54:57], v[160:163], v[176:179], v[54:57]
	v_mfma_f32_16x16x32_bf16 v[46:49], v[168:171], v[176:179], v[46:49]
	v_mfma_f32_16x16x32_bf16 v[34:37], v[160:163], v[184:187], v[34:37]
	v_mfma_f32_16x16x32_bf16 v[26:29], v[168:171], v[184:187], v[26:29]
	v_mfma_f32_16x16x32_bf16 v[18:21], v[160:163], v[192:195], v[18:21]
	v_mfma_f32_16x16x32_bf16 v[10:13], v[168:171], v[192:195], v[10:13]
	v_mfma_f32_16x16x32_bf16 v[6:9], v[160:163], v[200:203], v[6:9]
	v_mfma_f32_16x16x32_bf16 v[2:5], v[168:171], v[200:203], v[2:5]
	v_mfma_f32_16x16x32_bf16 v[54:57], v[164:167], v[180:183], v[54:57]
	v_mfma_f32_16x16x32_bf16 v[46:49], v[172:175], v[180:183], v[46:49]
	v_mfma_f32_16x16x32_bf16 v[34:37], v[164:167], v[188:191], v[34:37]
	v_mfma_f32_16x16x32_bf16 v[26:29], v[172:175], v[188:191], v[26:29]
	v_mfma_f32_16x16x32_bf16 v[18:21], v[164:167], v[196:199], v[18:21]
	v_mfma_f32_16x16x32_bf16 v[10:13], v[172:175], v[196:199], v[10:13]
	v_mfma_f32_16x16x32_bf16 v[6:9], v[164:167], v[204:207], v[6:9]
	v_mfma_f32_16x16x32_bf16 v[2:5], v[172:175], v[204:207], v[2:5]
	s_barrier
	s_add_i32 s13, 0, 0x18000
	v_add_u32_e32 v0, s13, v158
	s_add_i32 s59, 0, 0x1c000
	ds_read_b128 v[130:133], v0
	ds_read_b128 v[134:137], v0 offset:1024
	ds_read_b128 v[138:141], v0 offset:2048
	ds_read_b128 v[154:157], v0 offset:3072
	v_add_u32_e32 v0, s59, v158
	ds_read_b128 v[160:163], v0
	ds_read_b128 v[164:167], v0 offset:1024
	ds_read_b128 v[168:171], v0 offset:2048
	ds_read_b128 v[172:175], v0 offset:3072
	s_add_u32 s34, s50, 0x40000
	s_addc_u32 s35, s51, 0
	s_mov_b32 m0, s24
	v_lshl_add_u64 v[216:217], s[34:35], 0, v[148:149]
	ds_read_b128 v[176:179], v159 offset:32768
	ds_read_b128 v[180:183], v159 offset:33792
	ds_read_b128 v[184:187], v159 offset:34816
	ds_read_b128 v[188:191], v159 offset:35840
	ds_read_b128 v[192:195], v159 offset:36864
	ds_read_b128 v[196:199], v159 offset:37888
	ds_read_b128 v[200:203], v159 offset:38912
	ds_read_b128 v[204:207], v159 offset:39936
	global_load_lds_dwordx4 v[216:217], off
	v_lshl_add_u64 v[216:217], s[34:35], 0, v[144:145]
	s_mov_b32 m0, s25
	s_nop 0
	global_load_lds_dwordx4 v[216:217], off
	s_waitcnt vmcnt(8)
	s_waitcnt lgkmcnt(0)
	s_barrier
	s_waitcnt lgkmcnt(0)
	v_mfma_f32_16x16x32_bf16 v[126:129], v[130:133], v[176:179], v[126:129]
	v_mfma_f32_16x16x32_bf16 v[122:125], v[138:141], v[176:179], v[122:125]
	v_mfma_f32_16x16x32_bf16 v[114:117], v[130:133], v[184:187], v[114:117]
	v_mfma_f32_16x16x32_bf16 v[106:109], v[138:141], v[184:187], v[106:109]
	v_mfma_f32_16x16x32_bf16 v[102:105], v[130:133], v[192:195], v[102:105]
	v_mfma_f32_16x16x32_bf16 v[94:97], v[138:141], v[192:195], v[94:97]
	v_mfma_f32_16x16x32_bf16 v[86:89], v[130:133], v[200:203], v[86:89]
	v_mfma_f32_16x16x32_bf16 v[78:81], v[138:141], v[200:203], v[78:81]
	v_mfma_f32_16x16x32_bf16 v[126:129], v[134:137], v[180:183], v[126:129]
	v_mfma_f32_16x16x32_bf16 v[122:125], v[154:157], v[180:183], v[122:125]
	v_mfma_f32_16x16x32_bf16 v[114:117], v[134:137], v[188:191], v[114:117]
	v_mfma_f32_16x16x32_bf16 v[106:109], v[154:157], v[188:191], v[106:109]
	v_mfma_f32_16x16x32_bf16 v[102:105], v[134:137], v[196:199], v[102:105]
	v_mfma_f32_16x16x32_bf16 v[94:97], v[154:157], v[196:199], v[94:97]
	v_mfma_f32_16x16x32_bf16 v[86:89], v[134:137], v[204:207], v[86:89]
	v_mfma_f32_16x16x32_bf16 v[78:81], v[154:157], v[204:207], v[78:81]
	v_mfma_f32_16x16x32_bf16 v[118:121], v[160:163], v[176:179], v[118:121]
	v_mfma_f32_16x16x32_bf16 v[110:113], v[168:171], v[176:179], v[110:113]
	v_mfma_f32_16x16x32_bf16 v[98:101], v[160:163], v[184:187], v[98:101]
	v_mfma_f32_16x16x32_bf16 v[90:93], v[168:171], v[184:187], v[90:93]
	v_mfma_f32_16x16x32_bf16 v[82:85], v[160:163], v[192:195], v[82:85]
	v_mfma_f32_16x16x32_bf16 v[74:77], v[168:171], v[192:195], v[74:77]
	v_mfma_f32_16x16x32_bf16 v[70:73], v[160:163], v[200:203], v[70:73]
	v_mfma_f32_16x16x32_bf16 v[66:69], v[168:171], v[200:203], v[66:69]
	v_mfma_f32_16x16x32_bf16 v[118:121], v[164:167], v[180:183], v[118:121]
	v_mfma_f32_16x16x32_bf16 v[110:113], v[172:175], v[180:183], v[110:113]
	v_mfma_f32_16x16x32_bf16 v[98:101], v[164:167], v[188:191], v[98:101]
	v_mfma_f32_16x16x32_bf16 v[90:93], v[172:175], v[188:191], v[90:93]
	v_mfma_f32_16x16x32_bf16 v[82:85], v[164:167], v[196:199], v[82:85]
	v_mfma_f32_16x16x32_bf16 v[74:77], v[172:175], v[196:199], v[74:77]
	v_mfma_f32_16x16x32_bf16 v[70:73], v[164:167], v[204:207], v[70:73]
	v_mfma_f32_16x16x32_bf16 v[66:69], v[172:175], v[204:207], v[66:69]
	s_barrier
	s_add_i32 s13, s13, s21
	v_lshl_add_u64 v[208:209], v[208:209], 0, s[84:85]
	s_mov_b32 m0, s13
	ds_read_b128 v[176:179], v159 offset:49152
	ds_read_b128 v[180:183], v159 offset:50176
	ds_read_b128 v[184:187], v159 offset:51200
	ds_read_b128 v[188:191], v159 offset:52224
	ds_read_b128 v[192:195], v159 offset:53248
	ds_read_b128 v[196:199], v159 offset:54272
	ds_read_b128 v[200:203], v159 offset:55296
	ds_read_b128 v[204:207], v159 offset:56320
	global_load_lds_dwordx4 v[208:209], off
	s_add_i32 m0, s13, 0x2000
	s_add_u32 s34, s48, 0x40080
	v_lshl_add_u64 v[208:209], v[210:211], 0, s[84:85]
	s_addc_u32 s35, s49, 0
	s_add_i32 s13, s59, s21
	global_load_lds_dwordx4 v[208:209], off
	v_lshl_add_u64 v[208:209], s[34:35], 0, v[146:147]
	s_mov_b32 m0, s13
	s_nop 0
	global_load_lds_dwordx4 v[208:209], off
	v_lshl_add_u64 v[208:209], s[34:35], 0, v[142:143]
	s_add_i32 m0, s13, 0x2000
	s_nop 0
	global_load_lds_dwordx4 v[208:209], off
	v_lshl_add_u64 v[208:209], v[212:213], 0, s[84:85]
	s_mov_b32 m0, s53
	s_nop 0
	global_load_lds_dwordx4 v[208:209], off
	v_lshl_add_u64 v[208:209], v[214:215], 0, s[84:85]
	s_mov_b32 m0, s54
	s_nop 0
	global_load_lds_dwordx4 v[208:209], off
	s_waitcnt vmcnt(8)
	s_waitcnt lgkmcnt(0)
	s_barrier
	s_waitcnt lgkmcnt(0)
	v_mfma_f32_16x16x32_bf16 v[62:65], v[130:133], v[176:179], v[62:65]
	v_mfma_f32_16x16x32_bf16 v[58:61], v[138:141], v[176:179], v[58:61]
	v_mfma_f32_16x16x32_bf16 v[50:53], v[130:133], v[184:187], v[50:53]
	v_mfma_f32_16x16x32_bf16 v[42:45], v[138:141], v[184:187], v[42:45]
	v_mfma_f32_16x16x32_bf16 v[38:41], v[130:133], v[192:195], v[38:41]
	v_mfma_f32_16x16x32_bf16 v[30:33], v[138:141], v[192:195], v[30:33]
	v_mfma_f32_16x16x32_bf16 v[22:25], v[130:133], v[200:203], v[22:25]
	v_mfma_f32_16x16x32_bf16 v[14:17], v[138:141], v[200:203], v[14:17]
	v_mfma_f32_16x16x32_bf16 v[62:65], v[134:137], v[180:183], v[62:65]
	v_mfma_f32_16x16x32_bf16 v[58:61], v[154:157], v[180:183], v[58:61]
	v_mfma_f32_16x16x32_bf16 v[50:53], v[134:137], v[188:191], v[50:53]
	v_mfma_f32_16x16x32_bf16 v[42:45], v[154:157], v[188:191], v[42:45]
	v_mfma_f32_16x16x32_bf16 v[38:41], v[134:137], v[196:199], v[38:41]
	v_mfma_f32_16x16x32_bf16 v[30:33], v[154:157], v[196:199], v[30:33]
	v_mfma_f32_16x16x32_bf16 v[22:25], v[134:137], v[204:207], v[22:25]
	v_mfma_f32_16x16x32_bf16 v[14:17], v[154:157], v[204:207], v[14:17]
	v_mfma_f32_16x16x32_bf16 v[54:57], v[160:163], v[176:179], v[54:57]
	v_mfma_f32_16x16x32_bf16 v[46:49], v[168:171], v[176:179], v[46:49]
	v_mfma_f32_16x16x32_bf16 v[34:37], v[160:163], v[184:187], v[34:37]
	v_mfma_f32_16x16x32_bf16 v[26:29], v[168:171], v[184:187], v[26:29]
	v_mfma_f32_16x16x32_bf16 v[18:21], v[160:163], v[192:195], v[18:21]
	v_mfma_f32_16x16x32_bf16 v[10:13], v[168:171], v[192:195], v[10:13]
	v_mfma_f32_16x16x32_bf16 v[6:9], v[160:163], v[200:203], v[6:9]
	v_mfma_f32_16x16x32_bf16 v[2:5], v[168:171], v[200:203], v[2:5]
	v_mfma_f32_16x16x32_bf16 v[54:57], v[164:167], v[180:183], v[54:57]
	v_mfma_f32_16x16x32_bf16 v[46:49], v[172:175], v[180:183], v[46:49]
	v_mfma_f32_16x16x32_bf16 v[34:37], v[164:167], v[188:191], v[34:37]
	v_mfma_f32_16x16x32_bf16 v[26:29], v[172:175], v[188:191], v[26:29]
	v_mfma_f32_16x16x32_bf16 v[18:21], v[164:167], v[196:199], v[18:21]
	v_mfma_f32_16x16x32_bf16 v[10:13], v[172:175], v[196:199], v[10:13]
	v_mfma_f32_16x16x32_bf16 v[6:9], v[164:167], v[204:207], v[6:9]
	v_mfma_f32_16x16x32_bf16 v[2:5], v[172:175], v[204:207], v[2:5]
	s_barrier
	s_add_i32 s31, s31, 2
	s_add_u32 s44, s44, 0x100
	s_addc_u32 s45, s45, 0
	s_add_u32 s29, s29, 0x100
	s_addc_u32 s30, s30, 0
	s_cmp_gt_u32 s31, 13
	s_cbranch_scc0 .LBB0_408
	s_and_b64 vcc, exec, s[6:7]
	s_cbranch_vccz .LBB0_411
	s_barrier

.LBB0_622:
	s_add_u32 s13, s40, 0xfffc0080
	s_addc_u32 s31, s41, -1
	s_add_i32 s34, 0, 0x10000
	s_cmp_eq_u32 s30, 12
	s_cselect_b32 s49, s9, s31
	s_cselect_b32 s48, s26, s13
	s_cselect_b32 s45, s7, s29
	s_cselect_b32 s44, s27, s28
	s_add_i32 s13, 0, 0x14000
	v_add_u32_e32 v142, s34, v157
	v_add_u32_e32 v186, s13, v157
	ds_read_b128 v[130:133], v142
	ds_read_b128 v[134:137], v142 offset:1024
	ds_read_b128 v[138:141], v142 offset:2048
	ds_read_b128 v[142:145], v142 offset:3072
	ds_read_b128 v[172:175], v186
	ds_read_b128 v[178:181], v186 offset:1024
	ds_read_b128 v[182:185], v186 offset:2048
	ds_read_b128 v[186:189], v186 offset:3072
	v_lshl_add_u64 v[222:223], s[40:41], 0, v[152:153]
	s_add_i32 m0, s21, 0xc000
	ds_read_b128 v[190:193], v159
	ds_read_b128 v[194:197], v159 offset:1024
	ds_read_b128 v[198:201], v159 offset:2048
	ds_read_b128 v[202:205], v159 offset:3072
	ds_read_b128 v[206:209], v159 offset:4096
	ds_read_b128 v[210:213], v159 offset:5120
	ds_read_b128 v[214:217], v159 offset:6144
	ds_read_b128 v[218:221], v159 offset:7168
	global_load_lds_dwordx4 v[222:223], off
	v_lshl_add_u64 v[222:223], s[40:41], 0, v[154:155]
	s_add_i32 m0, s21, 0xe000
	s_nop 0
	global_load_lds_dwordx4 v[222:223], off
	s_waitcnt vmcnt(8)
	s_waitcnt lgkmcnt(0)
	s_barrier
	s_waitcnt lgkmcnt(0)
	v_mfma_f32_16x16x32_bf16 v[126:129], v[130:133], v[190:193], v[126:129]
	v_mfma_f32_16x16x32_bf16 v[118:121], v[138:141], v[190:193], v[118:121]
	v_mfma_f32_16x16x32_bf16 v[110:113], v[130:133], v[198:201], v[110:113]
	v_mfma_f32_16x16x32_bf16 v[102:105], v[138:141], v[198:201], v[102:105]
	v_mfma_f32_16x16x32_bf16 v[94:97], v[130:133], v[206:209], v[94:97]
	v_mfma_f32_16x16x32_bf16 v[86:89], v[138:141], v[206:209], v[86:89]
	v_mfma_f32_16x16x32_bf16 v[78:81], v[130:133], v[214:217], v[78:81]
	v_mfma_f32_16x16x32_bf16 v[70:73], v[138:141], v[214:217], v[70:73]
	v_mfma_f32_16x16x32_bf16 v[126:129], v[134:137], v[194:197], v[126:129]
	v_mfma_f32_16x16x32_bf16 v[118:121], v[142:145], v[194:197], v[118:121]
	v_mfma_f32_16x16x32_bf16 v[110:113], v[134:137], v[202:205], v[110:113]
	v_mfma_f32_16x16x32_bf16 v[102:105], v[142:145], v[202:205], v[102:105]
	v_mfma_f32_16x16x32_bf16 v[94:97], v[134:137], v[210:213], v[94:97]
	v_mfma_f32_16x16x32_bf16 v[86:89], v[142:145], v[210:213], v[86:89]
	v_mfma_f32_16x16x32_bf16 v[78:81], v[134:137], v[218:221], v[78:81]
	v_mfma_f32_16x16x32_bf16 v[70:73], v[142:145], v[218:221], v[70:73]
	v_mfma_f32_16x16x32_bf16 v[122:125], v[172:175], v[190:193], v[122:125]
	v_mfma_f32_16x16x32_bf16 v[114:117], v[182:185], v[190:193], v[114:117]
	v_mfma_f32_16x16x32_bf16 v[106:109], v[172:175], v[198:201], v[106:109]
	v_mfma_f32_16x16x32_bf16 v[98:101], v[182:185], v[198:201], v[98:101]
	v_mfma_f32_16x16x32_bf16 v[90:93], v[172:175], v[206:209], v[90:93]
	v_mfma_f32_16x16x32_bf16 v[82:85], v[182:185], v[206:209], v[82:85]
	v_mfma_f32_16x16x32_bf16 v[74:77], v[172:175], v[214:217], v[74:77]
	v_mfma_f32_16x16x32_bf16 v[66:69], v[182:185], v[214:217], v[66:69]
	v_mfma_f32_16x16x32_bf16 v[122:125], v[178:181], v[194:197], v[122:125]
	v_mfma_f32_16x16x32_bf16 v[114:117], v[186:189], v[194:197], v[114:117]
	v_mfma_f32_16x16x32_bf16 v[106:109], v[178:181], v[202:205], v[106:109]
	v_mfma_f32_16x16x32_bf16 v[98:101], v[186:189], v[202:205], v[98:101]
	v_mfma_f32_16x16x32_bf16 v[90:93], v[178:181], v[210:213], v[90:93]
	v_mfma_f32_16x16x32_bf16 v[82:85], v[186:189], v[210:213], v[82:85]
	v_mfma_f32_16x16x32_bf16 v[74:77], v[178:181], v[218:221], v[74:77]
	v_mfma_f32_16x16x32_bf16 v[66:69], v[186:189], v[218:221], v[66:69]
	s_barrier
	s_add_i32 s31, s34, s20
	v_lshl_add_u64 v[222:223], s[44:45], 0, v[0:1]
	s_mov_b32 m0, s31
	ds_read_b128 v[190:193], v159 offset:16384
	ds_read_b128 v[194:197], v159 offset:17408
	ds_read_b128 v[198:201], v159 offset:18432
	ds_read_b128 v[202:205], v159 offset:19456
	ds_read_b128 v[206:209], v159 offset:20480
	ds_read_b128 v[210:213], v159 offset:21504
	ds_read_b128 v[214:217], v159 offset:22528
	ds_read_b128 v[218:221], v159 offset:23552
	global_load_lds_dwordx4 v[222:223], off
	s_add_i32 m0, s31, 0x2000
	s_add_u32 s34, s44, 0x40000
	v_lshl_add_u64 v[224:225], s[44:45], 0, v[146:147]
	s_addc_u32 s35, s45, 0
	s_add_i32 s13, s13, s20
	global_load_lds_dwordx4 v[224:225], off
	v_lshl_add_u64 v[226:227], s[34:35], 0, v[0:1]
	s_mov_b32 m0, s13
	v_lshl_add_u64 v[228:229], s[48:49], 0, v[148:149]
	global_load_lds_dwordx4 v[226:227], off
	v_lshl_add_u64 v[226:227], s[34:35], 0, v[146:147]
	s_add_i32 m0, s13, 0x2000
	s_nop 0
	global_load_lds_dwordx4 v[226:227], off
	v_lshl_add_u64 v[226:227], s[48:49], 0, v[150:151]
	s_mov_b32 m0, s21
	s_nop 0
	global_load_lds_dwordx4 v[226:227], off
	s_mov_b32 m0, s22
	s_nop 0
	global_load_lds_dwordx4 v[228:229], off
	s_waitcnt vmcnt(8)
	s_waitcnt lgkmcnt(0)
	s_barrier
	s_waitcnt lgkmcnt(0)
	v_mfma_f32_16x16x32_bf16 v[62:65], v[130:133], v[190:193], v[62:65]
	v_mfma_f32_16x16x32_bf16 v[54:57], v[138:141], v[190:193], v[54:57]
	v_mfma_f32_16x16x32_bf16 v[46:49], v[130:133], v[198:201], v[46:49]
	v_mfma_f32_16x16x32_bf16 v[38:41], v[138:141], v[198:201], v[38:41]
	v_mfma_f32_16x16x32_bf16 v[30:33], v[130:133], v[206:209], v[30:33]
	v_mfma_f32_16x16x32_bf16 v[22:25], v[138:141], v[206:209], v[22:25]
	v_mfma_f32_16x16x32_bf16 v[14:17], v[130:133], v[214:217], v[14:17]
	v_mfma_f32_16x16x32_bf16 v[6:9], v[138:141], v[214:217], v[6:9]
	v_mfma_f32_16x16x32_bf16 v[62:65], v[134:137], v[194:197], v[62:65]
	v_mfma_f32_16x16x32_bf16 v[54:57], v[142:145], v[194:197], v[54:57]
	v_mfma_f32_16x16x32_bf16 v[46:49], v[134:137], v[202:205], v[46:49]
	v_mfma_f32_16x16x32_bf16 v[38:41], v[142:145], v[202:205], v[38:41]
	v_mfma_f32_16x16x32_bf16 v[30:33], v[134:137], v[210:213], v[30:33]
	v_mfma_f32_16x16x32_bf16 v[22:25], v[142:145], v[210:213], v[22:25]
	v_mfma_f32_16x16x32_bf16 v[14:17], v[134:137], v[218:221], v[14:17]
	v_mfma_f32_16x16x32_bf16 v[6:9], v[142:145], v[218:221], v[6:9]
	v_mfma_f32_16x16x32_bf16 v[58:61], v[172:175], v[190:193], v[58:61]
	v_mfma_f32_16x16x32_bf16 v[50:53], v[182:185], v[190:193], v[50:53]
	v_mfma_f32_16x16x32_bf16 v[42:45], v[172:175], v[198:201], v[42:45]
	v_mfma_f32_16x16x32_bf16 v[34:37], v[182:185], v[198:201], v[34:37]
	v_mfma_f32_16x16x32_bf16 v[26:29], v[172:175], v[206:209], v[26:29]
	v_mfma_f32_16x16x32_bf16 v[18:21], v[182:185], v[206:209], v[18:21]
	v_mfma_f32_16x16x32_bf16 v[10:13], v[172:175], v[214:217], v[10:13]
	v_mfma_f32_16x16x32_bf16 v[2:5], v[182:185], v[214:217], v[2:5]
	v_mfma_f32_16x16x32_bf16 v[58:61], v[178:181], v[194:197], v[58:61]
	v_mfma_f32_16x16x32_bf16 v[50:53], v[186:189], v[194:197], v[50:53]
	v_mfma_f32_16x16x32_bf16 v[42:45], v[178:181], v[202:205], v[42:45]
	v_mfma_f32_16x16x32_bf16 v[34:37], v[186:189], v[202:205], v[34:37]
	v_mfma_f32_16x16x32_bf16 v[26:29], v[178:181], v[210:213], v[26:29]
	v_mfma_f32_16x16x32_bf16 v[18:21], v[186:189], v[210:213], v[18:21]
	v_mfma_f32_16x16x32_bf16 v[10:13], v[178:181], v[218:221], v[10:13]
	v_mfma_f32_16x16x32_bf16 v[2:5], v[186:189], v[218:221], v[2:5]
	s_barrier
	s_add_i32 s13, 0, 0x18000
	s_add_i32 s31, 0, 0x1c000
	v_add_u32_e32 v142, s13, v157
	v_add_u32_e32 v186, s31, v157
	ds_read_b128 v[130:133], v142
	ds_read_b128 v[134:137], v142 offset:1024
	ds_read_b128 v[138:141], v142 offset:2048
	ds_read_b128 v[142:145], v142 offset:3072
	ds_read_b128 v[172:175], v186
	ds_read_b128 v[178:181], v186 offset:1024
	ds_read_b128 v[182:185], v186 offset:2048
	ds_read_b128 v[186:189], v186 offset:3072
	s_add_u32 s34, s48, 0x40000
	s_addc_u32 s35, s49, 0
	s_mov_b32 m0, s23
	v_lshl_add_u64 v[230:231], s[34:35], 0, v[150:151]
	ds_read_b128 v[190:193], v159 offset:32768
	ds_read_b128 v[194:197], v159 offset:33792
	ds_read_b128 v[198:201], v159 offset:34816
	ds_read_b128 v[202:205], v159 offset:35840
	ds_read_b128 v[206:209], v159 offset:36864
	ds_read_b128 v[210:213], v159 offset:37888
	ds_read_b128 v[214:217], v159 offset:38912
	ds_read_b128 v[218:221], v159 offset:39936
	global_load_lds_dwordx4 v[230:231], off
	v_lshl_add_u64 v[230:231], s[34:35], 0, v[148:149]
	s_mov_b32 m0, s50
	s_nop 0
	global_load_lds_dwordx4 v[230:231], off
	s_waitcnt vmcnt(8)
	s_waitcnt lgkmcnt(0)
	s_barrier
	s_waitcnt lgkmcnt(0)
	v_mfma_f32_16x16x32_bf16 v[126:129], v[130:133], v[190:193], v[126:129]
	v_mfma_f32_16x16x32_bf16 v[118:121], v[138:141], v[190:193], v[118:121]
	v_mfma_f32_16x16x32_bf16 v[110:113], v[130:133], v[198:201], v[110:113]
	v_mfma_f32_16x16x32_bf16 v[102:105], v[138:141], v[198:201], v[102:105]
	v_mfma_f32_16x16x32_bf16 v[94:97], v[130:133], v[206:209], v[94:97]
	v_mfma_f32_16x16x32_bf16 v[86:89], v[138:141], v[206:209], v[86:89]
	v_mfma_f32_16x16x32_bf16 v[78:81], v[130:133], v[214:217], v[78:81]
	v_mfma_f32_16x16x32_bf16 v[70:73], v[138:141], v[214:217], v[70:73]
	v_mfma_f32_16x16x32_bf16 v[126:129], v[134:137], v[194:197], v[126:129]
	v_mfma_f32_16x16x32_bf16 v[118:121], v[142:145], v[194:197], v[118:121]
	v_mfma_f32_16x16x32_bf16 v[110:113], v[134:137], v[202:205], v[110:113]
	v_mfma_f32_16x16x32_bf16 v[102:105], v[142:145], v[202:205], v[102:105]
	v_mfma_f32_16x16x32_bf16 v[94:97], v[134:137], v[210:213], v[94:97]
	v_mfma_f32_16x16x32_bf16 v[86:89], v[142:145], v[210:213], v[86:89]
	v_mfma_f32_16x16x32_bf16 v[78:81], v[134:137], v[218:221], v[78:81]
	v_mfma_f32_16x16x32_bf16 v[70:73], v[142:145], v[218:221], v[70:73]
	v_mfma_f32_16x16x32_bf16 v[122:125], v[172:175], v[190:193], v[122:125]
	v_mfma_f32_16x16x32_bf16 v[114:117], v[182:185], v[190:193], v[114:117]
	v_mfma_f32_16x16x32_bf16 v[106:109], v[172:175], v[198:201], v[106:109]
	v_mfma_f32_16x16x32_bf16 v[98:101], v[182:185], v[198:201], v[98:101]
	v_mfma_f32_16x16x32_bf16 v[90:93], v[172:175], v[206:209], v[90:93]
	v_mfma_f32_16x16x32_bf16 v[82:85], v[182:185], v[206:209], v[82:85]
	v_mfma_f32_16x16x32_bf16 v[74:77], v[172:175], v[214:217], v[74:77]
	v_mfma_f32_16x16x32_bf16 v[66:69], v[182:185], v[214:217], v[66:69]
	v_mfma_f32_16x16x32_bf16 v[122:125], v[178:181], v[194:197], v[122:125]
	v_mfma_f32_16x16x32_bf16 v[114:117], v[186:189], v[194:197], v[114:117]
	v_mfma_f32_16x16x32_bf16 v[106:109], v[178:181], v[202:205], v[106:109]
	v_mfma_f32_16x16x32_bf16 v[98:101], v[186:189], v[202:205], v[98:101]
	v_mfma_f32_16x16x32_bf16 v[90:93], v[178:181], v[210:213], v[90:93]
	v_mfma_f32_16x16x32_bf16 v[82:85], v[186:189], v[210:213], v[82:85]
	v_mfma_f32_16x16x32_bf16 v[74:77], v[178:181], v[218:221], v[74:77]
	v_mfma_f32_16x16x32_bf16 v[66:69], v[186:189], v[218:221], v[66:69]
	s_barrier
	s_add_i32 s13, s13, s20
	v_lshl_add_u64 v[222:223], v[222:223], 0, s[84:85]
	s_mov_b32 m0, s13
	ds_read_b128 v[190:193], v159 offset:49152
	ds_read_b128 v[194:197], v159 offset:50176
	ds_read_b128 v[198:201], v159 offset:51200
	ds_read_b128 v[202:205], v159 offset:52224
	ds_read_b128 v[206:209], v159 offset:53248
	ds_read_b128 v[210:213], v159 offset:54272
	ds_read_b128 v[214:217], v159 offset:55296
	ds_read_b128 v[218:221], v159 offset:56320
	global_load_lds_dwordx4 v[222:223], off
	s_add_i32 m0, s13, 0x2000
	s_add_u32 s34, s44, 0x40080
	v_lshl_add_u64 v[222:223], v[224:225], 0, s[84:85]
	s_addc_u32 s35, s45, 0
	s_add_i32 s13, s31, s20
	global_load_lds_dwordx4 v[222:223], off
	v_lshl_add_u64 v[222:223], s[34:35], 0, v[0:1]
	s_mov_b32 m0, s13
	s_nop 0
	global_load_lds_dwordx4 v[222:223], off
	v_lshl_add_u64 v[222:223], s[34:35], 0, v[146:147]
	s_add_i32 m0, s13, 0x2000
	s_nop 0
	global_load_lds_dwordx4 v[222:223], off
	v_lshl_add_u64 v[222:223], v[226:227], 0, s[84:85]
	s_mov_b32 m0, s24
	s_nop 0
	global_load_lds_dwordx4 v[222:223], off
	v_lshl_add_u64 v[222:223], v[228:229], 0, s[84:85]
	s_mov_b32 m0, s25
	s_nop 0
	global_load_lds_dwordx4 v[222:223], off
	s_waitcnt vmcnt(8)
	s_waitcnt lgkmcnt(0)
	s_barrier
	s_waitcnt lgkmcnt(0)
	v_mfma_f32_16x16x32_bf16 v[62:65], v[130:133], v[190:193], v[62:65]
	v_mfma_f32_16x16x32_bf16 v[54:57], v[138:141], v[190:193], v[54:57]
	v_mfma_f32_16x16x32_bf16 v[46:49], v[130:133], v[198:201], v[46:49]
	v_mfma_f32_16x16x32_bf16 v[38:41], v[138:141], v[198:201], v[38:41]
	v_mfma_f32_16x16x32_bf16 v[30:33], v[130:133], v[206:209], v[30:33]
	v_mfma_f32_16x16x32_bf16 v[22:25], v[138:141], v[206:209], v[22:25]
	v_mfma_f32_16x16x32_bf16 v[14:17], v[130:133], v[214:217], v[14:17]
	v_mfma_f32_16x16x32_bf16 v[6:9], v[138:141], v[214:217], v[6:9]
	v_mfma_f32_16x16x32_bf16 v[62:65], v[134:137], v[194:197], v[62:65]
	v_mfma_f32_16x16x32_bf16 v[54:57], v[142:145], v[194:197], v[54:57]
	v_mfma_f32_16x16x32_bf16 v[46:49], v[134:137], v[202:205], v[46:49]
	v_mfma_f32_16x16x32_bf16 v[38:41], v[142:145], v[202:205], v[38:41]
	v_mfma_f32_16x16x32_bf16 v[30:33], v[134:137], v[210:213], v[30:33]
	v_mfma_f32_16x16x32_bf16 v[22:25], v[142:145], v[210:213], v[22:25]
	v_mfma_f32_16x16x32_bf16 v[14:17], v[134:137], v[218:221], v[14:17]
	v_mfma_f32_16x16x32_bf16 v[6:9], v[142:145], v[218:221], v[6:9]
	v_mfma_f32_16x16x32_bf16 v[58:61], v[172:175], v[190:193], v[58:61]
	v_mfma_f32_16x16x32_bf16 v[50:53], v[182:185], v[190:193], v[50:53]
	v_mfma_f32_16x16x32_bf16 v[42:45], v[172:175], v[198:201], v[42:45]
	v_mfma_f32_16x16x32_bf16 v[34:37], v[182:185], v[198:201], v[34:37]
	v_mfma_f32_16x16x32_bf16 v[26:29], v[172:175], v[206:209], v[26:29]
	v_mfma_f32_16x16x32_bf16 v[18:21], v[182:185], v[206:209], v[18:21]
	v_mfma_f32_16x16x32_bf16 v[10:13], v[172:175], v[214:217], v[10:13]
	v_mfma_f32_16x16x32_bf16 v[2:5], v[182:185], v[214:217], v[2:5]
	v_mfma_f32_16x16x32_bf16 v[58:61], v[178:181], v[194:197], v[58:61]
	v_mfma_f32_16x16x32_bf16 v[50:53], v[186:189], v[194:197], v[50:53]
	v_mfma_f32_16x16x32_bf16 v[42:45], v[178:181], v[202:205], v[42:45]
	v_mfma_f32_16x16x32_bf16 v[34:37], v[186:189], v[202:205], v[34:37]
	v_mfma_f32_16x16x32_bf16 v[26:29], v[178:181], v[210:213], v[26:29]
	v_mfma_f32_16x16x32_bf16 v[18:21], v[186:189], v[210:213], v[18:21]
	v_mfma_f32_16x16x32_bf16 v[10:13], v[178:181], v[218:221], v[10:13]
	v_mfma_f32_16x16x32_bf16 v[2:5], v[186:189], v[218:221], v[2:5]
	s_barrier
	s_add_i32 s30, s30, 2
	s_add_u32 s40, s40, 0x100
	s_addc_u32 s41, s41, 0
	s_add_u32 s28, s28, 0x100
	s_addc_u32 s29, s29, 0
	s_cmp_gt_u32 s30, 13
	s_cbranch_scc0 .LBB0_622
	s_and_b64 vcc, exec, s[4:5]
	s_cbranch_vccz .LBB0_625
	s_barrier

.LBB0_820:
	s_add_u32 s13, s10, 0xfffc0080
	s_addc_u32 s28, s11, -1
	s_add_i32 s29, 0, 0x10000
	s_cmp_eq_u32 s27, 12
	s_cselect_b32 s49, s22, s28
	s_cselect_b32 s48, s23, s13
	s_cselect_b32 s43, s9, s26
	s_cselect_b32 s42, s24, s25
	s_add_i32 s13, 0, 0x14000
	v_add_u32_e32 v106, s29, v244
	v_add_u32_e32 v150, s13, v244
	ds_read_b128 v[90:93], v106
	ds_read_b128 v[94:97], v106 offset:1024
	ds_read_b128 v[102:105], v106 offset:2048
	ds_read_b128 v[106:109], v106 offset:3072
	ds_read_b128 v[122:125], v150
	ds_read_b128 v[130:133], v150 offset:1024
	ds_read_b128 v[138:141], v150 offset:2048
	ds_read_b128 v[150:153], v150 offset:3072
	v_lshl_add_u64 v[194:195], s[10:11], 0, v[220:221]
	s_add_i32 m0, s50, 0xc000
	ds_read_b128 v[154:157], v245
	ds_read_b128 v[158:161], v245 offset:1024
	ds_read_b128 v[162:165], v245 offset:2048
	ds_read_b128 v[166:169], v245 offset:3072
	ds_read_b128 v[178:181], v245 offset:4096
	ds_read_b128 v[182:185], v245 offset:5120
	ds_read_b128 v[186:189], v245 offset:6144
	ds_read_b128 v[190:193], v245 offset:7168
	global_load_lds_dwordx4 v[194:195], off
	v_lshl_add_u64 v[194:195], s[10:11], 0, v[222:223]
	s_add_i32 m0, s50, 0xe000
	s_nop 0
	global_load_lds_dwordx4 v[194:195], off
	s_waitcnt vmcnt(8)
	s_waitcnt lgkmcnt(0)
	s_barrier
	s_waitcnt lgkmcnt(0)
	v_mfma_f32_16x16x32_bf16 v[174:177], v[90:93], v[154:157], v[174:177]
	v_mfma_f32_16x16x32_bf16 v[170:173], v[102:105], v[154:157], v[170:173]
	v_mfma_f32_16x16x32_bf16 v[134:137], v[90:93], v[162:165], v[134:137]
	v_mfma_f32_16x16x32_bf16 v[126:129], v[102:105], v[162:165], v[126:129]
	v_mfma_f32_16x16x32_bf16 v[110:113], v[90:93], v[178:181], v[110:113]
	v_mfma_f32_16x16x32_bf16 v[98:101], v[102:105], v[178:181], v[98:101]
	v_mfma_f32_16x16x32_bf16 v[78:81], v[90:93], v[186:189], v[78:81]
	v_mfma_f32_16x16x32_bf16 v[74:77], v[102:105], v[186:189], v[74:77]
	v_mfma_f32_16x16x32_bf16 v[174:177], v[94:97], v[158:161], v[174:177]
	v_mfma_f32_16x16x32_bf16 v[170:173], v[106:109], v[158:161], v[170:173]
	v_mfma_f32_16x16x32_bf16 v[134:137], v[94:97], v[166:169], v[134:137]
	v_mfma_f32_16x16x32_bf16 v[126:129], v[106:109], v[166:169], v[126:129]
	v_mfma_f32_16x16x32_bf16 v[110:113], v[94:97], v[182:185], v[110:113]
	v_mfma_f32_16x16x32_bf16 v[98:101], v[106:109], v[182:185], v[98:101]
	v_mfma_f32_16x16x32_bf16 v[78:81], v[94:97], v[190:193], v[78:81]
	v_mfma_f32_16x16x32_bf16 v[74:77], v[106:109], v[190:193], v[74:77]
	v_mfma_f32_16x16x32_bf16 v[146:149], v[122:125], v[154:157], v[146:149]
	v_mfma_f32_16x16x32_bf16 v[142:145], v[138:141], v[154:157], v[142:145]
	v_mfma_f32_16x16x32_bf16 v[118:121], v[122:125], v[162:165], v[118:121]
	v_mfma_f32_16x16x32_bf16 v[114:117], v[138:141], v[162:165], v[114:117]
	v_mfma_f32_16x16x32_bf16 v[86:89], v[122:125], v[178:181], v[86:89]
	v_mfma_f32_16x16x32_bf16 v[82:85], v[138:141], v[178:181], v[82:85]
	v_mfma_f32_16x16x32_bf16 v[70:73], v[122:125], v[186:189], v[70:73]
	v_mfma_f32_16x16x32_bf16 v[66:69], v[138:141], v[186:189], v[66:69]
	v_mfma_f32_16x16x32_bf16 v[146:149], v[130:133], v[158:161], v[146:149]
	v_mfma_f32_16x16x32_bf16 v[142:145], v[150:153], v[158:161], v[142:145]
	v_mfma_f32_16x16x32_bf16 v[118:121], v[130:133], v[166:169], v[118:121]
	v_mfma_f32_16x16x32_bf16 v[114:117], v[150:153], v[166:169], v[114:117]
	v_mfma_f32_16x16x32_bf16 v[86:89], v[130:133], v[182:185], v[86:89]
	v_mfma_f32_16x16x32_bf16 v[82:85], v[150:153], v[182:185], v[82:85]
	v_mfma_f32_16x16x32_bf16 v[70:73], v[130:133], v[190:193], v[70:73]
	v_mfma_f32_16x16x32_bf16 v[66:69], v[150:153], v[190:193], v[66:69]
	s_barrier
	s_add_i32 s28, s29, s19
	v_lshl_add_u64 v[194:195], s[42:43], 0, v[0:1]
	s_mov_b32 m0, s28
	ds_read_b128 v[154:157], v245 offset:16384
	ds_read_b128 v[158:161], v245 offset:17408
	ds_read_b128 v[162:165], v245 offset:18432
	ds_read_b128 v[166:169], v245 offset:19456
	ds_read_b128 v[178:181], v245 offset:20480
	ds_read_b128 v[182:185], v245 offset:21504
	ds_read_b128 v[186:189], v245 offset:22528
	ds_read_b128 v[190:193], v245 offset:23552
	global_load_lds_dwordx4 v[194:195], off
	s_add_i32 m0, s28, 0x2000
	s_add_u32 s28, s42, 0x40000
	v_lshl_add_u64 v[196:197], s[42:43], 0, v[214:215]
	s_addc_u32 s29, s43, 0
	s_add_i32 s13, s13, s19
	global_load_lds_dwordx4 v[196:197], off
	v_lshl_add_u64 v[198:199], s[28:29], 0, v[0:1]
	s_mov_b32 m0, s13
	v_lshl_add_u64 v[200:201], s[48:49], 0, v[216:217]
	global_load_lds_dwordx4 v[198:199], off
	v_lshl_add_u64 v[198:199], s[28:29], 0, v[214:215]
	s_add_i32 m0, s13, 0x2000
	s_nop 0
	global_load_lds_dwordx4 v[198:199], off
	v_lshl_add_u64 v[198:199], s[48:49], 0, v[218:219]
	s_mov_b32 m0, s50
	s_nop 0
	global_load_lds_dwordx4 v[198:199], off
	s_mov_b32 m0, s51
	s_nop 0
	global_load_lds_dwordx4 v[200:201], off
	s_waitcnt vmcnt(8)
	s_waitcnt lgkmcnt(0)
	s_barrier
	s_waitcnt lgkmcnt(0)
	v_mfma_f32_16x16x32_bf16 v[62:65], v[90:93], v[154:157], v[62:65]
	v_mfma_f32_16x16x32_bf16 v[58:61], v[102:105], v[154:157], v[58:61]
	v_mfma_f32_16x16x32_bf16 v[46:49], v[90:93], v[162:165], v[46:49]
	v_mfma_f32_16x16x32_bf16 v[42:45], v[102:105], v[162:165], v[42:45]
	v_mfma_f32_16x16x32_bf16 v[30:33], v[90:93], v[178:181], v[30:33]
	v_mfma_f32_16x16x32_bf16 v[26:29], v[102:105], v[178:181], v[26:29]
	v_mfma_f32_16x16x32_bf16 v[14:17], v[90:93], v[186:189], v[14:17]
	v_mfma_f32_16x16x32_bf16 v[10:13], v[102:105], v[186:189], v[10:13]
	v_mfma_f32_16x16x32_bf16 v[62:65], v[94:97], v[158:161], v[62:65]
	v_mfma_f32_16x16x32_bf16 v[58:61], v[106:109], v[158:161], v[58:61]
	v_mfma_f32_16x16x32_bf16 v[46:49], v[94:97], v[166:169], v[46:49]
	v_mfma_f32_16x16x32_bf16 v[42:45], v[106:109], v[166:169], v[42:45]
	v_mfma_f32_16x16x32_bf16 v[30:33], v[94:97], v[182:185], v[30:33]
	v_mfma_f32_16x16x32_bf16 v[26:29], v[106:109], v[182:185], v[26:29]
	v_mfma_f32_16x16x32_bf16 v[14:17], v[94:97], v[190:193], v[14:17]
	v_mfma_f32_16x16x32_bf16 v[10:13], v[106:109], v[190:193], v[10:13]
	v_mfma_f32_16x16x32_bf16 v[54:57], v[122:125], v[154:157], v[54:57]
	v_mfma_f32_16x16x32_bf16 v[50:53], v[138:141], v[154:157], v[50:53]
	v_mfma_f32_16x16x32_bf16 v[38:41], v[122:125], v[162:165], v[38:41]
	v_mfma_f32_16x16x32_bf16 v[34:37], v[138:141], v[162:165], v[34:37]
	v_mfma_f32_16x16x32_bf16 v[22:25], v[122:125], v[178:181], v[22:25]
	v_mfma_f32_16x16x32_bf16 v[18:21], v[138:141], v[178:181], v[18:21]
	v_mfma_f32_16x16x32_bf16 v[6:9], v[122:125], v[186:189], v[6:9]
	v_mfma_f32_16x16x32_bf16 v[2:5], v[138:141], v[186:189], v[2:5]
	v_mfma_f32_16x16x32_bf16 v[54:57], v[130:133], v[158:161], v[54:57]
	v_mfma_f32_16x16x32_bf16 v[50:53], v[150:153], v[158:161], v[50:53]
	v_mfma_f32_16x16x32_bf16 v[38:41], v[130:133], v[166:169], v[38:41]
	v_mfma_f32_16x16x32_bf16 v[34:37], v[150:153], v[166:169], v[34:37]
	v_mfma_f32_16x16x32_bf16 v[22:25], v[130:133], v[182:185], v[22:25]
	v_mfma_f32_16x16x32_bf16 v[18:21], v[150:153], v[182:185], v[18:21]
	v_mfma_f32_16x16x32_bf16 v[6:9], v[130:133], v[190:193], v[6:9]
	v_mfma_f32_16x16x32_bf16 v[2:5], v[150:153], v[190:193], v[2:5]
	s_barrier
	s_add_i32 s13, 0, 0x18000
	s_add_i32 s30, 0, 0x1c000
	v_add_u32_e32 v106, s13, v244
	v_add_u32_e32 v150, s30, v244
	ds_read_b128 v[90:93], v106
	ds_read_b128 v[94:97], v106 offset:1024
	ds_read_b128 v[102:105], v106 offset:2048
	ds_read_b128 v[106:109], v106 offset:3072
	ds_read_b128 v[122:125], v150
	ds_read_b128 v[130:133], v150 offset:1024
	ds_read_b128 v[138:141], v150 offset:2048
	ds_read_b128 v[150:153], v150 offset:3072
	s_add_u32 s28, s48, 0x40000
	s_addc_u32 s29, s49, 0
	s_mov_b32 m0, s52
	v_lshl_add_u64 v[202:203], s[28:29], 0, v[218:219]
	ds_read_b128 v[154:157], v245 offset:32768
	ds_read_b128 v[158:161], v245 offset:33792
	ds_read_b128 v[162:165], v245 offset:34816
	ds_read_b128 v[166:169], v245 offset:35840
	ds_read_b128 v[178:181], v245 offset:36864
	ds_read_b128 v[182:185], v245 offset:37888
	ds_read_b128 v[186:189], v245 offset:38912
	ds_read_b128 v[190:193], v245 offset:39936
	global_load_lds_dwordx4 v[202:203], off
	v_lshl_add_u64 v[202:203], s[28:29], 0, v[216:217]
	s_mov_b32 m0, s53
	s_nop 0
	global_load_lds_dwordx4 v[202:203], off
	s_waitcnt vmcnt(8)
	s_waitcnt lgkmcnt(0)
	s_barrier
	s_waitcnt lgkmcnt(0)
	v_mfma_f32_16x16x32_bf16 v[174:177], v[90:93], v[154:157], v[174:177]
	v_mfma_f32_16x16x32_bf16 v[170:173], v[102:105], v[154:157], v[170:173]
	v_mfma_f32_16x16x32_bf16 v[134:137], v[90:93], v[162:165], v[134:137]
	v_mfma_f32_16x16x32_bf16 v[126:129], v[102:105], v[162:165], v[126:129]
	v_mfma_f32_16x16x32_bf16 v[110:113], v[90:93], v[178:181], v[110:113]
	v_mfma_f32_16x16x32_bf16 v[98:101], v[102:105], v[178:181], v[98:101]
	v_mfma_f32_16x16x32_bf16 v[78:81], v[90:93], v[186:189], v[78:81]
	v_mfma_f32_16x16x32_bf16 v[74:77], v[102:105], v[186:189], v[74:77]
	v_mfma_f32_16x16x32_bf16 v[174:177], v[94:97], v[158:161], v[174:177]
	v_mfma_f32_16x16x32_bf16 v[170:173], v[106:109], v[158:161], v[170:173]
	v_mfma_f32_16x16x32_bf16 v[134:137], v[94:97], v[166:169], v[134:137]
	v_mfma_f32_16x16x32_bf16 v[126:129], v[106:109], v[166:169], v[126:129]
	v_mfma_f32_16x16x32_bf16 v[110:113], v[94:97], v[182:185], v[110:113]
	v_mfma_f32_16x16x32_bf16 v[98:101], v[106:109], v[182:185], v[98:101]
	v_mfma_f32_16x16x32_bf16 v[78:81], v[94:97], v[190:193], v[78:81]
	v_mfma_f32_16x16x32_bf16 v[74:77], v[106:109], v[190:193], v[74:77]
	v_mfma_f32_16x16x32_bf16 v[146:149], v[122:125], v[154:157], v[146:149]
	v_mfma_f32_16x16x32_bf16 v[142:145], v[138:141], v[154:157], v[142:145]
	v_mfma_f32_16x16x32_bf16 v[118:121], v[122:125], v[162:165], v[118:121]
	v_mfma_f32_16x16x32_bf16 v[114:117], v[138:141], v[162:165], v[114:117]
	v_mfma_f32_16x16x32_bf16 v[86:89], v[122:125], v[178:181], v[86:89]
	v_mfma_f32_16x16x32_bf16 v[82:85], v[138:141], v[178:181], v[82:85]
	v_mfma_f32_16x16x32_bf16 v[70:73], v[122:125], v[186:189], v[70:73]
	v_mfma_f32_16x16x32_bf16 v[66:69], v[138:141], v[186:189], v[66:69]
	v_mfma_f32_16x16x32_bf16 v[146:149], v[130:133], v[158:161], v[146:149]
	v_mfma_f32_16x16x32_bf16 v[142:145], v[150:153], v[158:161], v[142:145]
	v_mfma_f32_16x16x32_bf16 v[118:121], v[130:133], v[166:169], v[118:121]
	v_mfma_f32_16x16x32_bf16 v[114:117], v[150:153], v[166:169], v[114:117]
	v_mfma_f32_16x16x32_bf16 v[86:89], v[130:133], v[182:185], v[86:89]
	v_mfma_f32_16x16x32_bf16 v[82:85], v[150:153], v[182:185], v[82:85]
	v_mfma_f32_16x16x32_bf16 v[70:73], v[130:133], v[190:193], v[70:73]
	v_mfma_f32_16x16x32_bf16 v[66:69], v[150:153], v[190:193], v[66:69]
	s_barrier
	s_add_i32 s13, s13, s19
	v_lshl_add_u64 v[194:195], v[194:195], 0, s[84:85]
	s_mov_b32 m0, s13
	ds_read_b128 v[154:157], v245 offset:49152
	ds_read_b128 v[158:161], v245 offset:50176
	ds_read_b128 v[162:165], v245 offset:51200
	ds_read_b128 v[166:169], v245 offset:52224
	ds_read_b128 v[178:181], v245 offset:53248
	ds_read_b128 v[182:185], v245 offset:54272
	ds_read_b128 v[186:189], v245 offset:55296
	ds_read_b128 v[190:193], v245 offset:56320
	global_load_lds_dwordx4 v[194:195], off
	s_add_i32 m0, s13, 0x2000
	s_add_u32 s28, s42, 0x40080
	v_lshl_add_u64 v[194:195], v[196:197], 0, s[84:85]
	s_addc_u32 s29, s43, 0
	s_add_i32 s13, s30, s19
	global_load_lds_dwordx4 v[194:195], off
	v_lshl_add_u64 v[194:195], s[28:29], 0, v[0:1]
	s_mov_b32 m0, s13
	s_nop 0
	global_load_lds_dwordx4 v[194:195], off
	v_lshl_add_u64 v[194:195], s[28:29], 0, v[214:215]
	s_add_i32 m0, s13, 0x2000
	s_nop 0
	global_load_lds_dwordx4 v[194:195], off
	v_lshl_add_u64 v[194:195], v[198:199], 0, s[84:85]
	s_mov_b32 m0, s59
	s_nop 0
	global_load_lds_dwordx4 v[194:195], off
	v_lshl_add_u64 v[194:195], v[200:201], 0, s[84:85]
	s_mov_b32 m0, s60
	s_nop 0
	global_load_lds_dwordx4 v[194:195], off
	s_waitcnt vmcnt(8)
	s_waitcnt lgkmcnt(0)
	s_barrier
	s_waitcnt lgkmcnt(0)
	v_mfma_f32_16x16x32_bf16 v[62:65], v[90:93], v[154:157], v[62:65]
	v_mfma_f32_16x16x32_bf16 v[58:61], v[102:105], v[154:157], v[58:61]
	v_mfma_f32_16x16x32_bf16 v[46:49], v[90:93], v[162:165], v[46:49]
	v_mfma_f32_16x16x32_bf16 v[42:45], v[102:105], v[162:165], v[42:45]
	v_mfma_f32_16x16x32_bf16 v[30:33], v[90:93], v[178:181], v[30:33]
	v_mfma_f32_16x16x32_bf16 v[26:29], v[102:105], v[178:181], v[26:29]
	v_mfma_f32_16x16x32_bf16 v[14:17], v[90:93], v[186:189], v[14:17]
	v_mfma_f32_16x16x32_bf16 v[10:13], v[102:105], v[186:189], v[10:13]
	v_mfma_f32_16x16x32_bf16 v[62:65], v[94:97], v[158:161], v[62:65]
	v_mfma_f32_16x16x32_bf16 v[58:61], v[106:109], v[158:161], v[58:61]
	v_mfma_f32_16x16x32_bf16 v[46:49], v[94:97], v[166:169], v[46:49]
	v_mfma_f32_16x16x32_bf16 v[42:45], v[106:109], v[166:169], v[42:45]
	v_mfma_f32_16x16x32_bf16 v[30:33], v[94:97], v[182:185], v[30:33]
	v_mfma_f32_16x16x32_bf16 v[26:29], v[106:109], v[182:185], v[26:29]
	v_mfma_f32_16x16x32_bf16 v[14:17], v[94:97], v[190:193], v[14:17]
	v_mfma_f32_16x16x32_bf16 v[10:13], v[106:109], v[190:193], v[10:13]
	v_mfma_f32_16x16x32_bf16 v[54:57], v[122:125], v[154:157], v[54:57]
	v_mfma_f32_16x16x32_bf16 v[50:53], v[138:141], v[154:157], v[50:53]
	v_mfma_f32_16x16x32_bf16 v[38:41], v[122:125], v[162:165], v[38:41]
	v_mfma_f32_16x16x32_bf16 v[34:37], v[138:141], v[162:165], v[34:37]
	v_mfma_f32_16x16x32_bf16 v[22:25], v[122:125], v[178:181], v[22:25]
	v_mfma_f32_16x16x32_bf16 v[18:21], v[138:141], v[178:181], v[18:21]
	v_mfma_f32_16x16x32_bf16 v[6:9], v[122:125], v[186:189], v[6:9]
	v_mfma_f32_16x16x32_bf16 v[2:5], v[138:141], v[186:189], v[2:5]
	v_mfma_f32_16x16x32_bf16 v[54:57], v[130:133], v[158:161], v[54:57]
	v_mfma_f32_16x16x32_bf16 v[50:53], v[150:153], v[158:161], v[50:53]
	v_mfma_f32_16x16x32_bf16 v[38:41], v[130:133], v[166:169], v[38:41]
	v_mfma_f32_16x16x32_bf16 v[34:37], v[150:153], v[166:169], v[34:37]
	v_mfma_f32_16x16x32_bf16 v[22:25], v[130:133], v[182:185], v[22:25]
	v_mfma_f32_16x16x32_bf16 v[18:21], v[150:153], v[182:185], v[18:21]
	v_mfma_f32_16x16x32_bf16 v[6:9], v[130:133], v[190:193], v[6:9]
	v_mfma_f32_16x16x32_bf16 v[2:5], v[150:153], v[190:193], v[2:5]
	s_barrier
	s_add_i32 s27, s27, 2
	s_add_u32 s10, s10, 0x100
	s_addc_u32 s11, s11, 0
	s_add_u32 s25, s25, 0x100
	s_addc_u32 s26, s26, 0
	s_cmp_gt_u32 s27, 13
	s_cbranch_scc0 .LBB0_820
	s_and_b64 vcc, exec, s[6:7]
	s_cbranch_vccz .LBB0_823
	s_barrier

.LBB0_945:
	s_add_u32 s13, s10, 0xfffc0080
	s_addc_u32 s28, s11, -1
	s_add_i32 s29, 0, 0x10000
	s_cmp_eq_u32 s27, 12
	s_cselect_b32 s51, s21, s28
	s_cselect_b32 s50, s22, s13
	s_cselect_b32 s49, s23, s26
	s_cselect_b32 s48, s24, s25
	s_add_i32 s13, 0, 0x14000
	v_add_u32_e32 v138, s29, v212
	v_add_u32_e32 v158, s13, v212
	ds_read_b128 v[122:125], v138
	ds_read_b128 v[126:129], v138 offset:1024
	ds_read_b128 v[134:137], v138 offset:2048
	ds_read_b128 v[138:141], v138 offset:3072
	ds_read_b128 v[142:145], v158
	ds_read_b128 v[146:149], v158 offset:1024
	ds_read_b128 v[154:157], v158 offset:2048
	ds_read_b128 v[158:161], v158 offset:3072
	v_lshl_add_u64 v[204:205], s[10:11], 0, v[200:201]
	s_add_i32 m0, s55, 0xc000
	ds_read_b128 v[162:165], v213
	ds_read_b128 v[166:169], v213 offset:1024
	ds_read_b128 v[170:173], v213 offset:2048
	ds_read_b128 v[174:177], v213 offset:3072
	ds_read_b128 v[178:181], v213 offset:4096
	ds_read_b128 v[182:185], v213 offset:5120
	ds_read_b128 v[186:189], v213 offset:6144
	ds_read_b128 v[190:193], v213 offset:7168
	global_load_lds_dwordx4 v[204:205], off
	v_lshl_add_u64 v[204:205], s[10:11], 0, v[202:203]
	s_add_i32 m0, s55, 0xe000
	s_nop 0
	global_load_lds_dwordx4 v[204:205], off
	s_waitcnt vmcnt(8)
	s_waitcnt lgkmcnt(0)
	s_barrier
	s_waitcnt lgkmcnt(0)
	v_mfma_f32_16x16x32_bf16 v[150:153], v[122:125], v[162:165], v[150:153]
	v_mfma_f32_16x16x32_bf16 v[130:133], v[134:137], v[162:165], v[130:133]
	v_mfma_f32_16x16x32_bf16 v[110:113], v[122:125], v[170:173], v[110:113]
	v_mfma_f32_16x16x32_bf16 v[106:109], v[134:137], v[170:173], v[106:109]
	v_mfma_f32_16x16x32_bf16 v[94:97], v[122:125], v[178:181], v[94:97]
	v_mfma_f32_16x16x32_bf16 v[90:93], v[134:137], v[178:181], v[90:93]
	v_mfma_f32_16x16x32_bf16 v[78:81], v[122:125], v[186:189], v[78:81]
	v_mfma_f32_16x16x32_bf16 v[74:77], v[134:137], v[186:189], v[74:77]
	v_mfma_f32_16x16x32_bf16 v[150:153], v[126:129], v[166:169], v[150:153]
	v_mfma_f32_16x16x32_bf16 v[130:133], v[138:141], v[166:169], v[130:133]
	v_mfma_f32_16x16x32_bf16 v[110:113], v[126:129], v[174:177], v[110:113]
	v_mfma_f32_16x16x32_bf16 v[106:109], v[138:141], v[174:177], v[106:109]
	v_mfma_f32_16x16x32_bf16 v[94:97], v[126:129], v[182:185], v[94:97]
	v_mfma_f32_16x16x32_bf16 v[90:93], v[138:141], v[182:185], v[90:93]
	v_mfma_f32_16x16x32_bf16 v[78:81], v[126:129], v[190:193], v[78:81]
	v_mfma_f32_16x16x32_bf16 v[74:77], v[138:141], v[190:193], v[74:77]
	v_mfma_f32_16x16x32_bf16 v[118:121], v[142:145], v[162:165], v[118:121]
	v_mfma_f32_16x16x32_bf16 v[114:117], v[154:157], v[162:165], v[114:117]
	v_mfma_f32_16x16x32_bf16 v[102:105], v[142:145], v[170:173], v[102:105]
	v_mfma_f32_16x16x32_bf16 v[98:101], v[154:157], v[170:173], v[98:101]
	v_mfma_f32_16x16x32_bf16 v[86:89], v[142:145], v[178:181], v[86:89]
	v_mfma_f32_16x16x32_bf16 v[82:85], v[154:157], v[178:181], v[82:85]
	v_mfma_f32_16x16x32_bf16 v[70:73], v[142:145], v[186:189], v[70:73]
	v_mfma_f32_16x16x32_bf16 v[66:69], v[154:157], v[186:189], v[66:69]
	v_mfma_f32_16x16x32_bf16 v[118:121], v[146:149], v[166:169], v[118:121]
	v_mfma_f32_16x16x32_bf16 v[114:117], v[158:161], v[166:169], v[114:117]
	v_mfma_f32_16x16x32_bf16 v[102:105], v[146:149], v[174:177], v[102:105]
	v_mfma_f32_16x16x32_bf16 v[98:101], v[158:161], v[174:177], v[98:101]
	v_mfma_f32_16x16x32_bf16 v[86:89], v[146:149], v[182:185], v[86:89]
	v_mfma_f32_16x16x32_bf16 v[82:85], v[158:161], v[182:185], v[82:85]
	v_mfma_f32_16x16x32_bf16 v[70:73], v[146:149], v[190:193], v[70:73]
	v_mfma_f32_16x16x32_bf16 v[66:69], v[158:161], v[190:193], v[66:69]
	s_barrier
	s_add_i32 s28, s29, s54
	v_lshl_add_u64 v[204:205], s[48:49], 0, v[0:1]
	s_mov_b32 m0, s28
	ds_read_b128 v[162:165], v213 offset:16384
	ds_read_b128 v[166:169], v213 offset:17408
	ds_read_b128 v[170:173], v213 offset:18432
	ds_read_b128 v[174:177], v213 offset:19456
	ds_read_b128 v[178:181], v213 offset:20480
	ds_read_b128 v[182:185], v213 offset:21504
	ds_read_b128 v[186:189], v213 offset:22528
	ds_read_b128 v[190:193], v213 offset:23552
	global_load_lds_dwordx4 v[204:205], off
	s_add_i32 m0, s28, 0x2000
	s_add_u32 s28, s48, 0x40000
	v_lshl_add_u64 v[206:207], s[48:49], 0, v[194:195]
	s_addc_u32 s29, s49, 0
	s_add_i32 s13, s13, s54
	global_load_lds_dwordx4 v[206:207], off
	v_lshl_add_u64 v[208:209], s[28:29], 0, v[0:1]
	s_mov_b32 m0, s13
	v_lshl_add_u64 v[210:211], s[50:51], 0, v[196:197]
	global_load_lds_dwordx4 v[208:209], off
	v_lshl_add_u64 v[208:209], s[28:29], 0, v[194:195]
	s_add_i32 m0, s13, 0x2000
	s_nop 0
	global_load_lds_dwordx4 v[208:209], off
	v_lshl_add_u64 v[208:209], s[50:51], 0, v[198:199]
	s_mov_b32 m0, s55
	s_nop 0
	global_load_lds_dwordx4 v[208:209], off
	s_mov_b32 m0, s58
	s_nop 0
	global_load_lds_dwordx4 v[210:211], off
	s_waitcnt vmcnt(8)
	s_waitcnt lgkmcnt(0)
	s_barrier
	s_waitcnt lgkmcnt(0)
	v_mfma_f32_16x16x32_bf16 v[62:65], v[122:125], v[162:165], v[62:65]
	v_mfma_f32_16x16x32_bf16 v[58:61], v[134:137], v[162:165], v[58:61]
	v_mfma_f32_16x16x32_bf16 v[46:49], v[122:125], v[170:173], v[46:49]
	v_mfma_f32_16x16x32_bf16 v[42:45], v[134:137], v[170:173], v[42:45]
	v_mfma_f32_16x16x32_bf16 v[30:33], v[122:125], v[178:181], v[30:33]
	v_mfma_f32_16x16x32_bf16 v[26:29], v[134:137], v[178:181], v[26:29]
	v_mfma_f32_16x16x32_bf16 v[14:17], v[122:125], v[186:189], v[14:17]
	v_mfma_f32_16x16x32_bf16 v[10:13], v[134:137], v[186:189], v[10:13]
	v_mfma_f32_16x16x32_bf16 v[62:65], v[126:129], v[166:169], v[62:65]
	v_mfma_f32_16x16x32_bf16 v[58:61], v[138:141], v[166:169], v[58:61]
	v_mfma_f32_16x16x32_bf16 v[46:49], v[126:129], v[174:177], v[46:49]
	v_mfma_f32_16x16x32_bf16 v[42:45], v[138:141], v[174:177], v[42:45]
	v_mfma_f32_16x16x32_bf16 v[30:33], v[126:129], v[182:185], v[30:33]
	v_mfma_f32_16x16x32_bf16 v[26:29], v[138:141], v[182:185], v[26:29]
	v_mfma_f32_16x16x32_bf16 v[14:17], v[126:129], v[190:193], v[14:17]
	v_mfma_f32_16x16x32_bf16 v[10:13], v[138:141], v[190:193], v[10:13]
	v_mfma_f32_16x16x32_bf16 v[54:57], v[142:145], v[162:165], v[54:57]
	v_mfma_f32_16x16x32_bf16 v[50:53], v[154:157], v[162:165], v[50:53]
	v_mfma_f32_16x16x32_bf16 v[38:41], v[142:145], v[170:173], v[38:41]
	v_mfma_f32_16x16x32_bf16 v[34:37], v[154:157], v[170:173], v[34:37]
	v_mfma_f32_16x16x32_bf16 v[22:25], v[142:145], v[178:181], v[22:25]
	v_mfma_f32_16x16x32_bf16 v[18:21], v[154:157], v[178:181], v[18:21]
	v_mfma_f32_16x16x32_bf16 v[6:9], v[142:145], v[186:189], v[6:9]
	v_mfma_f32_16x16x32_bf16 v[2:5], v[154:157], v[186:189], v[2:5]
	v_mfma_f32_16x16x32_bf16 v[54:57], v[146:149], v[166:169], v[54:57]
	v_mfma_f32_16x16x32_bf16 v[50:53], v[158:161], v[166:169], v[50:53]
	v_mfma_f32_16x16x32_bf16 v[38:41], v[146:149], v[174:177], v[38:41]
	v_mfma_f32_16x16x32_bf16 v[34:37], v[158:161], v[174:177], v[34:37]
	v_mfma_f32_16x16x32_bf16 v[22:25], v[146:149], v[182:185], v[22:25]
	v_mfma_f32_16x16x32_bf16 v[18:21], v[158:161], v[182:185], v[18:21]
	v_mfma_f32_16x16x32_bf16 v[6:9], v[146:149], v[190:193], v[6:9]
	v_mfma_f32_16x16x32_bf16 v[2:5], v[158:161], v[190:193], v[2:5]
	s_barrier
	s_add_i32 s13, 0, 0x18000
	s_add_i32 s30, 0, 0x1c000
	v_add_u32_e32 v138, s13, v212
	v_add_u32_e32 v158, s30, v212
	ds_read_b128 v[122:125], v138
	ds_read_b128 v[126:129], v138 offset:1024
	ds_read_b128 v[134:137], v138 offset:2048
	ds_read_b128 v[138:141], v138 offset:3072
	ds_read_b128 v[142:145], v158
	ds_read_b128 v[146:149], v158 offset:1024
	ds_read_b128 v[154:157], v158 offset:2048
	ds_read_b128 v[158:161], v158 offset:3072
	s_add_u32 s28, s50, 0x40000
	s_addc_u32 s29, s51, 0
	s_mov_b32 m0, s59
	v_lshl_add_u64 v[214:215], s[28:29], 0, v[198:199]
	ds_read_b128 v[162:165], v213 offset:32768
	ds_read_b128 v[166:169], v213 offset:33792
	ds_read_b128 v[170:173], v213 offset:34816
	ds_read_b128 v[174:177], v213 offset:35840
	ds_read_b128 v[178:181], v213 offset:36864
	ds_read_b128 v[182:185], v213 offset:37888
	ds_read_b128 v[186:189], v213 offset:38912
	ds_read_b128 v[190:193], v213 offset:39936
	global_load_lds_dwordx4 v[214:215], off
	v_lshl_add_u64 v[214:215], s[28:29], 0, v[196:197]
	s_mov_b32 m0, s60
	s_nop 0
	global_load_lds_dwordx4 v[214:215], off
	s_waitcnt vmcnt(8)
	s_waitcnt lgkmcnt(0)
	s_barrier
	s_waitcnt lgkmcnt(0)
	v_mfma_f32_16x16x32_bf16 v[150:153], v[122:125], v[162:165], v[150:153]
	v_mfma_f32_16x16x32_bf16 v[130:133], v[134:137], v[162:165], v[130:133]
	v_mfma_f32_16x16x32_bf16 v[110:113], v[122:125], v[170:173], v[110:113]
	v_mfma_f32_16x16x32_bf16 v[106:109], v[134:137], v[170:173], v[106:109]
	v_mfma_f32_16x16x32_bf16 v[94:97], v[122:125], v[178:181], v[94:97]
	v_mfma_f32_16x16x32_bf16 v[90:93], v[134:137], v[178:181], v[90:93]
	v_mfma_f32_16x16x32_bf16 v[78:81], v[122:125], v[186:189], v[78:81]
	v_mfma_f32_16x16x32_bf16 v[74:77], v[134:137], v[186:189], v[74:77]
	v_mfma_f32_16x16x32_bf16 v[150:153], v[126:129], v[166:169], v[150:153]
	v_mfma_f32_16x16x32_bf16 v[130:133], v[138:141], v[166:169], v[130:133]
	v_mfma_f32_16x16x32_bf16 v[110:113], v[126:129], v[174:177], v[110:113]
	v_mfma_f32_16x16x32_bf16 v[106:109], v[138:141], v[174:177], v[106:109]
	v_mfma_f32_16x16x32_bf16 v[94:97], v[126:129], v[182:185], v[94:97]
	v_mfma_f32_16x16x32_bf16 v[90:93], v[138:141], v[182:185], v[90:93]
	v_mfma_f32_16x16x32_bf16 v[78:81], v[126:129], v[190:193], v[78:81]
	v_mfma_f32_16x16x32_bf16 v[74:77], v[138:141], v[190:193], v[74:77]
	v_mfma_f32_16x16x32_bf16 v[118:121], v[142:145], v[162:165], v[118:121]
	v_mfma_f32_16x16x32_bf16 v[114:117], v[154:157], v[162:165], v[114:117]
	v_mfma_f32_16x16x32_bf16 v[102:105], v[142:145], v[170:173], v[102:105]
	v_mfma_f32_16x16x32_bf16 v[98:101], v[154:157], v[170:173], v[98:101]
	v_mfma_f32_16x16x32_bf16 v[86:89], v[142:145], v[178:181], v[86:89]
	v_mfma_f32_16x16x32_bf16 v[82:85], v[154:157], v[178:181], v[82:85]
	v_mfma_f32_16x16x32_bf16 v[70:73], v[142:145], v[186:189], v[70:73]
	v_mfma_f32_16x16x32_bf16 v[66:69], v[154:157], v[186:189], v[66:69]
	v_mfma_f32_16x16x32_bf16 v[118:121], v[146:149], v[166:169], v[118:121]
	v_mfma_f32_16x16x32_bf16 v[114:117], v[158:161], v[166:169], v[114:117]
	v_mfma_f32_16x16x32_bf16 v[102:105], v[146:149], v[174:177], v[102:105]
	v_mfma_f32_16x16x32_bf16 v[98:101], v[158:161], v[174:177], v[98:101]
	v_mfma_f32_16x16x32_bf16 v[86:89], v[146:149], v[182:185], v[86:89]
	v_mfma_f32_16x16x32_bf16 v[82:85], v[158:161], v[182:185], v[82:85]
	v_mfma_f32_16x16x32_bf16 v[70:73], v[146:149], v[190:193], v[70:73]
	v_mfma_f32_16x16x32_bf16 v[66:69], v[158:161], v[190:193], v[66:69]
	s_barrier
	s_add_i32 s13, s13, s54
	v_lshl_add_u64 v[204:205], v[204:205], 0, s[84:85]
	s_mov_b32 m0, s13
	ds_read_b128 v[162:165], v213 offset:49152
	ds_read_b128 v[166:169], v213 offset:50176
	ds_read_b128 v[170:173], v213 offset:51200
	ds_read_b128 v[174:177], v213 offset:52224
	ds_read_b128 v[178:181], v213 offset:53248
	ds_read_b128 v[182:185], v213 offset:54272
	ds_read_b128 v[186:189], v213 offset:55296
	ds_read_b128 v[190:193], v213 offset:56320
	global_load_lds_dwordx4 v[204:205], off
	s_add_i32 m0, s13, 0x2000
	s_add_u32 s28, s48, 0x40080
	v_lshl_add_u64 v[204:205], v[206:207], 0, s[84:85]
	s_addc_u32 s29, s49, 0
	s_add_i32 s13, s30, s54
	global_load_lds_dwordx4 v[204:205], off
	v_lshl_add_u64 v[204:205], s[28:29], 0, v[0:1]
	s_mov_b32 m0, s13
	s_nop 0
	global_load_lds_dwordx4 v[204:205], off
	v_lshl_add_u64 v[204:205], s[28:29], 0, v[194:195]
	s_add_i32 m0, s13, 0x2000
	s_nop 0
	global_load_lds_dwordx4 v[204:205], off
	v_lshl_add_u64 v[204:205], v[208:209], 0, s[84:85]
	s_mov_b32 m0, s69
	s_nop 0
	global_load_lds_dwordx4 v[204:205], off
	v_lshl_add_u64 v[204:205], v[210:211], 0, s[84:85]
	s_mov_b32 m0, s80
	s_nop 0
	global_load_lds_dwordx4 v[204:205], off
	s_waitcnt vmcnt(8)
	s_waitcnt lgkmcnt(0)
	s_barrier
	s_waitcnt lgkmcnt(0)
	v_mfma_f32_16x16x32_bf16 v[62:65], v[122:125], v[162:165], v[62:65]
	v_mfma_f32_16x16x32_bf16 v[58:61], v[134:137], v[162:165], v[58:61]
	v_mfma_f32_16x16x32_bf16 v[46:49], v[122:125], v[170:173], v[46:49]
	v_mfma_f32_16x16x32_bf16 v[42:45], v[134:137], v[170:173], v[42:45]
	v_mfma_f32_16x16x32_bf16 v[30:33], v[122:125], v[178:181], v[30:33]
	v_mfma_f32_16x16x32_bf16 v[26:29], v[134:137], v[178:181], v[26:29]
	v_mfma_f32_16x16x32_bf16 v[14:17], v[122:125], v[186:189], v[14:17]
	v_mfma_f32_16x16x32_bf16 v[10:13], v[134:137], v[186:189], v[10:13]
	v_mfma_f32_16x16x32_bf16 v[62:65], v[126:129], v[166:169], v[62:65]
	v_mfma_f32_16x16x32_bf16 v[58:61], v[138:141], v[166:169], v[58:61]
	v_mfma_f32_16x16x32_bf16 v[46:49], v[126:129], v[174:177], v[46:49]
	v_mfma_f32_16x16x32_bf16 v[42:45], v[138:141], v[174:177], v[42:45]
	v_mfma_f32_16x16x32_bf16 v[30:33], v[126:129], v[182:185], v[30:33]
	v_mfma_f32_16x16x32_bf16 v[26:29], v[138:141], v[182:185], v[26:29]
	v_mfma_f32_16x16x32_bf16 v[14:17], v[126:129], v[190:193], v[14:17]
	v_mfma_f32_16x16x32_bf16 v[10:13], v[138:141], v[190:193], v[10:13]
	v_mfma_f32_16x16x32_bf16 v[54:57], v[142:145], v[162:165], v[54:57]
	v_mfma_f32_16x16x32_bf16 v[50:53], v[154:157], v[162:165], v[50:53]
	v_mfma_f32_16x16x32_bf16 v[38:41], v[142:145], v[170:173], v[38:41]
	v_mfma_f32_16x16x32_bf16 v[34:37], v[154:157], v[170:173], v[34:37]
	v_mfma_f32_16x16x32_bf16 v[22:25], v[142:145], v[178:181], v[22:25]
	v_mfma_f32_16x16x32_bf16 v[18:21], v[154:157], v[178:181], v[18:21]
	v_mfma_f32_16x16x32_bf16 v[6:9], v[142:145], v[186:189], v[6:9]
	v_mfma_f32_16x16x32_bf16 v[2:5], v[154:157], v[186:189], v[2:5]
	v_mfma_f32_16x16x32_bf16 v[54:57], v[146:149], v[166:169], v[54:57]
	v_mfma_f32_16x16x32_bf16 v[50:53], v[158:161], v[166:169], v[50:53]
	v_mfma_f32_16x16x32_bf16 v[38:41], v[146:149], v[174:177], v[38:41]
	v_mfma_f32_16x16x32_bf16 v[34:37], v[158:161], v[174:177], v[34:37]
	v_mfma_f32_16x16x32_bf16 v[22:25], v[146:149], v[182:185], v[22:25]
	v_mfma_f32_16x16x32_bf16 v[18:21], v[158:161], v[182:185], v[18:21]
	v_mfma_f32_16x16x32_bf16 v[6:9], v[146:149], v[190:193], v[6:9]
	v_mfma_f32_16x16x32_bf16 v[2:5], v[158:161], v[190:193], v[2:5]
	s_barrier
	s_add_i32 s27, s27, 2
	s_add_u32 s10, s10, 0x100
	s_addc_u32 s11, s11, 0
	s_add_u32 s25, s25, 0x100
	s_addc_u32 s26, s26, 0
	s_cmp_gt_u32 s27, 13
	s_cbranch_scc0 .LBB0_945
	s_and_b64 vcc, exec, s[8:9]
	s_cbranch_vccz .LBB0_948
	s_barrier
